# strategy 4: static s_setprio 1 for waves 4-7 over each GEMM K-loop, per-MFMA-group priority flips replaced by s_nop 0 (on v13)
# speedup vs baseline: 1.0028x; 1.0020x over previous
; #define PG8_WAIT_V(n) asm volatile("s_waitcnt vmcnt(" #n ")" ::: "memory")
; template <class Epi, class Sched, bool ALIGN_EPI = GEMM_ALIGN, bool SP2 = GEMM_SP2>
; __device__ __forceinline__ void gemm_phase(PG8_LAS unsigned char* lds, const Gemm g, const Sched& S, const Epi& E, unsigned long long*  , int tid_in) {
;     ...
;     f32x4 acc[2][2][4][2];
; #pragma unroll
;     for (int a = 0; a < 2; ++a)
; #pragma unroll
;         for (int b = 0; b < 2; ++b)
; #pragma unroll
;             for (int m = 0; m < 4; ++m)
; #pragma unroll
;                 for (int n = 0; n < 2; ++n) acc[a][b][m][n] = (f32x4){0.f, 0.f, 0.f, 0.f};
;     bf16x8 At[4][2], B0[2][2], B1[2][2];
;     const char* cA = (const char*)g.A + (size_t)cur.pm * tstep; const char* cB = (const char*)g.Bt + (size_t)cur.pn * tstep;
;     S.a_ready(cur);
;     if constexpr (SP2) {
;         PG8_STAGE(PG8_SB(0, 0), cB, voffB); PG8_STAGE(PG8_SB(0, 1), cB + hstep, voffB); PG8_STAGE(PG8_SA(0, 0), cA, voffA); PG8_STAGE(PG8_SA(0, 1), cA + hstep, voffA);
;         if (wr == 1) PG8_BAR;
;         PG8_WAIT_V(2); PG8_BAR;
;         PG8_STAGE(PG8_SB(1, 0), cB + kstep, voffB); PG8_STAGE(PG8_SA(1, 0), cA + kstep, voffA); PG8_STAGE(PG8_SB(1, 1), cB + hstep + kstep, voffB);
;         PG8_WAIT_V(6); PG8_BAR;
;     } else {
;         PG8_STAGE(PG8_SB(0, 0), cB, voffB); PG8_STAGE(PG8_SA(0, 0), cA, voffA); PG8_STAGE(PG8_SB(0, 1), cB + hstep, voffB); PG8_STAGE(PG8_SA(0, 1), cA + hstep, voffA);
;         if (wr == 1) PG8_BAR;
;         PG8_WAIT_V(4); PG8_BAR;
;         PG8_STAGE(PG8_SB(1, 0), cB + kstep, voffB); PG8_STAGE(PG8_SA(1, 0), cA + kstep, voffA); PG8_STAGE(PG8_SB(1, 1), cB + hstep + kstep, voffB);
;         PG8_WAIT_V(6); PG8_BAR;
;     }
;     for (;;) {
;         const bool has_next = S.next(ui + 1, nxt);
;         const char* nA = has_next ? (const char*)g.A + (size_t)nxt.pm * tstep : cA; const char* nB = has_next ? (const char*)g.Bt + (size_t)nxt.pn * tstep : cB;
;         for (int t = 0; t < nt; t += 2) {
;             const bool last = (t == nt - 2);
;             const char* a1 = cA + (size_t)(t + 1) * kstep;
;             const char* a2 = last ? nA : cA + (size_t)(t + 2) * kstep; const char* b2 = last ? nB : cB + (size_t)(t + 2) * kstep;
;             const char* a3 = a2 + kstep; const char* b3 = b2 + kstep;
;             if (last && has_next) S.a_ready(nxt);
;             if constexpr (SP2) {
.LBB0_128:
	s_ashr_i32 s13, s12, 31
	s_lshl_b64 s[14:15], s[12:13], 19
	s_add_u32 s14, s26, s14
	s_addc_u32 s15, s27, s15
	s_and_b64 s[16:17], s[0:1], exec
	s_cselect_b32 s13, s15, s23
	s_cselect_b32 s45, s14, s22
	s_ashr_i32 s11, s10, 31
	s_lshl_b64 s[16:17], s[10:11], 19
	s_add_u32 s16, s28, s16
	s_addc_u32 s17, s29, s17
	s_and_b64 s[24:25], s[0:1], exec
	s_cselect_b32 s11, s17, s21
	s_cselect_b32 s46, s16, s20
	s_add_u32 s47, s20, 0x100
	s_addc_u32 s48, s21, 0
	s_add_u32 s20, s22, 0x40080
	v_mov_b32_e32 v0, 0
	s_addc_u32 s21, s23, 0
	s_mov_b32 s49, -2
	v_mov_b32_e32 v1, v0
	v_mov_b32_e32 v2, v0
	v_mov_b32_e32 v3, v0
	v_mov_b32_e32 v4, v0
	v_mov_b32_e32 v5, v0
	v_mov_b32_e32 v6, v0
	v_mov_b32_e32 v7, v0
	v_mov_b32_e32 v8, v0
	v_mov_b32_e32 v9, v0
	v_mov_b32_e32 v10, v0
	v_mov_b32_e32 v11, v0
	v_mov_b32_e32 v16, v0
	v_mov_b32_e32 v17, v0
	v_mov_b32_e32 v18, v0
	v_mov_b32_e32 v19, v0
	v_mov_b32_e32 v24, v0
	v_mov_b32_e32 v25, v0
	v_mov_b32_e32 v26, v0
	v_mov_b32_e32 v27, v0
	v_mov_b32_e32 v32, v0
	v_mov_b32_e32 v33, v0
	v_mov_b32_e32 v34, v0
	v_mov_b32_e32 v35, v0
	v_mov_b32_e32 v40, v0
	v_mov_b32_e32 v41, v0
	v_mov_b32_e32 v42, v0
	v_mov_b32_e32 v43, v0
	v_mov_b32_e32 v52, v0
	v_mov_b32_e32 v53, v0
	v_mov_b32_e32 v54, v0
	v_mov_b32_e32 v55, v0
	v_mov_b32_e32 v12, v0
	v_mov_b32_e32 v13, v0
	v_mov_b32_e32 v14, v0
	v_mov_b32_e32 v15, v0
	v_mov_b32_e32 v20, v0
	v_mov_b32_e32 v21, v0
	v_mov_b32_e32 v22, v0
	v_mov_b32_e32 v23, v0
	v_mov_b32_e32 v28, v0
	v_mov_b32_e32 v29, v0
	v_mov_b32_e32 v30, v0
	v_mov_b32_e32 v31, v0
	v_mov_b32_e32 v36, v0
	v_mov_b32_e32 v37, v0
	v_mov_b32_e32 v38, v0
	v_mov_b32_e32 v39, v0
	v_mov_b32_e32 v44, v0
	v_mov_b32_e32 v45, v0
	v_mov_b32_e32 v46, v0
	v_mov_b32_e32 v47, v0
	v_mov_b32_e32 v48, v0
	v_mov_b32_e32 v49, v0
	v_mov_b32_e32 v50, v0
	v_mov_b32_e32 v51, v0
	v_mov_b32_e32 v56, v0
	v_mov_b32_e32 v57, v0
	v_mov_b32_e32 v58, v0
	v_mov_b32_e32 v59, v0
	v_mov_b32_e32 v60, v0
	v_mov_b32_e32 v61, v0
	v_mov_b32_e32 v62, v0
	v_mov_b32_e32 v63, v0
	v_mov_b32_e32 v64, v0
	v_mov_b32_e32 v65, v0
	v_mov_b32_e32 v66, v0
	v_mov_b32_e32 v67, v0
	v_mov_b32_e32 v68, v0
	v_mov_b32_e32 v69, v0
	v_mov_b32_e32 v70, v0
	v_mov_b32_e32 v71, v0
	v_mov_b32_e32 v72, v0
	v_mov_b32_e32 v73, v0
	v_mov_b32_e32 v74, v0
	v_mov_b32_e32 v75, v0
	v_mov_b32_e32 v76, v0
	v_mov_b32_e32 v77, v0
	v_mov_b32_e32 v78, v0
	v_mov_b32_e32 v79, v0
	v_mov_b32_e32 v80, v0
	v_mov_b32_e32 v81, v0
	v_mov_b32_e32 v82, v0
	v_mov_b32_e32 v83, v0
	v_mov_b32_e32 v88, v0
	v_mov_b32_e32 v89, v0
	v_mov_b32_e32 v90, v0
	v_mov_b32_e32 v91, v0
	v_mov_b32_e32 v96, v0
	v_mov_b32_e32 v97, v0
	v_mov_b32_e32 v98, v0
	v_mov_b32_e32 v99, v0
	v_mov_b32_e32 v104, v0
	v_mov_b32_e32 v105, v0
	v_mov_b32_e32 v106, v0
	v_mov_b32_e32 v107, v0
	v_mov_b32_e32 v84, v0
	v_mov_b32_e32 v85, v0
	v_mov_b32_e32 v86, v0
	v_mov_b32_e32 v87, v0
	v_mov_b32_e32 v92, v0
	v_mov_b32_e32 v93, v0
	v_mov_b32_e32 v94, v0
	v_mov_b32_e32 v95, v0
	v_mov_b32_e32 v100, v0
	v_mov_b32_e32 v101, v0
	v_mov_b32_e32 v102, v0
	v_mov_b32_e32 v103, v0
	v_mov_b32_e32 v108, v0
	v_mov_b32_e32 v109, v0
	v_mov_b32_e32 v110, v0
	v_mov_b32_e32 v111, v0
	v_mov_b32_e32 v112, v0
	v_mov_b32_e32 v113, v0
	v_mov_b32_e32 v114, v0
	v_mov_b32_e32 v115, v0
	v_mov_b32_e32 v116, v0
	v_mov_b32_e32 v117, v0
	v_mov_b32_e32 v118, v0
	v_mov_b32_e32 v119, v0
	v_mov_b32_e32 v120, v0
	v_mov_b32_e32 v121, v0
	v_mov_b32_e32 v122, v0
	v_mov_b32_e32 v123, v0
	v_mov_b32_e32 v124, v0
	v_mov_b32_e32 v125, v0
	v_mov_b32_e32 v126, v0
	v_mov_b32_e32 v127, v0
	s_and_b64 vcc, exec, s[8:9]
	s_cbranch_vccnz .Lprio_129
	s_setprio 1
.Lprio_129:
.LBB0_129:
	ds_read_b128 v[128:131], v163
	ds_read_b128 v[132:135], v163 offset:1024
	ds_read_b128 v[136:139], v163 offset:2048
	ds_read_b128 v[140:143], v163 offset:3072
	ds_read_b128 v[156:159], v164
	ds_read_b128 v[166:169], v164 offset:1024
	ds_read_b128 v[170:173], v164 offset:2048
	ds_read_b128 v[174:177], v164 offset:3072
	s_add_u32 s22, s20, 0xfffc0080
	s_addc_u32 s23, s21, -1
	s_cmp_eq_u32 s49, 12
	s_cselect_b32 s25, s13, s23
	s_cselect_b32 s24, s45, s22
	s_cselect_b32 s23, s11, s48
	s_cselect_b32 s22, s46, s47
	v_lshl_add_u64 v[210:211], s[20:21], 0, v[150:151]
	s_add_i32 m0, s19, 0xc000
	ds_read_b128 v[178:181], v165
	ds_read_b128 v[182:185], v165 offset:1024
	ds_read_b128 v[186:189], v165 offset:2048
	ds_read_b128 v[190:193], v165 offset:3072
	ds_read_b128 v[194:197], v165 offset:4096
	ds_read_b128 v[198:201], v165 offset:5120
	ds_read_b128 v[202:205], v165 offset:6144
	ds_read_b128 v[206:209], v165 offset:7168
	global_load_lds_dwordx4 v[210:211], off
	v_lshl_add_u64 v[210:211], s[20:21], 0, v[148:149]
	s_add_i32 m0, s19, 0xe000
	s_nop 0
	global_load_lds_dwordx4 v[210:211], off
	s_waitcnt vmcnt(8)
	s_waitcnt lgkmcnt(0)
	s_barrier
; #define PG8_STAGE(bufoff, gbase, voff) do { _Pragma("unroll") for (int _i = 0; _i < 2; ++_i) \
;         __builtin_amdgcn_global_load_lds((const unsigned*)((const char*)(gbase) + (voff)[_i]), (PG8_LAS unsigned*)(lds + (bufoff) + ldsw + _i * 8192), 16, 0, 0); } while (0)
; #define PG8_LDA(dst, b, h) do { _Pragma("unroll") for (int m = 0; m < 4; ++m) _Pragma("unroll") for (int k = 0; k < 2; ++k) dst[m][k] = *(const PG8_LAS bf16x8*)(lds + PG8_SA(b, h) + aoff + m * 2048 + k * 1024); } while (0)
; #define PG8_MMA(ai, bj, At, Bt) do { __builtin_amdgcn_s_setprio(1); _Pragma("unroll") for (int m = 0; m < 4; ++m) _Pragma("unroll") for (int n = 0; n < 2; ++n) _Pragma("unroll") for (int k = 0; k < 2; ++k) \
;         acc[ai][bj][m][n] = __builtin_amdgcn_mfma_f32_16x16x32_bf16(Bt[n][k], At[m][k], acc[ai][bj][m][n], 0, 0, 0); __builtin_amdgcn_s_setprio(0); } while (0)
; #define PG8_WAIT_V(n) asm volatile("s_waitcnt vmcnt(" #n ")" ::: "memory")
; #define PG8_WAIT_L(n) asm volatile("s_waitcnt lgkmcnt(" #n ")" ::: "memory")
; #define PG8_BAR __builtin_amdgcn_s_barrier()
; #define PG8_SCHED __builtin_amdgcn_sched_barrier(0)
; template <class Epi, class Sched, bool ALIGN_EPI = GEMM_ALIGN, bool SP2 = GEMM_SP2>
; __device__ __forceinline__ void gemm_phase(PG8_LAS unsigned char* lds, const Gemm g, const Sched& S, const Epi& E, unsigned long long*  , int tid_in) {
;     ...
;             PG8_WAIT_V(8); PG8_WAIT_L(0); PG8_BAR; PG8_MMA(0, 0, At, B0); PG8_MMA(0, 1, At, B1); PG8_BAR; PG8_SCHED;
;             PG8_LDA(At, 0, 1); PG8_STAGE(PG8_SB(0, 0), b2, voffB); PG8_STAGE(PG8_SB(0, 1), b2 + hstep, voffB); PG8_STAGE(PG8_SA(0, 0), a2, voffA);
;             PG8_WAIT_V(8); PG8_WAIT_L(0); PG8_BAR; PG8_MMA(1, 0, At, B0); PG8_MMA(1, 1, At, B1); PG8_BAR; PG8_SCHED;
	s_nop 0
	s_waitcnt lgkmcnt(0)
	v_mfma_f32_16x16x32_bf16 v[124:127], v[128:131], v[178:181], v[124:127]
	v_mfma_f32_16x16x32_bf16 v[120:123], v[136:139], v[178:181], v[120:123]
	v_mfma_f32_16x16x32_bf16 v[116:119], v[128:131], v[186:189], v[116:119]
	v_mfma_f32_16x16x32_bf16 v[112:115], v[136:139], v[186:189], v[112:115]
	v_mfma_f32_16x16x32_bf16 v[108:111], v[128:131], v[194:197], v[108:111]
	v_mfma_f32_16x16x32_bf16 v[100:103], v[136:139], v[194:197], v[100:103]
	v_mfma_f32_16x16x32_bf16 v[92:95], v[128:131], v[202:205], v[92:95]
	v_mfma_f32_16x16x32_bf16 v[84:87], v[136:139], v[202:205], v[84:87]
	v_mfma_f32_16x16x32_bf16 v[124:127], v[132:135], v[182:185], v[124:127]
	v_mfma_f32_16x16x32_bf16 v[120:123], v[140:143], v[182:185], v[120:123]
	v_mfma_f32_16x16x32_bf16 v[116:119], v[132:135], v[190:193], v[116:119]
	v_mfma_f32_16x16x32_bf16 v[112:115], v[140:143], v[190:193], v[112:115]
	v_mfma_f32_16x16x32_bf16 v[108:111], v[132:135], v[198:201], v[108:111]
	v_mfma_f32_16x16x32_bf16 v[100:103], v[140:143], v[198:201], v[100:103]
	v_mfma_f32_16x16x32_bf16 v[92:95], v[132:135], v[206:209], v[92:95]
	v_mfma_f32_16x16x32_bf16 v[84:87], v[140:143], v[206:209], v[84:87]
	s_nop 0
	s_nop 0
	v_mfma_f32_16x16x32_bf16 v[104:107], v[156:159], v[178:181], v[104:107]
	v_mfma_f32_16x16x32_bf16 v[96:99], v[170:173], v[178:181], v[96:99]
	v_mfma_f32_16x16x32_bf16 v[88:91], v[156:159], v[186:189], v[88:91]
	v_mfma_f32_16x16x32_bf16 v[80:83], v[170:173], v[186:189], v[80:83]
	v_mfma_f32_16x16x32_bf16 v[76:79], v[156:159], v[194:197], v[76:79]
	v_mfma_f32_16x16x32_bf16 v[72:75], v[170:173], v[194:197], v[72:75]
	v_mfma_f32_16x16x32_bf16 v[68:71], v[156:159], v[202:205], v[68:71]
	v_mfma_f32_16x16x32_bf16 v[64:67], v[170:173], v[202:205], v[64:67]
	v_mfma_f32_16x16x32_bf16 v[104:107], v[166:169], v[182:185], v[104:107]
	v_mfma_f32_16x16x32_bf16 v[96:99], v[174:177], v[182:185], v[96:99]
	v_mfma_f32_16x16x32_bf16 v[88:91], v[166:169], v[190:193], v[88:91]
	v_mfma_f32_16x16x32_bf16 v[80:83], v[174:177], v[190:193], v[80:83]
	v_mfma_f32_16x16x32_bf16 v[76:79], v[166:169], v[198:201], v[76:79]
	v_mfma_f32_16x16x32_bf16 v[72:75], v[174:177], v[198:201], v[72:75]
	v_mfma_f32_16x16x32_bf16 v[68:71], v[166:169], v[206:209], v[68:71]
	v_mfma_f32_16x16x32_bf16 v[64:67], v[174:177], v[206:209], v[64:67]
	s_nop 0
	s_barrier
	s_add_i32 s50, s42, s30
	v_lshl_add_u64 v[210:211], s[22:23], 0, v[146:147]
	s_mov_b32 m0, s50
	ds_read_b128 v[178:181], v165 offset:16384
	ds_read_b128 v[182:185], v165 offset:17408
	ds_read_b128 v[186:189], v165 offset:18432
	ds_read_b128 v[190:193], v165 offset:19456
	ds_read_b128 v[194:197], v165 offset:20480
	ds_read_b128 v[198:201], v165 offset:21504
	ds_read_b128 v[202:205], v165 offset:22528
	ds_read_b128 v[206:209], v165 offset:23552
	global_load_lds_dwordx4 v[210:211], off
	s_add_i32 m0, s50, 0x2000
	s_add_u32 s50, s22, 0x40000
	v_lshl_add_u64 v[212:213], s[22:23], 0, v[144:145]
	s_addc_u32 s51, s23, 0
	s_add_i32 s53, s43, s30
	global_load_lds_dwordx4 v[212:213], off
	v_lshl_add_u64 v[214:215], s[50:51], 0, v[146:147]
	s_mov_b32 m0, s53
	v_lshl_add_u64 v[216:217], s[24:25], 0, v[144:145]
	global_load_lds_dwordx4 v[214:215], off
	v_lshl_add_u64 v[214:215], s[50:51], 0, v[144:145]
	s_add_i32 m0, s53, 0x2000
	s_nop 0
	global_load_lds_dwordx4 v[214:215], off
	v_lshl_add_u64 v[214:215], s[24:25], 0, v[146:147]
	s_mov_b32 m0, s19
	s_nop 0
	global_load_lds_dwordx4 v[214:215], off
	s_mov_b32 m0, s33
	s_nop 0
	global_load_lds_dwordx4 v[216:217], off
	s_waitcnt vmcnt(8)
	s_waitcnt lgkmcnt(0)
	s_barrier
	s_nop 0
	s_waitcnt lgkmcnt(0)
	v_mfma_f32_16x16x32_bf16 v[60:63], v[128:131], v[178:181], v[60:63]
	v_mfma_f32_16x16x32_bf16 v[56:59], v[136:139], v[178:181], v[56:59]
	v_mfma_f32_16x16x32_bf16 v[48:51], v[128:131], v[186:189], v[48:51]
	v_mfma_f32_16x16x32_bf16 v[44:47], v[136:139], v[186:189], v[44:47]
	v_mfma_f32_16x16x32_bf16 v[36:39], v[128:131], v[194:197], v[36:39]
	v_mfma_f32_16x16x32_bf16 v[28:31], v[136:139], v[194:197], v[28:31]
	v_mfma_f32_16x16x32_bf16 v[20:23], v[128:131], v[202:205], v[20:23]
	v_mfma_f32_16x16x32_bf16 v[12:15], v[136:139], v[202:205], v[12:15]
	v_mfma_f32_16x16x32_bf16 v[60:63], v[132:135], v[182:185], v[60:63]
	v_mfma_f32_16x16x32_bf16 v[56:59], v[140:143], v[182:185], v[56:59]
	v_mfma_f32_16x16x32_bf16 v[48:51], v[132:135], v[190:193], v[48:51]
	v_mfma_f32_16x16x32_bf16 v[44:47], v[140:143], v[190:193], v[44:47]
	v_mfma_f32_16x16x32_bf16 v[36:39], v[132:135], v[198:201], v[36:39]
	v_mfma_f32_16x16x32_bf16 v[28:31], v[140:143], v[198:201], v[28:31]
	v_mfma_f32_16x16x32_bf16 v[20:23], v[132:135], v[206:209], v[20:23]
	v_mfma_f32_16x16x32_bf16 v[12:15], v[140:143], v[206:209], v[12:15]
	s_nop 0
	s_nop 0
	v_mfma_f32_16x16x32_bf16 v[52:55], v[156:159], v[178:181], v[52:55]
	v_mfma_f32_16x16x32_bf16 v[40:43], v[170:173], v[178:181], v[40:43]
	v_mfma_f32_16x16x32_bf16 v[32:35], v[156:159], v[186:189], v[32:35]
	v_mfma_f32_16x16x32_bf16 v[24:27], v[170:173], v[186:189], v[24:27]
	v_mfma_f32_16x16x32_bf16 v[16:19], v[156:159], v[194:197], v[16:19]
	v_mfma_f32_16x16x32_bf16 v[8:11], v[170:173], v[194:197], v[8:11]
	v_mfma_f32_16x16x32_bf16 v[4:7], v[156:159], v[202:205], v[4:7]
	v_mfma_f32_16x16x32_bf16 v[0:3], v[170:173], v[202:205], v[0:3]
	v_mfma_f32_16x16x32_bf16 v[52:55], v[166:169], v[182:185], v[52:55]
	v_mfma_f32_16x16x32_bf16 v[40:43], v[174:177], v[182:185], v[40:43]
	v_mfma_f32_16x16x32_bf16 v[32:35], v[166:169], v[190:193], v[32:35]
	v_mfma_f32_16x16x32_bf16 v[24:27], v[174:177], v[190:193], v[24:27]
	v_mfma_f32_16x16x32_bf16 v[16:19], v[166:169], v[198:201], v[16:19]
	v_mfma_f32_16x16x32_bf16 v[8:11], v[174:177], v[198:201], v[8:11]
	v_mfma_f32_16x16x32_bf16 v[4:7], v[166:169], v[206:209], v[4:7]
	v_mfma_f32_16x16x32_bf16 v[0:3], v[174:177], v[206:209], v[0:3]
	s_nop 0
	s_barrier
; #define PG8_STAGE(bufoff, gbase, voff) do { _Pragma("unroll") for (int _i = 0; _i < 2; ++_i) \
;         __builtin_amdgcn_global_load_lds((const unsigned*)((const char*)(gbase) + (voff)[_i]), (PG8_LAS unsigned*)(lds + (bufoff) + ldsw + _i * 8192), 16, 0, 0); } while (0)
; #define PG8_LDA(dst, b, h) do { _Pragma("unroll") for (int m = 0; m < 4; ++m) _Pragma("unroll") for (int k = 0; k < 2; ++k) dst[m][k] = *(const PG8_LAS bf16x8*)(lds + PG8_SA(b, h) + aoff + m * 2048 + k * 1024); } while (0)
; #define PG8_LDB(dst, b, h) do { _Pragma("unroll") for (int n = 0; n < 2; ++n) _Pragma("unroll") for (int k = 0; k < 2; ++k) dst[n][k] = *(const PG8_LAS bf16x8*)(lds + PG8_SB(b, h) + boff + n * 2048 + k * 1024); } while (0)
; #define PG8_MMA(ai, bj, At, Bt) do { __builtin_amdgcn_s_setprio(1); _Pragma("unroll") for (int m = 0; m < 4; ++m) _Pragma("unroll") for (int n = 0; n < 2; ++n) _Pragma("unroll") for (int k = 0; k < 2; ++k) \
;         acc[ai][bj][m][n] = __builtin_amdgcn_mfma_f32_16x16x32_bf16(Bt[n][k], At[m][k], acc[ai][bj][m][n], 0, 0, 0); __builtin_amdgcn_s_setprio(0); } while (0)
; #define PG8_WAIT_V(n) asm volatile("s_waitcnt vmcnt(" #n ")" ::: "memory")
; #define PG8_WAIT_L(n) asm volatile("s_waitcnt lgkmcnt(" #n ")" ::: "memory")
; #define PG8_BAR __builtin_amdgcn_s_barrier()
; #define PG8_SCHED __builtin_amdgcn_sched_barrier(0)
; template <class Epi, class Sched, bool ALIGN_EPI = GEMM_ALIGN, bool SP2 = GEMM_SP2>
; __device__ __forceinline__ void gemm_phase(PG8_LAS unsigned char* lds, const Gemm g, const Sched& S, const Epi& E, unsigned long long*  , int tid_in) {
;     ...
;             PG8_LDB(B0, 1, 0); PG8_LDB(B1, 1, 1); PG8_SCHED; PG8_LDA(At, 1, 0); PG8_STAGE(PG8_SA(0, 1), a2 + hstep, voffA);
;             PG8_WAIT_V(8); PG8_WAIT_L(0); PG8_BAR; PG8_MMA(0, 0, At, B0); PG8_MMA(0, 1, At, B1); PG8_BAR; PG8_SCHED;
	s_add_i32 s50, 0, 0x18000
	s_add_i32 s51, 0, 0x1c000
	v_add_u32_e32 v140, s50, v161
	v_add_u32_e32 v174, s51, v161
	ds_read_b128 v[128:131], v140
	ds_read_b128 v[132:135], v140 offset:1024
	ds_read_b128 v[136:139], v140 offset:2048
	ds_read_b128 v[140:143], v140 offset:3072
	ds_read_b128 v[156:159], v174
	ds_read_b128 v[166:169], v174 offset:1024
	ds_read_b128 v[170:173], v174 offset:2048
	ds_read_b128 v[174:177], v174 offset:3072
	s_add_u32 s24, s24, 0x40000
	s_addc_u32 s25, s25, 0
	s_mov_b32 m0, s34
	v_lshl_add_u64 v[218:219], s[24:25], 0, v[146:147]
	ds_read_b128 v[178:181], v165 offset:32768
	ds_read_b128 v[182:185], v165 offset:33792
	ds_read_b128 v[186:189], v165 offset:34816
	ds_read_b128 v[190:193], v165 offset:35840
	ds_read_b128 v[194:197], v165 offset:36864
	ds_read_b128 v[198:201], v165 offset:37888
	ds_read_b128 v[202:205], v165 offset:38912
	ds_read_b128 v[206:209], v165 offset:39936
	global_load_lds_dwordx4 v[218:219], off
	v_lshl_add_u64 v[218:219], s[24:25], 0, v[144:145]
	s_mov_b32 m0, s35
	s_nop 0
	global_load_lds_dwordx4 v[218:219], off
	s_waitcnt vmcnt(8)
	s_waitcnt lgkmcnt(0)
	s_barrier
	s_nop 0
	s_waitcnt lgkmcnt(0)
	v_mfma_f32_16x16x32_bf16 v[124:127], v[128:131], v[178:181], v[124:127]
	v_mfma_f32_16x16x32_bf16 v[120:123], v[136:139], v[178:181], v[120:123]
	v_mfma_f32_16x16x32_bf16 v[116:119], v[128:131], v[186:189], v[116:119]
	v_mfma_f32_16x16x32_bf16 v[112:115], v[136:139], v[186:189], v[112:115]
	v_mfma_f32_16x16x32_bf16 v[108:111], v[128:131], v[194:197], v[108:111]
	v_mfma_f32_16x16x32_bf16 v[100:103], v[136:139], v[194:197], v[100:103]
	v_mfma_f32_16x16x32_bf16 v[92:95], v[128:131], v[202:205], v[92:95]
	v_mfma_f32_16x16x32_bf16 v[84:87], v[136:139], v[202:205], v[84:87]
	v_mfma_f32_16x16x32_bf16 v[124:127], v[132:135], v[182:185], v[124:127]
	v_mfma_f32_16x16x32_bf16 v[120:123], v[140:143], v[182:185], v[120:123]
	v_mfma_f32_16x16x32_bf16 v[116:119], v[132:135], v[190:193], v[116:119]
	v_mfma_f32_16x16x32_bf16 v[112:115], v[140:143], v[190:193], v[112:115]
	v_mfma_f32_16x16x32_bf16 v[108:111], v[132:135], v[198:201], v[108:111]
	v_mfma_f32_16x16x32_bf16 v[100:103], v[140:143], v[198:201], v[100:103]
	v_mfma_f32_16x16x32_bf16 v[92:95], v[132:135], v[206:209], v[92:95]
	v_mfma_f32_16x16x32_bf16 v[84:87], v[140:143], v[206:209], v[84:87]
	s_nop 0
	s_nop 0
	v_mfma_f32_16x16x32_bf16 v[104:107], v[156:159], v[178:181], v[104:107]
	v_mfma_f32_16x16x32_bf16 v[96:99], v[170:173], v[178:181], v[96:99]
	v_mfma_f32_16x16x32_bf16 v[88:91], v[156:159], v[186:189], v[88:91]
	v_mfma_f32_16x16x32_bf16 v[80:83], v[170:173], v[186:189], v[80:83]
	v_mfma_f32_16x16x32_bf16 v[76:79], v[156:159], v[194:197], v[76:79]
	v_mfma_f32_16x16x32_bf16 v[72:75], v[170:173], v[194:197], v[72:75]
	v_mfma_f32_16x16x32_bf16 v[68:71], v[156:159], v[202:205], v[68:71]
	v_mfma_f32_16x16x32_bf16 v[64:67], v[170:173], v[202:205], v[64:67]
	v_mfma_f32_16x16x32_bf16 v[104:107], v[166:169], v[182:185], v[104:107]
	v_mfma_f32_16x16x32_bf16 v[96:99], v[174:177], v[182:185], v[96:99]
	v_mfma_f32_16x16x32_bf16 v[88:91], v[166:169], v[190:193], v[88:91]
	v_mfma_f32_16x16x32_bf16 v[80:83], v[174:177], v[190:193], v[80:83]
	v_mfma_f32_16x16x32_bf16 v[76:79], v[166:169], v[198:201], v[76:79]
	v_mfma_f32_16x16x32_bf16 v[72:75], v[174:177], v[198:201], v[72:75]
	v_mfma_f32_16x16x32_bf16 v[68:71], v[166:169], v[206:209], v[68:71]
	v_mfma_f32_16x16x32_bf16 v[64:67], v[174:177], v[206:209], v[64:67]
	s_nop 0
	s_barrier
; #define PG8_STAGE(bufoff, gbase, voff) do { _Pragma("unroll") for (int _i = 0; _i < 2; ++_i) \
;         __builtin_amdgcn_global_load_lds((const unsigned*)((const char*)(gbase) + (voff)[_i]), (PG8_LAS unsigned*)(lds + (bufoff) + ldsw + _i * 8192), 16, 0, 0); } while (0)
; #define PG8_LDA(dst, b, h) do { _Pragma("unroll") for (int m = 0; m < 4; ++m) _Pragma("unroll") for (int k = 0; k < 2; ++k) dst[m][k] = *(const PG8_LAS bf16x8*)(lds + PG8_SA(b, h) + aoff + m * 2048 + k * 1024); } while (0)
; #define PG8_MMA(ai, bj, At, Bt) do { __builtin_amdgcn_s_setprio(1); _Pragma("unroll") for (int m = 0; m < 4; ++m) _Pragma("unroll") for (int n = 0; n < 2; ++n) _Pragma("unroll") for (int k = 0; k < 2; ++k) \
;         acc[ai][bj][m][n] = __builtin_amdgcn_mfma_f32_16x16x32_bf16(Bt[n][k], At[m][k], acc[ai][bj][m][n], 0, 0, 0); __builtin_amdgcn_s_setprio(0); } while (0)
; #define PG8_WAIT_V(n) asm volatile("s_waitcnt vmcnt(" #n ")" ::: "memory")
; #define PG8_WAIT_L(n) asm volatile("s_waitcnt lgkmcnt(" #n ")" ::: "memory")
; #define PG8_BAR __builtin_amdgcn_s_barrier()
; #define PG8_SCHED __builtin_amdgcn_sched_barrier(0)
; template <class Epi, class Sched, bool ALIGN_EPI = GEMM_ALIGN, bool SP2 = GEMM_SP2>
; __device__ __forceinline__ void gemm_phase(PG8_LAS unsigned char* lds, const Gemm g, const Sched& S, const Epi& E, unsigned long long*  , int tid_in) {
;     ...
;         for (int t = 0; t < nt; t += 2) {
;             const bool last = (t == nt - 2);
;             const char* a1 = cA + (size_t)(t + 1) * kstep;
;             const char* a2 = last ? nA : cA + (size_t)(t + 2) * kstep; const char* b2 = last ? nB : cB + (size_t)(t + 2) * kstep;
;             const char* a3 = a2 + kstep; const char* b3 = b2 + kstep;
;             if (last && has_next) S.a_ready(nxt);
;     ...
;             PG8_LDA(At, 1, 1); PG8_STAGE(PG8_SB(1, 0), b3, voffB); PG8_STAGE(PG8_SB(1, 1), b3 + hstep, voffB); PG8_STAGE(PG8_SA(1, 0), a3, voffA);
;             PG8_WAIT_V(8); PG8_WAIT_L(0); PG8_BAR; PG8_MMA(1, 0, At, B0); PG8_MMA(1, 1, At, B1); PG8_BAR; PG8_SCHED;
	s_add_i32 s24, s50, s30
	v_lshl_add_u64 v[210:211], v[210:211], 0, s[6:7]
	s_mov_b32 m0, s24
	ds_read_b128 v[178:181], v165 offset:49152
	ds_read_b128 v[182:185], v165 offset:50176
	ds_read_b128 v[186:189], v165 offset:51200
	ds_read_b128 v[190:193], v165 offset:52224
	ds_read_b128 v[194:197], v165 offset:53248
	ds_read_b128 v[198:201], v165 offset:54272
	ds_read_b128 v[202:205], v165 offset:55296
	ds_read_b128 v[206:209], v165 offset:56320
	global_load_lds_dwordx4 v[210:211], off
	s_add_i32 m0, s24, 0x2000
	s_add_u32 s22, s22, 0x40080
	v_lshl_add_u64 v[210:211], v[212:213], 0, s[6:7]
	s_addc_u32 s23, s23, 0
	s_add_i32 s24, s51, s30
	global_load_lds_dwordx4 v[210:211], off
	v_lshl_add_u64 v[210:211], s[22:23], 0, v[146:147]
	s_mov_b32 m0, s24
	s_nop 0
	global_load_lds_dwordx4 v[210:211], off
	v_lshl_add_u64 v[210:211], s[22:23], 0, v[144:145]
	s_add_i32 m0, s24, 0x2000
	s_nop 0
	global_load_lds_dwordx4 v[210:211], off
	v_lshl_add_u64 v[210:211], v[214:215], 0, s[6:7]
	s_mov_b32 m0, s37
	s_nop 0
	global_load_lds_dwordx4 v[210:211], off
	v_lshl_add_u64 v[210:211], v[216:217], 0, s[6:7]
	s_mov_b32 m0, s38
	s_nop 0
	global_load_lds_dwordx4 v[210:211], off
	s_waitcnt vmcnt(8)
	s_waitcnt lgkmcnt(0)
	s_barrier
	s_nop 0
	s_waitcnt lgkmcnt(0)
	v_mfma_f32_16x16x32_bf16 v[60:63], v[128:131], v[178:181], v[60:63]
	v_mfma_f32_16x16x32_bf16 v[56:59], v[136:139], v[178:181], v[56:59]
	v_mfma_f32_16x16x32_bf16 v[48:51], v[128:131], v[186:189], v[48:51]
	v_mfma_f32_16x16x32_bf16 v[44:47], v[136:139], v[186:189], v[44:47]
	v_mfma_f32_16x16x32_bf16 v[36:39], v[128:131], v[194:197], v[36:39]
	v_mfma_f32_16x16x32_bf16 v[28:31], v[136:139], v[194:197], v[28:31]
	v_mfma_f32_16x16x32_bf16 v[20:23], v[128:131], v[202:205], v[20:23]
	v_mfma_f32_16x16x32_bf16 v[12:15], v[136:139], v[202:205], v[12:15]
	v_mfma_f32_16x16x32_bf16 v[60:63], v[132:135], v[182:185], v[60:63]
	v_mfma_f32_16x16x32_bf16 v[56:59], v[140:143], v[182:185], v[56:59]
	v_mfma_f32_16x16x32_bf16 v[48:51], v[132:135], v[190:193], v[48:51]
	v_mfma_f32_16x16x32_bf16 v[44:47], v[140:143], v[190:193], v[44:47]
	v_mfma_f32_16x16x32_bf16 v[36:39], v[132:135], v[198:201], v[36:39]
	v_mfma_f32_16x16x32_bf16 v[28:31], v[140:143], v[198:201], v[28:31]
	v_mfma_f32_16x16x32_bf16 v[20:23], v[132:135], v[206:209], v[20:23]
	v_mfma_f32_16x16x32_bf16 v[12:15], v[140:143], v[206:209], v[12:15]
	s_nop 0
	s_nop 0
	v_mfma_f32_16x16x32_bf16 v[52:55], v[156:159], v[178:181], v[52:55]
	v_mfma_f32_16x16x32_bf16 v[40:43], v[170:173], v[178:181], v[40:43]
	v_mfma_f32_16x16x32_bf16 v[32:35], v[156:159], v[186:189], v[32:35]
	v_mfma_f32_16x16x32_bf16 v[24:27], v[170:173], v[186:189], v[24:27]
	v_mfma_f32_16x16x32_bf16 v[16:19], v[156:159], v[194:197], v[16:19]
	v_mfma_f32_16x16x32_bf16 v[8:11], v[170:173], v[194:197], v[8:11]
	v_mfma_f32_16x16x32_bf16 v[4:7], v[156:159], v[202:205], v[4:7]
	v_mfma_f32_16x16x32_bf16 v[0:3], v[170:173], v[202:205], v[0:3]
	v_mfma_f32_16x16x32_bf16 v[52:55], v[166:169], v[182:185], v[52:55]
	v_mfma_f32_16x16x32_bf16 v[40:43], v[174:177], v[182:185], v[40:43]
	v_mfma_f32_16x16x32_bf16 v[32:35], v[166:169], v[190:193], v[32:35]
	v_mfma_f32_16x16x32_bf16 v[24:27], v[174:177], v[190:193], v[24:27]
	v_mfma_f32_16x16x32_bf16 v[16:19], v[166:169], v[198:201], v[16:19]
	v_mfma_f32_16x16x32_bf16 v[8:11], v[174:177], v[198:201], v[8:11]
	v_mfma_f32_16x16x32_bf16 v[4:7], v[166:169], v[206:209], v[4:7]
	v_mfma_f32_16x16x32_bf16 v[0:3], v[174:177], v[206:209], v[0:3]
	s_nop 0
	s_barrier
	s_add_i32 s49, s49, 2
	s_add_u32 s47, s47, 0x100
	s_addc_u32 s48, s48, 0
	s_add_u32 s20, s20, 0x100
	s_addc_u32 s21, s21, 0
	s_cmp_gt_u32 s49, 13
	s_cbranch_scc0 .LBB0_129
	s_setprio 0
	s_and_b64 vcc, exec, s[8:9]
	s_cbranch_vccz .LBB0_132
	s_barrier

; #define PG8_WAIT_V(n) asm volatile("s_waitcnt vmcnt(" #n ")" ::: "memory")
; template <class Epi, class Sched, bool ALIGN_EPI = GEMM_ALIGN, bool SP2 = GEMM_SP2>
; __device__ __forceinline__ void gemm_phase(PG8_LAS unsigned char* lds, const Gemm g, const Sched& S, const Epi& E, unsigned long long*  , int tid_in) {
;     ...
;     f32x4 acc[2][2][4][2];
; #pragma unroll
;     for (int a = 0; a < 2; ++a)
; #pragma unroll
;         for (int b = 0; b < 2; ++b)
; #pragma unroll
;             for (int m = 0; m < 4; ++m)
; #pragma unroll
;                 for (int n = 0; n < 2; ++n) acc[a][b][m][n] = (f32x4){0.f, 0.f, 0.f, 0.f};
;     bf16x8 At[4][2], B0[2][2], B1[2][2];
;     const char* cA = (const char*)g.A + (size_t)cur.pm * tstep; const char* cB = (const char*)g.Bt + (size_t)cur.pn * tstep;
;     S.a_ready(cur);
;     if constexpr (SP2) {
;         PG8_STAGE(PG8_SB(0, 0), cB, voffB); PG8_STAGE(PG8_SB(0, 1), cB + hstep, voffB); PG8_STAGE(PG8_SA(0, 0), cA, voffA); PG8_STAGE(PG8_SA(0, 1), cA + hstep, voffA);
;         if (wr == 1) PG8_BAR;
;         PG8_WAIT_V(2); PG8_BAR;
;         PG8_STAGE(PG8_SB(1, 0), cB + kstep, voffB); PG8_STAGE(PG8_SA(1, 0), cA + kstep, voffA); PG8_STAGE(PG8_SB(1, 1), cB + hstep + kstep, voffB);
;         PG8_WAIT_V(6); PG8_BAR;
;     } else {
;         PG8_STAGE(PG8_SB(0, 0), cB, voffB); PG8_STAGE(PG8_SA(0, 0), cA, voffA); PG8_STAGE(PG8_SB(0, 1), cB + hstep, voffB); PG8_STAGE(PG8_SA(0, 1), cA + hstep, voffA);
;         if (wr == 1) PG8_BAR;
;         PG8_WAIT_V(4); PG8_BAR;
;         PG8_STAGE(PG8_SB(1, 0), cB + kstep, voffB); PG8_STAGE(PG8_SA(1, 0), cA + kstep, voffA); PG8_STAGE(PG8_SB(1, 1), cB + hstep + kstep, voffB);
;         PG8_WAIT_V(6); PG8_BAR;
;     }
;     for (;;) {
;         const bool has_next = S.next(ui + 1, nxt);
;         const char* nA = has_next ? (const char*)g.A + (size_t)nxt.pm * tstep : cA; const char* nB = has_next ? (const char*)g.Bt + (size_t)nxt.pn * tstep : cB;
;         for (int t = 0; t < nt; t += 2) {
;             const bool last = (t == nt - 2);
;             const char* a1 = cA + (size_t)(t + 1) * kstep;
;             const char* a2 = last ? nA : cA + (size_t)(t + 2) * kstep; const char* b2 = last ? nB : cB + (size_t)(t + 2) * kstep;
;             const char* a3 = a2 + kstep; const char* b3 = b2 + kstep;
;             if (last && has_next) S.a_ready(nxt);
;             if constexpr (SP2) {
.LBB0_251:
	s_ashr_i32 s15, s14, 31
	s_lshl_b64 s[16:17], s[14:15], 19
	s_add_u32 s16, s26, s16
	s_addc_u32 s17, s27, s17
	s_and_b64 s[18:19], s[0:1], exec
	s_cselect_b32 s15, s17, s23
	s_cselect_b32 s58, s16, s22
	s_ashr_i32 s13, s12, 31
	s_lshl_b64 s[18:19], s[12:13], 19
	s_add_u32 s18, s4, s18
	s_addc_u32 s19, s5, s19
	s_and_b64 s[24:25], s[0:1], exec
	s_cselect_b32 s13, s19, s21
	s_cselect_b32 s59, s18, s20
	s_add_u32 s60, s20, 0x100
	s_addc_u32 s61, s21, 0
	s_add_u32 s20, s22, 0x40080
	v_mov_b32_e32 v0, 0
	s_addc_u32 s21, s23, 0
	s_mov_b32 s62, -2
	v_mov_b32_e32 v1, v0
	v_mov_b32_e32 v2, v0
	v_mov_b32_e32 v3, v0
	v_mov_b32_e32 v4, v0
	v_mov_b32_e32 v5, v0
	v_mov_b32_e32 v6, v0
	v_mov_b32_e32 v7, v0
	v_mov_b32_e32 v12, v0
	v_mov_b32_e32 v13, v0
	v_mov_b32_e32 v14, v0
	v_mov_b32_e32 v15, v0
	v_mov_b32_e32 v20, v0
	v_mov_b32_e32 v21, v0
	v_mov_b32_e32 v22, v0
	v_mov_b32_e32 v23, v0
	v_mov_b32_e32 v28, v0
	v_mov_b32_e32 v29, v0
	v_mov_b32_e32 v30, v0
	v_mov_b32_e32 v31, v0
	v_mov_b32_e32 v36, v0
	v_mov_b32_e32 v37, v0
	v_mov_b32_e32 v38, v0
	v_mov_b32_e32 v39, v0
	v_mov_b32_e32 v44, v0
	v_mov_b32_e32 v45, v0
	v_mov_b32_e32 v46, v0
	v_mov_b32_e32 v47, v0
	v_mov_b32_e32 v52, v0
	v_mov_b32_e32 v53, v0
	v_mov_b32_e32 v54, v0
	v_mov_b32_e32 v55, v0
	v_mov_b32_e32 v16, v0
	v_mov_b32_e32 v17, v0
	v_mov_b32_e32 v18, v0
	v_mov_b32_e32 v19, v0
	v_mov_b32_e32 v24, v0
	v_mov_b32_e32 v25, v0
	v_mov_b32_e32 v26, v0
	v_mov_b32_e32 v27, v0
	v_mov_b32_e32 v32, v0
	v_mov_b32_e32 v33, v0
	v_mov_b32_e32 v34, v0
	v_mov_b32_e32 v35, v0
	v_mov_b32_e32 v40, v0
	v_mov_b32_e32 v41, v0
	v_mov_b32_e32 v42, v0
	v_mov_b32_e32 v43, v0
	v_mov_b32_e32 v48, v0
	v_mov_b32_e32 v49, v0
	v_mov_b32_e32 v50, v0
	v_mov_b32_e32 v51, v0
	v_mov_b32_e32 v56, v0
	v_mov_b32_e32 v57, v0
	v_mov_b32_e32 v58, v0
	v_mov_b32_e32 v59, v0
	v_mov_b32_e32 v60, v0
	v_mov_b32_e32 v61, v0
	v_mov_b32_e32 v62, v0
	v_mov_b32_e32 v63, v0
	v_mov_b32_e32 v64, v0
	v_mov_b32_e32 v65, v0
	v_mov_b32_e32 v66, v0
	v_mov_b32_e32 v67, v0
	v_mov_b32_e32 v68, v0
	v_mov_b32_e32 v69, v0
	v_mov_b32_e32 v70, v0
	v_mov_b32_e32 v71, v0
	v_mov_b32_e32 v72, v0
	v_mov_b32_e32 v73, v0
	v_mov_b32_e32 v74, v0
	v_mov_b32_e32 v75, v0
	v_mov_b32_e32 v76, v0
	v_mov_b32_e32 v77, v0
	v_mov_b32_e32 v78, v0
	v_mov_b32_e32 v79, v0
	v_mov_b32_e32 v84, v0
	v_mov_b32_e32 v85, v0
	v_mov_b32_e32 v86, v0
	v_mov_b32_e32 v87, v0
	v_mov_b32_e32 v92, v0
	v_mov_b32_e32 v93, v0
	v_mov_b32_e32 v94, v0
	v_mov_b32_e32 v95, v0
	v_mov_b32_e32 v100, v0
	v_mov_b32_e32 v101, v0
	v_mov_b32_e32 v102, v0
	v_mov_b32_e32 v103, v0
	v_mov_b32_e32 v108, v0
	v_mov_b32_e32 v109, v0
	v_mov_b32_e32 v110, v0
	v_mov_b32_e32 v111, v0
	v_mov_b32_e32 v116, v0
	v_mov_b32_e32 v117, v0
	v_mov_b32_e32 v118, v0
	v_mov_b32_e32 v119, v0
	v_mov_b32_e32 v80, v0
	v_mov_b32_e32 v81, v0
	v_mov_b32_e32 v82, v0
	v_mov_b32_e32 v83, v0
	v_mov_b32_e32 v88, v0
	v_mov_b32_e32 v89, v0
	v_mov_b32_e32 v90, v0
	v_mov_b32_e32 v91, v0
	v_mov_b32_e32 v96, v0
	v_mov_b32_e32 v97, v0
	v_mov_b32_e32 v98, v0
	v_mov_b32_e32 v99, v0
	v_mov_b32_e32 v104, v0
	v_mov_b32_e32 v105, v0
	v_mov_b32_e32 v106, v0
	v_mov_b32_e32 v107, v0
	v_mov_b32_e32 v112, v0
	v_mov_b32_e32 v113, v0
	v_mov_b32_e32 v114, v0
	v_mov_b32_e32 v115, v0
	v_mov_b32_e32 v120, v0
	v_mov_b32_e32 v121, v0
	v_mov_b32_e32 v122, v0
	v_mov_b32_e32 v123, v0
	v_mov_b32_e32 v124, v0
	v_mov_b32_e32 v125, v0
	v_mov_b32_e32 v126, v0
	v_mov_b32_e32 v127, v0
	v_mov_b32_e32 v128, v0
	v_mov_b32_e32 v129, v0
	v_mov_b32_e32 v130, v0
	v_mov_b32_e32 v131, v0
	s_and_b64 vcc, exec, s[10:11]
	s_cbranch_vccnz .Lprio_252
	s_setprio 1
.Lprio_252:
.LBB0_252:
	s_add_u32 s22, s20, 0xfffc0080
	s_addc_u32 s23, s21, -1
	s_add_i32 s63, 0, 0x10000
	s_cmp_eq_u32 s62, 12
	s_cselect_b32 s25, s15, s23
	s_cselect_b32 s24, s58, s22
	v_add_u32_e32 v140, s63, v142
	s_cselect_b32 s23, s13, s61
	s_cselect_b32 s22, s59, s60
	s_add_i32 s64, 0, 0x14000
	ds_read_b128 v[156:159], v140
	ds_read_b128 v[160:163], v140 offset:1024
	ds_read_b128 v[164:167], v140 offset:2048
	ds_read_b128 v[168:171], v140 offset:3072
	v_add_u32_e32 v140, s64, v142
	ds_read_b128 v[172:175], v140
	ds_read_b128 v[188:191], v140 offset:1024
	ds_read_b128 v[192:195], v140 offset:2048
	ds_read_b128 v[196:199], v140 offset:3072
	v_lshl_add_u64 v[140:141], s[20:21], 0, v[138:139]
	s_add_i32 m0, s29, 0xc000
	ds_read_b128 v[200:203], v146
	ds_read_b128 v[204:207], v146 offset:1024
	ds_read_b128 v[208:211], v146 offset:2048
	ds_read_b128 v[212:215], v146 offset:3072
	ds_read_b128 v[216:219], v146 offset:4096
	ds_read_b128 v[220:223], v146 offset:5120
	ds_read_b128 v[224:227], v146 offset:6144
	ds_read_b128 v[228:231], v146 offset:7168
	global_load_lds_dwordx4 v[140:141], off
	v_lshl_add_u64 v[140:141], s[20:21], 0, v[136:137]
	s_add_i32 m0, s29, 0xe000
	s_nop 0
	global_load_lds_dwordx4 v[140:141], off
	s_waitcnt vmcnt(8)
	s_waitcnt lgkmcnt(0)
	s_barrier
; #define PG8_STAGE(bufoff, gbase, voff) do { _Pragma("unroll") for (int _i = 0; _i < 2; ++_i) \
;         __builtin_amdgcn_global_load_lds((const unsigned*)((const char*)(gbase) + (voff)[_i]), (PG8_LAS unsigned*)(lds + (bufoff) + ldsw + _i * 8192), 16, 0, 0); } while (0)
; #define PG8_LDA(dst, b, h) do { _Pragma("unroll") for (int m = 0; m < 4; ++m) _Pragma("unroll") for (int k = 0; k < 2; ++k) dst[m][k] = *(const PG8_LAS bf16x8*)(lds + PG8_SA(b, h) + aoff + m * 2048 + k * 1024); } while (0)
; #define PG8_MMA(ai, bj, At, Bt) do { __builtin_amdgcn_s_setprio(1); _Pragma("unroll") for (int m = 0; m < 4; ++m) _Pragma("unroll") for (int n = 0; n < 2; ++n) _Pragma("unroll") for (int k = 0; k < 2; ++k) \
;         acc[ai][bj][m][n] = __builtin_amdgcn_mfma_f32_16x16x32_bf16(Bt[n][k], At[m][k], acc[ai][bj][m][n], 0, 0, 0); __builtin_amdgcn_s_setprio(0); } while (0)
; #define PG8_WAIT_V(n) asm volatile("s_waitcnt vmcnt(" #n ")" ::: "memory")
; #define PG8_WAIT_L(n) asm volatile("s_waitcnt lgkmcnt(" #n ")" ::: "memory")
; #define PG8_BAR __builtin_amdgcn_s_barrier()
; #define PG8_SCHED __builtin_amdgcn_sched_barrier(0)
; template <class Epi, class Sched, bool ALIGN_EPI = GEMM_ALIGN, bool SP2 = GEMM_SP2>
; __device__ __forceinline__ void gemm_phase(PG8_LAS unsigned char* lds, const Gemm g, const Sched& S, const Epi& E, unsigned long long*  , int tid_in) {
;     ...
;             PG8_WAIT_V(8); PG8_WAIT_L(0); PG8_BAR; PG8_MMA(0, 0, At, B0); PG8_MMA(0, 1, At, B1); PG8_BAR; PG8_SCHED;
;             PG8_LDA(At, 0, 1); PG8_STAGE(PG8_SB(0, 0), b2, voffB); PG8_STAGE(PG8_SB(0, 1), b2 + hstep, voffB); PG8_STAGE(PG8_SA(0, 0), a2, voffA);
;             PG8_WAIT_V(8); PG8_WAIT_L(0); PG8_BAR; PG8_MMA(1, 0, At, B0); PG8_MMA(1, 1, At, B1); PG8_BAR; PG8_SCHED;
	s_nop 0
	s_waitcnt lgkmcnt(0)
	v_mfma_f32_16x16x32_bf16 v[128:131], v[156:159], v[200:203], v[128:131]
	v_mfma_f32_16x16x32_bf16 v[124:127], v[164:167], v[200:203], v[124:127]
	v_mfma_f32_16x16x32_bf16 v[120:123], v[156:159], v[208:211], v[120:123]
	v_mfma_f32_16x16x32_bf16 v[112:115], v[164:167], v[208:211], v[112:115]
	v_mfma_f32_16x16x32_bf16 v[104:107], v[156:159], v[216:219], v[104:107]
	v_mfma_f32_16x16x32_bf16 v[96:99], v[164:167], v[216:219], v[96:99]
	v_mfma_f32_16x16x32_bf16 v[88:91], v[156:159], v[224:227], v[88:91]
	v_mfma_f32_16x16x32_bf16 v[80:83], v[164:167], v[224:227], v[80:83]
	v_mfma_f32_16x16x32_bf16 v[128:131], v[160:163], v[204:207], v[128:131]
	v_mfma_f32_16x16x32_bf16 v[124:127], v[168:171], v[204:207], v[124:127]
	v_mfma_f32_16x16x32_bf16 v[120:123], v[160:163], v[212:215], v[120:123]
	v_mfma_f32_16x16x32_bf16 v[112:115], v[168:171], v[212:215], v[112:115]
	v_mfma_f32_16x16x32_bf16 v[104:107], v[160:163], v[220:223], v[104:107]
	v_mfma_f32_16x16x32_bf16 v[96:99], v[168:171], v[220:223], v[96:99]
	v_mfma_f32_16x16x32_bf16 v[88:91], v[160:163], v[228:231], v[88:91]
	v_mfma_f32_16x16x32_bf16 v[80:83], v[168:171], v[228:231], v[80:83]
	s_nop 0
	s_nop 0
	v_mfma_f32_16x16x32_bf16 v[116:119], v[172:175], v[200:203], v[116:119]
	v_mfma_f32_16x16x32_bf16 v[108:111], v[192:195], v[200:203], v[108:111]
	v_mfma_f32_16x16x32_bf16 v[100:103], v[172:175], v[208:211], v[100:103]
	v_mfma_f32_16x16x32_bf16 v[92:95], v[192:195], v[208:211], v[92:95]
	v_mfma_f32_16x16x32_bf16 v[84:87], v[172:175], v[216:219], v[84:87]
	v_mfma_f32_16x16x32_bf16 v[76:79], v[192:195], v[216:219], v[76:79]
	v_mfma_f32_16x16x32_bf16 v[72:75], v[172:175], v[224:227], v[72:75]
	v_mfma_f32_16x16x32_bf16 v[68:71], v[192:195], v[224:227], v[68:71]
	v_mfma_f32_16x16x32_bf16 v[116:119], v[188:191], v[204:207], v[116:119]
	v_mfma_f32_16x16x32_bf16 v[108:111], v[196:199], v[204:207], v[108:111]
	v_mfma_f32_16x16x32_bf16 v[100:103], v[188:191], v[212:215], v[100:103]
	v_mfma_f32_16x16x32_bf16 v[92:95], v[196:199], v[212:215], v[92:95]
	v_mfma_f32_16x16x32_bf16 v[84:87], v[188:191], v[220:223], v[84:87]
	v_mfma_f32_16x16x32_bf16 v[76:79], v[196:199], v[220:223], v[76:79]
	v_mfma_f32_16x16x32_bf16 v[72:75], v[188:191], v[228:231], v[72:75]
	v_mfma_f32_16x16x32_bf16 v[68:71], v[196:199], v[228:231], v[68:71]
	s_nop 0
	s_barrier
	s_add_i32 s63, s63, s28
	v_lshl_add_u64 v[140:141], s[22:23], 0, v[10:11]
	s_mov_b32 m0, s63
	ds_read_b128 v[200:203], v146 offset:16384
	ds_read_b128 v[204:207], v146 offset:17408
	ds_read_b128 v[208:211], v146 offset:18432
	ds_read_b128 v[212:215], v146 offset:19456
	ds_read_b128 v[216:219], v146 offset:20480
	ds_read_b128 v[220:223], v146 offset:21504
	ds_read_b128 v[224:227], v146 offset:22528
	ds_read_b128 v[228:231], v146 offset:23552
	global_load_lds_dwordx4 v[140:141], off
	s_add_i32 m0, s63, 0x2000
	s_add_u32 s66, s22, 0x40000
	v_lshl_add_u64 v[232:233], s[22:23], 0, v[8:9]
	s_addc_u32 s67, s23, 0
	s_add_i32 s63, s64, s28
	global_load_lds_dwordx4 v[232:233], off
	v_lshl_add_u64 v[234:235], s[66:67], 0, v[10:11]
	s_mov_b32 m0, s63
	v_lshl_add_u64 v[236:237], s[24:25], 0, v[132:133]
	global_load_lds_dwordx4 v[234:235], off
	v_lshl_add_u64 v[234:235], s[66:67], 0, v[8:9]
	s_add_i32 m0, s63, 0x2000
	s_nop 0
	global_load_lds_dwordx4 v[234:235], off
	v_lshl_add_u64 v[234:235], s[24:25], 0, v[134:135]
	s_mov_b32 m0, s29
	s_nop 0
	global_load_lds_dwordx4 v[234:235], off
	s_mov_b32 m0, s30
	s_nop 0
	global_load_lds_dwordx4 v[236:237], off
	s_waitcnt vmcnt(8)
	s_waitcnt lgkmcnt(0)
	s_barrier
	s_nop 0
	s_waitcnt lgkmcnt(0)
	v_mfma_f32_16x16x32_bf16 v[64:67], v[156:159], v[200:203], v[64:67]
	v_mfma_f32_16x16x32_bf16 v[60:63], v[164:167], v[200:203], v[60:63]
	v_mfma_f32_16x16x32_bf16 v[56:59], v[156:159], v[208:211], v[56:59]
	v_mfma_f32_16x16x32_bf16 v[48:51], v[164:167], v[208:211], v[48:51]
	v_mfma_f32_16x16x32_bf16 v[40:43], v[156:159], v[216:219], v[40:43]
	v_mfma_f32_16x16x32_bf16 v[32:35], v[164:167], v[216:219], v[32:35]
	v_mfma_f32_16x16x32_bf16 v[24:27], v[156:159], v[224:227], v[24:27]
	v_mfma_f32_16x16x32_bf16 v[16:19], v[164:167], v[224:227], v[16:19]
	v_mfma_f32_16x16x32_bf16 v[64:67], v[160:163], v[204:207], v[64:67]
	v_mfma_f32_16x16x32_bf16 v[60:63], v[168:171], v[204:207], v[60:63]
	v_mfma_f32_16x16x32_bf16 v[56:59], v[160:163], v[212:215], v[56:59]
	v_mfma_f32_16x16x32_bf16 v[48:51], v[168:171], v[212:215], v[48:51]
	v_mfma_f32_16x16x32_bf16 v[40:43], v[160:163], v[220:223], v[40:43]
	v_mfma_f32_16x16x32_bf16 v[32:35], v[168:171], v[220:223], v[32:35]
	v_mfma_f32_16x16x32_bf16 v[24:27], v[160:163], v[228:231], v[24:27]
	v_mfma_f32_16x16x32_bf16 v[16:19], v[168:171], v[228:231], v[16:19]
	s_nop 0
	s_nop 0
	v_mfma_f32_16x16x32_bf16 v[52:55], v[172:175], v[200:203], v[52:55]
	v_mfma_f32_16x16x32_bf16 v[44:47], v[192:195], v[200:203], v[44:47]
	v_mfma_f32_16x16x32_bf16 v[36:39], v[172:175], v[208:211], v[36:39]
	v_mfma_f32_16x16x32_bf16 v[28:31], v[192:195], v[208:211], v[28:31]
	v_mfma_f32_16x16x32_bf16 v[20:23], v[172:175], v[216:219], v[20:23]
	v_mfma_f32_16x16x32_bf16 v[12:15], v[192:195], v[216:219], v[12:15]
	v_mfma_f32_16x16x32_bf16 v[4:7], v[172:175], v[224:227], v[4:7]
	v_mfma_f32_16x16x32_bf16 v[0:3], v[192:195], v[224:227], v[0:3]
	v_mfma_f32_16x16x32_bf16 v[52:55], v[188:191], v[204:207], v[52:55]
	v_mfma_f32_16x16x32_bf16 v[44:47], v[196:199], v[204:207], v[44:47]
	v_mfma_f32_16x16x32_bf16 v[36:39], v[188:191], v[212:215], v[36:39]
	v_mfma_f32_16x16x32_bf16 v[28:31], v[196:199], v[212:215], v[28:31]
	v_mfma_f32_16x16x32_bf16 v[20:23], v[188:191], v[220:223], v[20:23]
	v_mfma_f32_16x16x32_bf16 v[12:15], v[196:199], v[220:223], v[12:15]
	v_mfma_f32_16x16x32_bf16 v[4:7], v[188:191], v[228:231], v[4:7]
	v_mfma_f32_16x16x32_bf16 v[0:3], v[196:199], v[228:231], v[0:3]
	s_nop 0
	s_barrier
; #define PG8_STAGE(bufoff, gbase, voff) do { _Pragma("unroll") for (int _i = 0; _i < 2; ++_i) \
;         __builtin_amdgcn_global_load_lds((const unsigned*)((const char*)(gbase) + (voff)[_i]), (PG8_LAS unsigned*)(lds + (bufoff) + ldsw + _i * 8192), 16, 0, 0); } while (0)
; #define PG8_LDA(dst, b, h) do { _Pragma("unroll") for (int m = 0; m < 4; ++m) _Pragma("unroll") for (int k = 0; k < 2; ++k) dst[m][k] = *(const PG8_LAS bf16x8*)(lds + PG8_SA(b, h) + aoff + m * 2048 + k * 1024); } while (0)
; #define PG8_LDB(dst, b, h) do { _Pragma("unroll") for (int n = 0; n < 2; ++n) _Pragma("unroll") for (int k = 0; k < 2; ++k) dst[n][k] = *(const PG8_LAS bf16x8*)(lds + PG8_SB(b, h) + boff + n * 2048 + k * 1024); } while (0)
; #define PG8_MMA(ai, bj, At, Bt) do { __builtin_amdgcn_s_setprio(1); _Pragma("unroll") for (int m = 0; m < 4; ++m) _Pragma("unroll") for (int n = 0; n < 2; ++n) _Pragma("unroll") for (int k = 0; k < 2; ++k) \
;         acc[ai][bj][m][n] = __builtin_amdgcn_mfma_f32_16x16x32_bf16(Bt[n][k], At[m][k], acc[ai][bj][m][n], 0, 0, 0); __builtin_amdgcn_s_setprio(0); } while (0)
; #define PG8_WAIT_V(n) asm volatile("s_waitcnt vmcnt(" #n ")" ::: "memory")
; #define PG8_WAIT_L(n) asm volatile("s_waitcnt lgkmcnt(" #n ")" ::: "memory")
; #define PG8_BAR __builtin_amdgcn_s_barrier()
; #define PG8_SCHED __builtin_amdgcn_sched_barrier(0)
; template <class Epi, class Sched, bool ALIGN_EPI = GEMM_ALIGN, bool SP2 = GEMM_SP2>
; __device__ __forceinline__ void gemm_phase(PG8_LAS unsigned char* lds, const Gemm g, const Sched& S, const Epi& E, unsigned long long*  , int tid_in) {
;     ...
;             PG8_LDB(B0, 1, 0); PG8_LDB(B1, 1, 1); PG8_SCHED; PG8_LDA(At, 1, 0); PG8_STAGE(PG8_SA(0, 1), a2 + hstep, voffA);
;             PG8_WAIT_V(8); PG8_WAIT_L(0); PG8_BAR; PG8_MMA(0, 0, At, B0); PG8_MMA(0, 1, At, B1); PG8_BAR; PG8_SCHED;
	s_add_i32 s63, 0, 0x18000
	v_add_u32_e32 v147, s63, v142
	s_add_i32 s64, 0, 0x1c000
	ds_read_b128 v[156:159], v147
	ds_read_b128 v[160:163], v147 offset:1024
	ds_read_b128 v[164:167], v147 offset:2048
	ds_read_b128 v[168:171], v147 offset:3072
	v_add_u32_e32 v147, s64, v142
	ds_read_b128 v[172:175], v147
	ds_read_b128 v[188:191], v147 offset:1024
	ds_read_b128 v[192:195], v147 offset:2048
	ds_read_b128 v[196:199], v147 offset:3072
	s_add_u32 s24, s24, 0x40000
	s_addc_u32 s25, s25, 0
	s_mov_b32 m0, s31
	v_lshl_add_u64 v[238:239], s[24:25], 0, v[134:135]
	ds_read_b128 v[200:203], v146 offset:32768
	ds_read_b128 v[204:207], v146 offset:33792
	ds_read_b128 v[208:211], v146 offset:34816
	ds_read_b128 v[212:215], v146 offset:35840
	ds_read_b128 v[216:219], v146 offset:36864
	ds_read_b128 v[220:223], v146 offset:37888
	ds_read_b128 v[224:227], v146 offset:38912
	ds_read_b128 v[228:231], v146 offset:39936
	global_load_lds_dwordx4 v[238:239], off
	v_lshl_add_u64 v[238:239], s[24:25], 0, v[132:133]
	s_mov_b32 m0, s34
	s_nop 0
	global_load_lds_dwordx4 v[238:239], off
	s_waitcnt vmcnt(8)
	s_waitcnt lgkmcnt(0)
	s_barrier
	s_nop 0
	s_waitcnt lgkmcnt(0)
	v_mfma_f32_16x16x32_bf16 v[128:131], v[156:159], v[200:203], v[128:131]
	v_mfma_f32_16x16x32_bf16 v[124:127], v[164:167], v[200:203], v[124:127]
	v_mfma_f32_16x16x32_bf16 v[120:123], v[156:159], v[208:211], v[120:123]
	v_mfma_f32_16x16x32_bf16 v[112:115], v[164:167], v[208:211], v[112:115]
	v_mfma_f32_16x16x32_bf16 v[104:107], v[156:159], v[216:219], v[104:107]
	v_mfma_f32_16x16x32_bf16 v[96:99], v[164:167], v[216:219], v[96:99]
	v_mfma_f32_16x16x32_bf16 v[88:91], v[156:159], v[224:227], v[88:91]
	v_mfma_f32_16x16x32_bf16 v[80:83], v[164:167], v[224:227], v[80:83]
	v_mfma_f32_16x16x32_bf16 v[128:131], v[160:163], v[204:207], v[128:131]
	v_mfma_f32_16x16x32_bf16 v[124:127], v[168:171], v[204:207], v[124:127]
	v_mfma_f32_16x16x32_bf16 v[120:123], v[160:163], v[212:215], v[120:123]
	v_mfma_f32_16x16x32_bf16 v[112:115], v[168:171], v[212:215], v[112:115]
	v_mfma_f32_16x16x32_bf16 v[104:107], v[160:163], v[220:223], v[104:107]
	v_mfma_f32_16x16x32_bf16 v[96:99], v[168:171], v[220:223], v[96:99]
	v_mfma_f32_16x16x32_bf16 v[88:91], v[160:163], v[228:231], v[88:91]
	v_mfma_f32_16x16x32_bf16 v[80:83], v[168:171], v[228:231], v[80:83]
	s_nop 0
	s_nop 0
	v_mfma_f32_16x16x32_bf16 v[116:119], v[172:175], v[200:203], v[116:119]
	v_mfma_f32_16x16x32_bf16 v[108:111], v[192:195], v[200:203], v[108:111]
	v_mfma_f32_16x16x32_bf16 v[100:103], v[172:175], v[208:211], v[100:103]
	v_mfma_f32_16x16x32_bf16 v[92:95], v[192:195], v[208:211], v[92:95]
	v_mfma_f32_16x16x32_bf16 v[84:87], v[172:175], v[216:219], v[84:87]
	v_mfma_f32_16x16x32_bf16 v[76:79], v[192:195], v[216:219], v[76:79]
	v_mfma_f32_16x16x32_bf16 v[72:75], v[172:175], v[224:227], v[72:75]
	v_mfma_f32_16x16x32_bf16 v[68:71], v[192:195], v[224:227], v[68:71]
	v_mfma_f32_16x16x32_bf16 v[116:119], v[188:191], v[204:207], v[116:119]
	v_mfma_f32_16x16x32_bf16 v[108:111], v[196:199], v[204:207], v[108:111]
	v_mfma_f32_16x16x32_bf16 v[100:103], v[188:191], v[212:215], v[100:103]
	v_mfma_f32_16x16x32_bf16 v[92:95], v[196:199], v[212:215], v[92:95]
	v_mfma_f32_16x16x32_bf16 v[84:87], v[188:191], v[220:223], v[84:87]
	v_mfma_f32_16x16x32_bf16 v[76:79], v[196:199], v[220:223], v[76:79]
	v_mfma_f32_16x16x32_bf16 v[72:75], v[188:191], v[228:231], v[72:75]
	v_mfma_f32_16x16x32_bf16 v[68:71], v[196:199], v[228:231], v[68:71]
	s_nop 0
	s_barrier
; #define PG8_STAGE(bufoff, gbase, voff) do { _Pragma("unroll") for (int _i = 0; _i < 2; ++_i) \
;         __builtin_amdgcn_global_load_lds((const unsigned*)((const char*)(gbase) + (voff)[_i]), (PG8_LAS unsigned*)(lds + (bufoff) + ldsw + _i * 8192), 16, 0, 0); } while (0)
; #define PG8_LDA(dst, b, h) do { _Pragma("unroll") for (int m = 0; m < 4; ++m) _Pragma("unroll") for (int k = 0; k < 2; ++k) dst[m][k] = *(const PG8_LAS bf16x8*)(lds + PG8_SA(b, h) + aoff + m * 2048 + k * 1024); } while (0)
; #define PG8_MMA(ai, bj, At, Bt) do { __builtin_amdgcn_s_setprio(1); _Pragma("unroll") for (int m = 0; m < 4; ++m) _Pragma("unroll") for (int n = 0; n < 2; ++n) _Pragma("unroll") for (int k = 0; k < 2; ++k) \
;         acc[ai][bj][m][n] = __builtin_amdgcn_mfma_f32_16x16x32_bf16(Bt[n][k], At[m][k], acc[ai][bj][m][n], 0, 0, 0); __builtin_amdgcn_s_setprio(0); } while (0)
; #define PG8_WAIT_V(n) asm volatile("s_waitcnt vmcnt(" #n ")" ::: "memory")
; #define PG8_WAIT_L(n) asm volatile("s_waitcnt lgkmcnt(" #n ")" ::: "memory")
; #define PG8_BAR __builtin_amdgcn_s_barrier()
; #define PG8_SCHED __builtin_amdgcn_sched_barrier(0)
; template <class Epi, class Sched, bool ALIGN_EPI = GEMM_ALIGN, bool SP2 = GEMM_SP2>
; __device__ __forceinline__ void gemm_phase(PG8_LAS unsigned char* lds, const Gemm g, const Sched& S, const Epi& E, unsigned long long*  , int tid_in) {
;     ...
;         for (int t = 0; t < nt; t += 2) {
;             const bool last = (t == nt - 2);
;             const char* a1 = cA + (size_t)(t + 1) * kstep;
;             const char* a2 = last ? nA : cA + (size_t)(t + 2) * kstep; const char* b2 = last ? nB : cB + (size_t)(t + 2) * kstep;
;             const char* a3 = a2 + kstep; const char* b3 = b2 + kstep;
;             if (last && has_next) S.a_ready(nxt);
;     ...
;             PG8_LDA(At, 1, 1); PG8_STAGE(PG8_SB(1, 0), b3, voffB); PG8_STAGE(PG8_SB(1, 1), b3 + hstep, voffB); PG8_STAGE(PG8_SA(1, 0), a3, voffA);
;             PG8_WAIT_V(8); PG8_WAIT_L(0); PG8_BAR; PG8_MMA(1, 0, At, B0); PG8_MMA(1, 1, At, B1); PG8_BAR; PG8_SCHED;
	s_add_i32 s24, s63, s28
	v_lshl_add_u64 v[140:141], v[140:141], 0, s[82:83]
	s_mov_b32 m0, s24
	ds_read_b128 v[200:203], v146 offset:49152
	ds_read_b128 v[204:207], v146 offset:50176
	ds_read_b128 v[208:211], v146 offset:51200
	ds_read_b128 v[212:215], v146 offset:52224
	ds_read_b128 v[216:219], v146 offset:53248
	ds_read_b128 v[220:223], v146 offset:54272
	ds_read_b128 v[224:227], v146 offset:55296
	ds_read_b128 v[228:231], v146 offset:56320
	global_load_lds_dwordx4 v[140:141], off
	s_add_i32 m0, s24, 0x2000
	s_add_u32 s22, s22, 0x40080
	v_lshl_add_u64 v[140:141], v[232:233], 0, s[82:83]
	s_addc_u32 s23, s23, 0
	s_add_i32 s24, s64, s28
	global_load_lds_dwordx4 v[140:141], off
	v_lshl_add_u64 v[140:141], s[22:23], 0, v[10:11]
	s_mov_b32 m0, s24
	s_nop 0
	global_load_lds_dwordx4 v[140:141], off
	v_lshl_add_u64 v[140:141], s[22:23], 0, v[8:9]
	s_add_i32 m0, s24, 0x2000
	s_nop 0
	global_load_lds_dwordx4 v[140:141], off
	v_lshl_add_u64 v[140:141], v[234:235], 0, s[82:83]
	s_mov_b32 m0, s35
	s_nop 0
	global_load_lds_dwordx4 v[140:141], off
	v_lshl_add_u64 v[140:141], v[236:237], 0, s[82:83]
	s_mov_b32 m0, s36
	s_nop 0
	global_load_lds_dwordx4 v[140:141], off
	s_waitcnt vmcnt(8)
	s_waitcnt lgkmcnt(0)
	s_barrier
	s_nop 0
	s_waitcnt lgkmcnt(0)
	v_mfma_f32_16x16x32_bf16 v[64:67], v[156:159], v[200:203], v[64:67]
	v_mfma_f32_16x16x32_bf16 v[60:63], v[164:167], v[200:203], v[60:63]
	v_mfma_f32_16x16x32_bf16 v[56:59], v[156:159], v[208:211], v[56:59]
	v_mfma_f32_16x16x32_bf16 v[48:51], v[164:167], v[208:211], v[48:51]
	v_mfma_f32_16x16x32_bf16 v[40:43], v[156:159], v[216:219], v[40:43]
	v_mfma_f32_16x16x32_bf16 v[32:35], v[164:167], v[216:219], v[32:35]
	v_mfma_f32_16x16x32_bf16 v[24:27], v[156:159], v[224:227], v[24:27]
	v_mfma_f32_16x16x32_bf16 v[16:19], v[164:167], v[224:227], v[16:19]
	v_mfma_f32_16x16x32_bf16 v[64:67], v[160:163], v[204:207], v[64:67]
	v_mfma_f32_16x16x32_bf16 v[60:63], v[168:171], v[204:207], v[60:63]
	v_mfma_f32_16x16x32_bf16 v[56:59], v[160:163], v[212:215], v[56:59]
	v_mfma_f32_16x16x32_bf16 v[48:51], v[168:171], v[212:215], v[48:51]
	v_mfma_f32_16x16x32_bf16 v[40:43], v[160:163], v[220:223], v[40:43]
	v_mfma_f32_16x16x32_bf16 v[32:35], v[168:171], v[220:223], v[32:35]
	v_mfma_f32_16x16x32_bf16 v[24:27], v[160:163], v[228:231], v[24:27]
	v_mfma_f32_16x16x32_bf16 v[16:19], v[168:171], v[228:231], v[16:19]
	s_nop 0
	s_nop 0
	v_mfma_f32_16x16x32_bf16 v[52:55], v[172:175], v[200:203], v[52:55]
	v_mfma_f32_16x16x32_bf16 v[44:47], v[192:195], v[200:203], v[44:47]
	v_mfma_f32_16x16x32_bf16 v[36:39], v[172:175], v[208:211], v[36:39]
	v_mfma_f32_16x16x32_bf16 v[28:31], v[192:195], v[208:211], v[28:31]
	v_mfma_f32_16x16x32_bf16 v[20:23], v[172:175], v[216:219], v[20:23]
	v_mfma_f32_16x16x32_bf16 v[12:15], v[192:195], v[216:219], v[12:15]
	v_mfma_f32_16x16x32_bf16 v[4:7], v[172:175], v[224:227], v[4:7]
	v_mfma_f32_16x16x32_bf16 v[0:3], v[192:195], v[224:227], v[0:3]
	v_mfma_f32_16x16x32_bf16 v[52:55], v[188:191], v[204:207], v[52:55]
	v_mfma_f32_16x16x32_bf16 v[44:47], v[196:199], v[204:207], v[44:47]
	v_mfma_f32_16x16x32_bf16 v[36:39], v[188:191], v[212:215], v[36:39]
	v_mfma_f32_16x16x32_bf16 v[28:31], v[196:199], v[212:215], v[28:31]
	v_mfma_f32_16x16x32_bf16 v[20:23], v[188:191], v[220:223], v[20:23]
	v_mfma_f32_16x16x32_bf16 v[12:15], v[196:199], v[220:223], v[12:15]
	v_mfma_f32_16x16x32_bf16 v[4:7], v[188:191], v[228:231], v[4:7]
	v_mfma_f32_16x16x32_bf16 v[0:3], v[196:199], v[228:231], v[0:3]
	s_nop 0
	s_barrier
	s_add_i32 s62, s62, 2
	s_add_u32 s60, s60, 0x100
	s_addc_u32 s61, s61, 0
	s_add_u32 s20, s20, 0x100
	s_addc_u32 s21, s21, 0
	s_cmp_gt_u32 s62, 13
	s_cbranch_scc0 .LBB0_252
	s_setprio 0
	s_and_b64 vcc, exec, s[10:11]
	s_cbranch_vccz .LBB0_255
	s_barrier

; #define PG8_WAIT_V(n) asm volatile("s_waitcnt vmcnt(" #n ")" ::: "memory")
; template <class Epi, class Sched, bool ALIGN_EPI = GEMM_ALIGN, bool SP2 = GEMM_SP2>
; __device__ __forceinline__ void gemm_phase(PG8_LAS unsigned char* lds, const Gemm g, const Sched& S, const Epi& E, unsigned long long*  , int tid_in) {
;     ...
;     f32x4 acc[2][2][4][2];
; #pragma unroll
;     for (int a = 0; a < 2; ++a)
; #pragma unroll
;         for (int b = 0; b < 2; ++b)
; #pragma unroll
;             for (int m = 0; m < 4; ++m)
; #pragma unroll
;                 for (int n = 0; n < 2; ++n) acc[a][b][m][n] = (f32x4){0.f, 0.f, 0.f, 0.f};
;     bf16x8 At[4][2], B0[2][2], B1[2][2];
;     const char* cA = (const char*)g.A + (size_t)cur.pm * tstep; const char* cB = (const char*)g.Bt + (size_t)cur.pn * tstep;
;     S.a_ready(cur);
;     if constexpr (SP2) {
;         PG8_STAGE(PG8_SB(0, 0), cB, voffB); PG8_STAGE(PG8_SB(0, 1), cB + hstep, voffB); PG8_STAGE(PG8_SA(0, 0), cA, voffA); PG8_STAGE(PG8_SA(0, 1), cA + hstep, voffA);
;         if (wr == 1) PG8_BAR;
;         PG8_WAIT_V(2); PG8_BAR;
;         PG8_STAGE(PG8_SB(1, 0), cB + kstep, voffB); PG8_STAGE(PG8_SA(1, 0), cA + kstep, voffA); PG8_STAGE(PG8_SB(1, 1), cB + hstep + kstep, voffB);
;         PG8_WAIT_V(6); PG8_BAR;
;     } else {
;         PG8_STAGE(PG8_SB(0, 0), cB, voffB); PG8_STAGE(PG8_SA(0, 0), cA, voffA); PG8_STAGE(PG8_SB(0, 1), cB + hstep, voffB); PG8_STAGE(PG8_SA(0, 1), cA + hstep, voffA);
;         if (wr == 1) PG8_BAR;
;         PG8_WAIT_V(4); PG8_BAR;
;         PG8_STAGE(PG8_SB(1, 0), cB + kstep, voffB); PG8_STAGE(PG8_SA(1, 0), cA + kstep, voffA); PG8_STAGE(PG8_SB(1, 1), cB + hstep + kstep, voffB);
;         PG8_WAIT_V(6); PG8_BAR;
;     }
;     for (;;) {
;         const bool has_next = S.next(ui + 1, nxt);
;         const char* nA = has_next ? (const char*)g.A + (size_t)nxt.pm * tstep : cA; const char* nB = has_next ? (const char*)g.Bt + (size_t)nxt.pn * tstep : cB;
;         for (int t = 0; t < nt; t += 2) {
;             const bool last = (t == nt - 2);
;             const char* a1 = cA + (size_t)(t + 1) * kstep;
;             const char* a2 = last ? nA : cA + (size_t)(t + 2) * kstep; const char* b2 = last ? nB : cB + (size_t)(t + 2) * kstep;
;             const char* a3 = a2 + kstep; const char* b3 = b2 + kstep;
;             if (last && has_next) S.a_ready(nxt);
;             if constexpr (SP2) {
.LBB0_976:
	s_ashr_i32 s19, s18, 31
	s_lshl_b64 s[20:21], s[18:19], 19
	s_add_u32 s20, s30, s20
	s_addc_u32 s21, s31, s21
	s_and_b64 s[22:23], s[4:5], exec
	s_cselect_b32 s19, s21, s27
	s_cselect_b32 s62, s20, s26
	s_ashr_i32 s17, s16, 31
	s_lshl_b64 s[22:23], s[16:17], 19
	s_add_u32 s22, s2, s22
	s_addc_u32 s23, s3, s23
	s_and_b64 s[28:29], s[4:5], exec
	s_cselect_b32 s17, s23, s25
	s_cselect_b32 s63, s22, s24
	s_add_u32 s64, s24, 0x100
	s_addc_u32 s66, s25, 0
	s_add_u32 s24, s26, 0x40080
	v_mov_b32_e32 v0, 0
	s_addc_u32 s25, s27, 0
	s_mov_b32 s67, -2
	v_mov_b32_e32 v1, v0
	v_mov_b32_e32 v2, v0
	v_mov_b32_e32 v3, v0
	v_mov_b32_e32 v4, v0
	v_mov_b32_e32 v5, v0
	v_mov_b32_e32 v6, v0
	v_mov_b32_e32 v7, v0
	v_mov_b32_e32 v20, v0
	v_mov_b32_e32 v21, v0
	v_mov_b32_e32 v22, v0
	v_mov_b32_e32 v23, v0
	v_mov_b32_e32 v24, v0
	v_mov_b32_e32 v25, v0
	v_mov_b32_e32 v26, v0
	v_mov_b32_e32 v27, v0
	v_mov_b32_e32 v36, v0
	v_mov_b32_e32 v37, v0
	v_mov_b32_e32 v38, v0
	v_mov_b32_e32 v39, v0
	v_mov_b32_e32 v40, v0
	v_mov_b32_e32 v41, v0
	v_mov_b32_e32 v42, v0
	v_mov_b32_e32 v43, v0
	v_mov_b32_e32 v52, v0
	v_mov_b32_e32 v53, v0
	v_mov_b32_e32 v54, v0
	v_mov_b32_e32 v55, v0
	v_mov_b32_e32 v56, v0
	v_mov_b32_e32 v57, v0
	v_mov_b32_e32 v58, v0
	v_mov_b32_e32 v59, v0
	v_mov_b32_e32 v12, v0
	v_mov_b32_e32 v13, v0
	v_mov_b32_e32 v14, v0
	v_mov_b32_e32 v15, v0
	v_mov_b32_e32 v16, v0
	v_mov_b32_e32 v17, v0
	v_mov_b32_e32 v18, v0
	v_mov_b32_e32 v19, v0
	v_mov_b32_e32 v28, v0
	v_mov_b32_e32 v29, v0
	v_mov_b32_e32 v30, v0
	v_mov_b32_e32 v31, v0
	v_mov_b32_e32 v32, v0
	v_mov_b32_e32 v33, v0
	v_mov_b32_e32 v34, v0
	v_mov_b32_e32 v35, v0
	v_mov_b32_e32 v44, v0
	v_mov_b32_e32 v45, v0
	v_mov_b32_e32 v46, v0
	v_mov_b32_e32 v47, v0
	v_mov_b32_e32 v48, v0
	v_mov_b32_e32 v49, v0
	v_mov_b32_e32 v50, v0
	v_mov_b32_e32 v51, v0
	v_mov_b32_e32 v68, v0
	v_mov_b32_e32 v69, v0
	v_mov_b32_e32 v70, v0
	v_mov_b32_e32 v71, v0
	v_mov_b32_e32 v72, v0
	v_mov_b32_e32 v73, v0
	v_mov_b32_e32 v74, v0
	v_mov_b32_e32 v75, v0
	v_mov_b32_e32 v80, v0
	v_mov_b32_e32 v81, v0
	v_mov_b32_e32 v82, v0
	v_mov_b32_e32 v83, v0
	v_mov_b32_e32 v88, v0
	v_mov_b32_e32 v89, v0
	v_mov_b32_e32 v90, v0
	v_mov_b32_e32 v91, v0
	v_mov_b32_e32 v100, v0
	v_mov_b32_e32 v101, v0
	v_mov_b32_e32 v102, v0
	v_mov_b32_e32 v103, v0
	v_mov_b32_e32 v104, v0
	v_mov_b32_e32 v105, v0
	v_mov_b32_e32 v106, v0
	v_mov_b32_e32 v107, v0
	v_mov_b32_e32 v116, v0
	v_mov_b32_e32 v117, v0
	v_mov_b32_e32 v118, v0
	v_mov_b32_e32 v119, v0
	v_mov_b32_e32 v120, v0
	v_mov_b32_e32 v121, v0
	v_mov_b32_e32 v122, v0
	v_mov_b32_e32 v123, v0
	v_mov_b32_e32 v132, v0
	v_mov_b32_e32 v133, v0
	v_mov_b32_e32 v134, v0
	v_mov_b32_e32 v135, v0
	v_mov_b32_e32 v136, v0
	v_mov_b32_e32 v137, v0
	v_mov_b32_e32 v138, v0
	v_mov_b32_e32 v139, v0
	v_mov_b32_e32 v92, v0
	v_mov_b32_e32 v93, v0
	v_mov_b32_e32 v94, v0
	v_mov_b32_e32 v95, v0
	v_mov_b32_e32 v96, v0
	v_mov_b32_e32 v97, v0
	v_mov_b32_e32 v98, v0
	v_mov_b32_e32 v99, v0
	v_mov_b32_e32 v108, v0
	v_mov_b32_e32 v109, v0
	v_mov_b32_e32 v110, v0
	v_mov_b32_e32 v111, v0
	v_mov_b32_e32 v112, v0
	v_mov_b32_e32 v113, v0
	v_mov_b32_e32 v114, v0
	v_mov_b32_e32 v115, v0
	v_mov_b32_e32 v124, v0
	v_mov_b32_e32 v125, v0
	v_mov_b32_e32 v126, v0
	v_mov_b32_e32 v127, v0
	v_mov_b32_e32 v128, v0
	v_mov_b32_e32 v129, v0
	v_mov_b32_e32 v130, v0
	v_mov_b32_e32 v131, v0
	v_mov_b32_e32 v140, v0
	v_mov_b32_e32 v141, v0
	v_mov_b32_e32 v142, v0
	v_mov_b32_e32 v143, v0
	v_mov_b32_e32 v144, v0
	v_mov_b32_e32 v145, v0
	v_mov_b32_e32 v146, v0
	v_mov_b32_e32 v147, v0
	s_and_b64 vcc, exec, s[14:15]
	s_cbranch_vccnz .Lprio_977
	s_setprio 1
.Lprio_977:
.LBB0_977:
	s_add_u32 s26, s24, 0xfffc0080
	s_addc_u32 s27, s25, -1
	s_add_i32 s68, 0, 0x10000
	s_cmp_eq_u32 s67, 12
	s_cselect_b32 s29, s19, s27
	s_cselect_b32 s28, s62, s26
	s_cselect_b32 s27, s17, s66
	s_cselect_b32 s26, s63, s64
	s_add_i32 s70, 0, 0x14000
	v_add_u32_e32 v84, s68, v170
	v_add_u32_e32 v150, s70, v170
	ds_read_b128 v[60:63], v84
	ds_read_b128 v[64:67], v84 offset:1024
	ds_read_b128 v[76:79], v84 offset:2048
	ds_read_b128 v[84:87], v84 offset:3072
	ds_read_b128 v[164:167], v150
	ds_read_b128 v[188:191], v150 offset:1024
	ds_read_b128 v[192:195], v150 offset:2048
	ds_read_b128 v[196:199], v150 offset:3072
	v_lshl_add_u64 v[168:169], s[24:25], 0, v[162:163]
	s_add_i32 m0, s35, 0xc000
	ds_read_b128 v[200:203], v172
	ds_read_b128 v[204:207], v172 offset:1024
	ds_read_b128 v[208:211], v172 offset:2048
	ds_read_b128 v[212:215], v172 offset:3072
	ds_read_b128 v[216:219], v172 offset:4096
	ds_read_b128 v[220:223], v172 offset:5120
	ds_read_b128 v[224:227], v172 offset:6144
	ds_read_b128 v[228:231], v172 offset:7168
	global_load_lds_dwordx4 v[168:169], off
	v_lshl_add_u64 v[168:169], s[24:25], 0, v[160:161]
	s_add_i32 m0, s35, 0xe000
	s_nop 0
	global_load_lds_dwordx4 v[168:169], off
	s_waitcnt vmcnt(8)
	s_waitcnt lgkmcnt(0)
	s_barrier
; #define PG8_STAGE(bufoff, gbase, voff) do { _Pragma("unroll") for (int _i = 0; _i < 2; ++_i) \
;         __builtin_amdgcn_global_load_lds((const unsigned*)((const char*)(gbase) + (voff)[_i]), (PG8_LAS unsigned*)(lds + (bufoff) + ldsw + _i * 8192), 16, 0, 0); } while (0)
; #define PG8_LDA(dst, b, h) do { _Pragma("unroll") for (int m = 0; m < 4; ++m) _Pragma("unroll") for (int k = 0; k < 2; ++k) dst[m][k] = *(const PG8_LAS bf16x8*)(lds + PG8_SA(b, h) + aoff + m * 2048 + k * 1024); } while (0)
; #define PG8_MMA(ai, bj, At, Bt) do { __builtin_amdgcn_s_setprio(1); _Pragma("unroll") for (int m = 0; m < 4; ++m) _Pragma("unroll") for (int n = 0; n < 2; ++n) _Pragma("unroll") for (int k = 0; k < 2; ++k) \
;         acc[ai][bj][m][n] = __builtin_amdgcn_mfma_f32_16x16x32_bf16(Bt[n][k], At[m][k], acc[ai][bj][m][n], 0, 0, 0); __builtin_amdgcn_s_setprio(0); } while (0)
; #define PG8_WAIT_V(n) asm volatile("s_waitcnt vmcnt(" #n ")" ::: "memory")
; #define PG8_WAIT_L(n) asm volatile("s_waitcnt lgkmcnt(" #n ")" ::: "memory")
; #define PG8_BAR __builtin_amdgcn_s_barrier()
; #define PG8_SCHED __builtin_amdgcn_sched_barrier(0)
; template <class Epi, class Sched, bool ALIGN_EPI = GEMM_ALIGN, bool SP2 = GEMM_SP2>
; __device__ __forceinline__ void gemm_phase(PG8_LAS unsigned char* lds, const Gemm g, const Sched& S, const Epi& E, unsigned long long*  , int tid_in) {
;     ...
;             PG8_WAIT_V(8); PG8_WAIT_L(0); PG8_BAR; PG8_MMA(0, 0, At, B0); PG8_MMA(0, 1, At, B1); PG8_BAR; PG8_SCHED;
;             PG8_LDA(At, 0, 1); PG8_STAGE(PG8_SB(0, 0), b2, voffB); PG8_STAGE(PG8_SB(0, 1), b2 + hstep, voffB); PG8_STAGE(PG8_SA(0, 0), a2, voffA);
;             PG8_WAIT_V(8); PG8_WAIT_L(0); PG8_BAR; PG8_MMA(1, 0, At, B0); PG8_MMA(1, 1, At, B1); PG8_BAR; PG8_SCHED;
	s_nop 0
	s_waitcnt lgkmcnt(0)
	v_mfma_f32_16x16x32_bf16 v[144:147], v[60:63], v[200:203], v[144:147]
	v_mfma_f32_16x16x32_bf16 v[140:143], v[76:79], v[200:203], v[140:143]
	v_mfma_f32_16x16x32_bf16 v[128:131], v[60:63], v[208:211], v[128:131]
	v_mfma_f32_16x16x32_bf16 v[124:127], v[76:79], v[208:211], v[124:127]
	v_mfma_f32_16x16x32_bf16 v[112:115], v[60:63], v[216:219], v[112:115]
	v_mfma_f32_16x16x32_bf16 v[108:111], v[76:79], v[216:219], v[108:111]
	v_mfma_f32_16x16x32_bf16 v[96:99], v[60:63], v[224:227], v[96:99]
	v_mfma_f32_16x16x32_bf16 v[92:95], v[76:79], v[224:227], v[92:95]
	v_mfma_f32_16x16x32_bf16 v[144:147], v[64:67], v[204:207], v[144:147]
	v_mfma_f32_16x16x32_bf16 v[140:143], v[84:87], v[204:207], v[140:143]
	v_mfma_f32_16x16x32_bf16 v[128:131], v[64:67], v[212:215], v[128:131]
	v_mfma_f32_16x16x32_bf16 v[124:127], v[84:87], v[212:215], v[124:127]
	v_mfma_f32_16x16x32_bf16 v[112:115], v[64:67], v[220:223], v[112:115]
	v_mfma_f32_16x16x32_bf16 v[108:111], v[84:87], v[220:223], v[108:111]
	v_mfma_f32_16x16x32_bf16 v[96:99], v[64:67], v[228:231], v[96:99]
	v_mfma_f32_16x16x32_bf16 v[92:95], v[84:87], v[228:231], v[92:95]
	s_nop 0
	s_nop 0
	v_mfma_f32_16x16x32_bf16 v[136:139], v[164:167], v[200:203], v[136:139]
	v_mfma_f32_16x16x32_bf16 v[132:135], v[192:195], v[200:203], v[132:135]
	v_mfma_f32_16x16x32_bf16 v[120:123], v[164:167], v[208:211], v[120:123]
	v_mfma_f32_16x16x32_bf16 v[116:119], v[192:195], v[208:211], v[116:119]
	v_mfma_f32_16x16x32_bf16 v[104:107], v[164:167], v[216:219], v[104:107]
	v_mfma_f32_16x16x32_bf16 v[100:103], v[192:195], v[216:219], v[100:103]
	v_mfma_f32_16x16x32_bf16 v[88:91], v[164:167], v[224:227], v[88:91]
	v_mfma_f32_16x16x32_bf16 v[80:83], v[192:195], v[224:227], v[80:83]
	v_mfma_f32_16x16x32_bf16 v[136:139], v[188:191], v[204:207], v[136:139]
	v_mfma_f32_16x16x32_bf16 v[132:135], v[196:199], v[204:207], v[132:135]
	v_mfma_f32_16x16x32_bf16 v[120:123], v[188:191], v[212:215], v[120:123]
	v_mfma_f32_16x16x32_bf16 v[116:119], v[196:199], v[212:215], v[116:119]
	v_mfma_f32_16x16x32_bf16 v[104:107], v[188:191], v[220:223], v[104:107]
	v_mfma_f32_16x16x32_bf16 v[100:103], v[196:199], v[220:223], v[100:103]
	v_mfma_f32_16x16x32_bf16 v[88:91], v[188:191], v[228:231], v[88:91]
	v_mfma_f32_16x16x32_bf16 v[80:83], v[196:199], v[228:231], v[80:83]
	s_nop 0
	s_barrier
	s_add_i32 s68, s68, s34
	v_lshl_add_u64 v[168:169], s[26:27], 0, v[10:11]
	s_mov_b32 m0, s68
	ds_read_b128 v[200:203], v172 offset:16384
	ds_read_b128 v[204:207], v172 offset:17408
	ds_read_b128 v[208:211], v172 offset:18432
	ds_read_b128 v[212:215], v172 offset:19456
	ds_read_b128 v[216:219], v172 offset:20480
	ds_read_b128 v[220:223], v172 offset:21504
	ds_read_b128 v[224:227], v172 offset:22528
	ds_read_b128 v[228:231], v172 offset:23552
	global_load_lds_dwordx4 v[168:169], off
	s_add_i32 m0, s68, 0x2000
	s_add_u32 s68, s26, 0x40000
	v_lshl_add_u64 v[174:175], s[26:27], 0, v[8:9]
	s_addc_u32 s69, s27, 0
	s_add_i32 s70, s70, s34
	global_load_lds_dwordx4 v[174:175], off
	v_lshl_add_u64 v[232:233], s[68:69], 0, v[10:11]
	s_mov_b32 m0, s70
	v_lshl_add_u64 v[234:235], s[28:29], 0, v[156:157]
	global_load_lds_dwordx4 v[232:233], off
	v_lshl_add_u64 v[232:233], s[68:69], 0, v[8:9]
	s_add_i32 m0, s70, 0x2000
	s_nop 0
	global_load_lds_dwordx4 v[232:233], off
	v_lshl_add_u64 v[232:233], s[28:29], 0, v[158:159]
	s_mov_b32 m0, s35
	s_nop 0
	global_load_lds_dwordx4 v[232:233], off
	s_mov_b32 m0, s36
	s_nop 0
	global_load_lds_dwordx4 v[234:235], off
	s_waitcnt vmcnt(8)
	s_waitcnt lgkmcnt(0)
	s_barrier
	s_nop 0
	s_waitcnt lgkmcnt(0)
	v_mfma_f32_16x16x32_bf16 v[72:75], v[60:63], v[200:203], v[72:75]
	v_mfma_f32_16x16x32_bf16 v[68:71], v[76:79], v[200:203], v[68:71]
	v_mfma_f32_16x16x32_bf16 v[48:51], v[60:63], v[208:211], v[48:51]
	v_mfma_f32_16x16x32_bf16 v[44:47], v[76:79], v[208:211], v[44:47]
	v_mfma_f32_16x16x32_bf16 v[32:35], v[60:63], v[216:219], v[32:35]
	v_mfma_f32_16x16x32_bf16 v[28:31], v[76:79], v[216:219], v[28:31]
	v_mfma_f32_16x16x32_bf16 v[16:19], v[60:63], v[224:227], v[16:19]
	v_mfma_f32_16x16x32_bf16 v[12:15], v[76:79], v[224:227], v[12:15]
	v_mfma_f32_16x16x32_bf16 v[72:75], v[64:67], v[204:207], v[72:75]
	v_mfma_f32_16x16x32_bf16 v[68:71], v[84:87], v[204:207], v[68:71]
	v_mfma_f32_16x16x32_bf16 v[48:51], v[64:67], v[212:215], v[48:51]
	v_mfma_f32_16x16x32_bf16 v[44:47], v[84:87], v[212:215], v[44:47]
	v_mfma_f32_16x16x32_bf16 v[32:35], v[64:67], v[220:223], v[32:35]
	v_mfma_f32_16x16x32_bf16 v[28:31], v[84:87], v[220:223], v[28:31]
	v_mfma_f32_16x16x32_bf16 v[16:19], v[64:67], v[228:231], v[16:19]
	v_mfma_f32_16x16x32_bf16 v[12:15], v[84:87], v[228:231], v[12:15]
	s_nop 0
	s_nop 0
	v_mfma_f32_16x16x32_bf16 v[56:59], v[164:167], v[200:203], v[56:59]
	v_mfma_f32_16x16x32_bf16 v[52:55], v[192:195], v[200:203], v[52:55]
	v_mfma_f32_16x16x32_bf16 v[40:43], v[164:167], v[208:211], v[40:43]
	v_mfma_f32_16x16x32_bf16 v[36:39], v[192:195], v[208:211], v[36:39]
	v_mfma_f32_16x16x32_bf16 v[24:27], v[164:167], v[216:219], v[24:27]
	v_mfma_f32_16x16x32_bf16 v[20:23], v[192:195], v[216:219], v[20:23]
	v_mfma_f32_16x16x32_bf16 v[4:7], v[164:167], v[224:227], v[4:7]
	v_mfma_f32_16x16x32_bf16 v[0:3], v[192:195], v[224:227], v[0:3]
	v_mfma_f32_16x16x32_bf16 v[56:59], v[188:191], v[204:207], v[56:59]
	v_mfma_f32_16x16x32_bf16 v[52:55], v[196:199], v[204:207], v[52:55]
	v_mfma_f32_16x16x32_bf16 v[40:43], v[188:191], v[212:215], v[40:43]
	v_mfma_f32_16x16x32_bf16 v[36:39], v[196:199], v[212:215], v[36:39]
	v_mfma_f32_16x16x32_bf16 v[24:27], v[188:191], v[220:223], v[24:27]
	v_mfma_f32_16x16x32_bf16 v[20:23], v[196:199], v[220:223], v[20:23]
	v_mfma_f32_16x16x32_bf16 v[4:7], v[188:191], v[228:231], v[4:7]
	v_mfma_f32_16x16x32_bf16 v[0:3], v[196:199], v[228:231], v[0:3]
	s_nop 0
	s_barrier
; #define PG8_STAGE(bufoff, gbase, voff) do { _Pragma("unroll") for (int _i = 0; _i < 2; ++_i) \
;         __builtin_amdgcn_global_load_lds((const unsigned*)((const char*)(gbase) + (voff)[_i]), (PG8_LAS unsigned*)(lds + (bufoff) + ldsw + _i * 8192), 16, 0, 0); } while (0)
; #define PG8_LDA(dst, b, h) do { _Pragma("unroll") for (int m = 0; m < 4; ++m) _Pragma("unroll") for (int k = 0; k < 2; ++k) dst[m][k] = *(const PG8_LAS bf16x8*)(lds + PG8_SA(b, h) + aoff + m * 2048 + k * 1024); } while (0)
; #define PG8_LDB(dst, b, h) do { _Pragma("unroll") for (int n = 0; n < 2; ++n) _Pragma("unroll") for (int k = 0; k < 2; ++k) dst[n][k] = *(const PG8_LAS bf16x8*)(lds + PG8_SB(b, h) + boff + n * 2048 + k * 1024); } while (0)
; #define PG8_MMA(ai, bj, At, Bt) do { __builtin_amdgcn_s_setprio(1); _Pragma("unroll") for (int m = 0; m < 4; ++m) _Pragma("unroll") for (int n = 0; n < 2; ++n) _Pragma("unroll") for (int k = 0; k < 2; ++k) \
;         acc[ai][bj][m][n] = __builtin_amdgcn_mfma_f32_16x16x32_bf16(Bt[n][k], At[m][k], acc[ai][bj][m][n], 0, 0, 0); __builtin_amdgcn_s_setprio(0); } while (0)
; #define PG8_WAIT_V(n) asm volatile("s_waitcnt vmcnt(" #n ")" ::: "memory")
; #define PG8_WAIT_L(n) asm volatile("s_waitcnt lgkmcnt(" #n ")" ::: "memory")
; #define PG8_BAR __builtin_amdgcn_s_barrier()
; #define PG8_SCHED __builtin_amdgcn_sched_barrier(0)
; template <class Epi, class Sched, bool ALIGN_EPI = GEMM_ALIGN, bool SP2 = GEMM_SP2>
; __device__ __forceinline__ void gemm_phase(PG8_LAS unsigned char* lds, const Gemm g, const Sched& S, const Epi& E, unsigned long long*  , int tid_in) {
;     ...
;             PG8_LDB(B0, 1, 0); PG8_LDB(B1, 1, 1); PG8_SCHED; PG8_LDA(At, 1, 0); PG8_STAGE(PG8_SA(0, 1), a2 + hstep, voffA);
;             PG8_WAIT_V(8); PG8_WAIT_L(0); PG8_BAR; PG8_MMA(0, 0, At, B0); PG8_MMA(0, 1, At, B1); PG8_BAR; PG8_SCHED;
	s_add_i32 s68, 0, 0x18000
	s_add_i32 s69, 0, 0x1c000
	v_add_u32_e32 v84, s68, v170
	v_add_u32_e32 v150, s69, v170
	ds_read_b128 v[60:63], v84
	ds_read_b128 v[64:67], v84 offset:1024
	ds_read_b128 v[76:79], v84 offset:2048
	ds_read_b128 v[84:87], v84 offset:3072
	ds_read_b128 v[164:167], v150
	ds_read_b128 v[188:191], v150 offset:1024
	ds_read_b128 v[192:195], v150 offset:2048
	ds_read_b128 v[196:199], v150 offset:3072
	s_add_u32 s28, s28, 0x40000
	s_addc_u32 s29, s29, 0
	s_mov_b32 m0, s37
	v_lshl_add_u64 v[236:237], s[28:29], 0, v[158:159]
	ds_read_b128 v[200:203], v172 offset:32768
	ds_read_b128 v[204:207], v172 offset:33792
	ds_read_b128 v[208:211], v172 offset:34816
	ds_read_b128 v[212:215], v172 offset:35840
	ds_read_b128 v[216:219], v172 offset:36864
	ds_read_b128 v[220:223], v172 offset:37888
	ds_read_b128 v[224:227], v172 offset:38912
	ds_read_b128 v[228:231], v172 offset:39936
	global_load_lds_dwordx4 v[236:237], off
	v_lshl_add_u64 v[236:237], s[28:29], 0, v[156:157]
	s_mov_b32 m0, s50
	s_nop 0
	global_load_lds_dwordx4 v[236:237], off
	s_waitcnt vmcnt(8)
	s_waitcnt lgkmcnt(0)
	s_barrier
	s_nop 0
	s_waitcnt lgkmcnt(0)
	v_mfma_f32_16x16x32_bf16 v[144:147], v[60:63], v[200:203], v[144:147]
	v_mfma_f32_16x16x32_bf16 v[140:143], v[76:79], v[200:203], v[140:143]
	v_mfma_f32_16x16x32_bf16 v[128:131], v[60:63], v[208:211], v[128:131]
	v_mfma_f32_16x16x32_bf16 v[124:127], v[76:79], v[208:211], v[124:127]
	v_mfma_f32_16x16x32_bf16 v[112:115], v[60:63], v[216:219], v[112:115]
	v_mfma_f32_16x16x32_bf16 v[108:111], v[76:79], v[216:219], v[108:111]
	v_mfma_f32_16x16x32_bf16 v[96:99], v[60:63], v[224:227], v[96:99]
	v_mfma_f32_16x16x32_bf16 v[92:95], v[76:79], v[224:227], v[92:95]
	v_mfma_f32_16x16x32_bf16 v[144:147], v[64:67], v[204:207], v[144:147]
	v_mfma_f32_16x16x32_bf16 v[140:143], v[84:87], v[204:207], v[140:143]
	v_mfma_f32_16x16x32_bf16 v[128:131], v[64:67], v[212:215], v[128:131]
	v_mfma_f32_16x16x32_bf16 v[124:127], v[84:87], v[212:215], v[124:127]
	v_mfma_f32_16x16x32_bf16 v[112:115], v[64:67], v[220:223], v[112:115]
	v_mfma_f32_16x16x32_bf16 v[108:111], v[84:87], v[220:223], v[108:111]
	v_mfma_f32_16x16x32_bf16 v[96:99], v[64:67], v[228:231], v[96:99]
	v_mfma_f32_16x16x32_bf16 v[92:95], v[84:87], v[228:231], v[92:95]
	s_nop 0
	s_nop 0
	v_mfma_f32_16x16x32_bf16 v[136:139], v[164:167], v[200:203], v[136:139]
	v_mfma_f32_16x16x32_bf16 v[132:135], v[192:195], v[200:203], v[132:135]
	v_mfma_f32_16x16x32_bf16 v[120:123], v[164:167], v[208:211], v[120:123]
	v_mfma_f32_16x16x32_bf16 v[116:119], v[192:195], v[208:211], v[116:119]
	v_mfma_f32_16x16x32_bf16 v[104:107], v[164:167], v[216:219], v[104:107]
	v_mfma_f32_16x16x32_bf16 v[100:103], v[192:195], v[216:219], v[100:103]
	v_mfma_f32_16x16x32_bf16 v[88:91], v[164:167], v[224:227], v[88:91]
	v_mfma_f32_16x16x32_bf16 v[80:83], v[192:195], v[224:227], v[80:83]
	v_mfma_f32_16x16x32_bf16 v[136:139], v[188:191], v[204:207], v[136:139]
	v_mfma_f32_16x16x32_bf16 v[132:135], v[196:199], v[204:207], v[132:135]
	v_mfma_f32_16x16x32_bf16 v[120:123], v[188:191], v[212:215], v[120:123]
	v_mfma_f32_16x16x32_bf16 v[116:119], v[196:199], v[212:215], v[116:119]
	v_mfma_f32_16x16x32_bf16 v[104:107], v[188:191], v[220:223], v[104:107]
	v_mfma_f32_16x16x32_bf16 v[100:103], v[196:199], v[220:223], v[100:103]
	v_mfma_f32_16x16x32_bf16 v[88:91], v[188:191], v[228:231], v[88:91]
	v_mfma_f32_16x16x32_bf16 v[80:83], v[196:199], v[228:231], v[80:83]
	s_nop 0
	s_barrier
; #define PG8_STAGE(bufoff, gbase, voff) do { _Pragma("unroll") for (int _i = 0; _i < 2; ++_i) \
;         __builtin_amdgcn_global_load_lds((const unsigned*)((const char*)(gbase) + (voff)[_i]), (PG8_LAS unsigned*)(lds + (bufoff) + ldsw + _i * 8192), 16, 0, 0); } while (0)
; #define PG8_LDA(dst, b, h) do { _Pragma("unroll") for (int m = 0; m < 4; ++m) _Pragma("unroll") for (int k = 0; k < 2; ++k) dst[m][k] = *(const PG8_LAS bf16x8*)(lds + PG8_SA(b, h) + aoff + m * 2048 + k * 1024); } while (0)
; #define PG8_MMA(ai, bj, At, Bt) do { __builtin_amdgcn_s_setprio(1); _Pragma("unroll") for (int m = 0; m < 4; ++m) _Pragma("unroll") for (int n = 0; n < 2; ++n) _Pragma("unroll") for (int k = 0; k < 2; ++k) \
;         acc[ai][bj][m][n] = __builtin_amdgcn_mfma_f32_16x16x32_bf16(Bt[n][k], At[m][k], acc[ai][bj][m][n], 0, 0, 0); __builtin_amdgcn_s_setprio(0); } while (0)
; #define PG8_WAIT_V(n) asm volatile("s_waitcnt vmcnt(" #n ")" ::: "memory")
; #define PG8_WAIT_L(n) asm volatile("s_waitcnt lgkmcnt(" #n ")" ::: "memory")
; #define PG8_BAR __builtin_amdgcn_s_barrier()
; #define PG8_SCHED __builtin_amdgcn_sched_barrier(0)
; template <class Epi, class Sched, bool ALIGN_EPI = GEMM_ALIGN, bool SP2 = GEMM_SP2>
; __device__ __forceinline__ void gemm_phase(PG8_LAS unsigned char* lds, const Gemm g, const Sched& S, const Epi& E, unsigned long long*  , int tid_in) {
;     ...
;         for (int t = 0; t < nt; t += 2) {
;             const bool last = (t == nt - 2);
;             const char* a1 = cA + (size_t)(t + 1) * kstep;
;             const char* a2 = last ? nA : cA + (size_t)(t + 2) * kstep; const char* b2 = last ? nB : cB + (size_t)(t + 2) * kstep;
;             const char* a3 = a2 + kstep; const char* b3 = b2 + kstep;
;             if (last && has_next) S.a_ready(nxt);
;     ...
;             PG8_LDA(At, 1, 1); PG8_STAGE(PG8_SB(1, 0), b3, voffB); PG8_STAGE(PG8_SB(1, 1), b3 + hstep, voffB); PG8_STAGE(PG8_SA(1, 0), a3, voffA);
;             PG8_WAIT_V(8); PG8_WAIT_L(0); PG8_BAR; PG8_MMA(1, 0, At, B0); PG8_MMA(1, 1, At, B1); PG8_BAR; PG8_SCHED;
	s_add_i32 s28, s68, s34
	v_lshl_add_u64 v[168:169], v[168:169], 0, s[82:83]
	s_mov_b32 m0, s28
	ds_read_b128 v[200:203], v172 offset:49152
	ds_read_b128 v[204:207], v172 offset:50176
	ds_read_b128 v[208:211], v172 offset:51200
	ds_read_b128 v[212:215], v172 offset:52224
	ds_read_b128 v[216:219], v172 offset:53248
	ds_read_b128 v[220:223], v172 offset:54272
	ds_read_b128 v[224:227], v172 offset:55296
	ds_read_b128 v[228:231], v172 offset:56320
	global_load_lds_dwordx4 v[168:169], off
	s_add_i32 m0, s28, 0x2000
	s_add_u32 s26, s26, 0x40080
	v_lshl_add_u64 v[168:169], v[174:175], 0, s[82:83]
	s_addc_u32 s27, s27, 0
	s_add_i32 s28, s69, s34
	global_load_lds_dwordx4 v[168:169], off
	v_lshl_add_u64 v[168:169], s[26:27], 0, v[10:11]
	s_mov_b32 m0, s28
	s_nop 0
	global_load_lds_dwordx4 v[168:169], off
	v_lshl_add_u64 v[168:169], s[26:27], 0, v[8:9]
	s_add_i32 m0, s28, 0x2000
	s_nop 0
	global_load_lds_dwordx4 v[168:169], off
	v_lshl_add_u64 v[168:169], v[232:233], 0, s[82:83]
	s_mov_b32 m0, s51
	s_nop 0
	global_load_lds_dwordx4 v[168:169], off
	v_lshl_add_u64 v[168:169], v[234:235], 0, s[82:83]
	s_mov_b32 m0, s58
	s_nop 0
	global_load_lds_dwordx4 v[168:169], off
	s_waitcnt vmcnt(8)
	s_waitcnt lgkmcnt(0)
	s_barrier
	s_nop 0
	s_waitcnt lgkmcnt(0)
	v_mfma_f32_16x16x32_bf16 v[72:75], v[60:63], v[200:203], v[72:75]
	v_mfma_f32_16x16x32_bf16 v[68:71], v[76:79], v[200:203], v[68:71]
	v_mfma_f32_16x16x32_bf16 v[48:51], v[60:63], v[208:211], v[48:51]
	v_mfma_f32_16x16x32_bf16 v[44:47], v[76:79], v[208:211], v[44:47]
	v_mfma_f32_16x16x32_bf16 v[32:35], v[60:63], v[216:219], v[32:35]
	v_mfma_f32_16x16x32_bf16 v[28:31], v[76:79], v[216:219], v[28:31]
	v_mfma_f32_16x16x32_bf16 v[16:19], v[60:63], v[224:227], v[16:19]
	v_mfma_f32_16x16x32_bf16 v[12:15], v[76:79], v[224:227], v[12:15]
	v_mfma_f32_16x16x32_bf16 v[72:75], v[64:67], v[204:207], v[72:75]
	v_mfma_f32_16x16x32_bf16 v[68:71], v[84:87], v[204:207], v[68:71]
	v_mfma_f32_16x16x32_bf16 v[48:51], v[64:67], v[212:215], v[48:51]
	v_mfma_f32_16x16x32_bf16 v[44:47], v[84:87], v[212:215], v[44:47]
	v_mfma_f32_16x16x32_bf16 v[32:35], v[64:67], v[220:223], v[32:35]
	v_mfma_f32_16x16x32_bf16 v[28:31], v[84:87], v[220:223], v[28:31]
	v_mfma_f32_16x16x32_bf16 v[16:19], v[64:67], v[228:231], v[16:19]
	v_mfma_f32_16x16x32_bf16 v[12:15], v[84:87], v[228:231], v[12:15]
	s_nop 0
	s_nop 0
	v_mfma_f32_16x16x32_bf16 v[56:59], v[164:167], v[200:203], v[56:59]
	v_mfma_f32_16x16x32_bf16 v[52:55], v[192:195], v[200:203], v[52:55]
	v_mfma_f32_16x16x32_bf16 v[40:43], v[164:167], v[208:211], v[40:43]
	v_mfma_f32_16x16x32_bf16 v[36:39], v[192:195], v[208:211], v[36:39]
	v_mfma_f32_16x16x32_bf16 v[24:27], v[164:167], v[216:219], v[24:27]
	v_mfma_f32_16x16x32_bf16 v[20:23], v[192:195], v[216:219], v[20:23]
	v_mfma_f32_16x16x32_bf16 v[4:7], v[164:167], v[224:227], v[4:7]
	v_mfma_f32_16x16x32_bf16 v[0:3], v[192:195], v[224:227], v[0:3]
	v_mfma_f32_16x16x32_bf16 v[56:59], v[188:191], v[204:207], v[56:59]
	v_mfma_f32_16x16x32_bf16 v[52:55], v[196:199], v[204:207], v[52:55]
	v_mfma_f32_16x16x32_bf16 v[40:43], v[188:191], v[212:215], v[40:43]
	v_mfma_f32_16x16x32_bf16 v[36:39], v[196:199], v[212:215], v[36:39]
	v_mfma_f32_16x16x32_bf16 v[24:27], v[188:191], v[220:223], v[24:27]
	v_mfma_f32_16x16x32_bf16 v[20:23], v[196:199], v[220:223], v[20:23]
	v_mfma_f32_16x16x32_bf16 v[4:7], v[188:191], v[228:231], v[4:7]
	v_mfma_f32_16x16x32_bf16 v[0:3], v[196:199], v[228:231], v[0:3]
	s_nop 0
	s_barrier
	s_add_i32 s67, s67, 2
	s_add_u32 s64, s64, 0x100
	s_addc_u32 s66, s66, 0
	s_add_u32 s24, s24, 0x100
	s_addc_u32 s25, s25, 0
	s_cmp_gt_u32 s67, 13
	s_cbranch_scc0 .LBB0_977
	s_setprio 0
	s_and_b64 vcc, exec, s[14:15]
	s_cbranch_vccz .LBB0_980
	s_barrier

; #define PG8_WAIT_V(n) asm volatile("s_waitcnt vmcnt(" #n ")" ::: "memory")
; template <class Epi, class Sched, bool ALIGN_EPI = GEMM_ALIGN, bool SP2 = GEMM_SP2>
; __device__ __forceinline__ void gemm_phase(PG8_LAS unsigned char* lds, const Gemm g, const Sched& S, const Epi& E, unsigned long long*  , int tid_in) {
;     ...
;     f32x4 acc[2][2][4][2];
; #pragma unroll
;     for (int a = 0; a < 2; ++a)
; #pragma unroll
;         for (int b = 0; b < 2; ++b)
; #pragma unroll
;             for (int m = 0; m < 4; ++m)
; #pragma unroll
;                 for (int n = 0; n < 2; ++n) acc[a][b][m][n] = (f32x4){0.f, 0.f, 0.f, 0.f};
;     bf16x8 At[4][2], B0[2][2], B1[2][2];
;     const char* cA = (const char*)g.A + (size_t)cur.pm * tstep; const char* cB = (const char*)g.Bt + (size_t)cur.pn * tstep;
;     S.a_ready(cur);
;     if constexpr (SP2) {
;         PG8_STAGE(PG8_SB(0, 0), cB, voffB); PG8_STAGE(PG8_SB(0, 1), cB + hstep, voffB); PG8_STAGE(PG8_SA(0, 0), cA, voffA); PG8_STAGE(PG8_SA(0, 1), cA + hstep, voffA);
;         if (wr == 1) PG8_BAR;
;         PG8_WAIT_V(2); PG8_BAR;
;         PG8_STAGE(PG8_SB(1, 0), cB + kstep, voffB); PG8_STAGE(PG8_SA(1, 0), cA + kstep, voffA); PG8_STAGE(PG8_SB(1, 1), cB + hstep + kstep, voffB);
;         PG8_WAIT_V(6); PG8_BAR;
;     } else {
;         PG8_STAGE(PG8_SB(0, 0), cB, voffB); PG8_STAGE(PG8_SA(0, 0), cA, voffA); PG8_STAGE(PG8_SB(0, 1), cB + hstep, voffB); PG8_STAGE(PG8_SA(0, 1), cA + hstep, voffA);
;         if (wr == 1) PG8_BAR;
;         PG8_WAIT_V(4); PG8_BAR;
;         PG8_STAGE(PG8_SB(1, 0), cB + kstep, voffB); PG8_STAGE(PG8_SA(1, 0), cA + kstep, voffA); PG8_STAGE(PG8_SB(1, 1), cB + hstep + kstep, voffB);
;         PG8_WAIT_V(6); PG8_BAR;
;     }
;     for (;;) {
;         const bool has_next = S.next(ui + 1, nxt);
;         const char* nA = has_next ? (const char*)g.A + (size_t)nxt.pm * tstep : cA; const char* nB = has_next ? (const char*)g.Bt + (size_t)nxt.pn * tstep : cB;
;         for (int t = 0; t < nt; t += 2) {
;             const bool last = (t == nt - 2);
;             const char* a1 = cA + (size_t)(t + 1) * kstep;
;             const char* a2 = last ? nA : cA + (size_t)(t + 2) * kstep; const char* b2 = last ? nB : cB + (size_t)(t + 2) * kstep;
;             const char* a3 = a2 + kstep; const char* b3 = b2 + kstep;
;             if (last && has_next) S.a_ready(nxt);
;             if constexpr (SP2) {
.LBB0_1001:
	s_ashr_i32 s23, s22, 31
	s_lshl_b64 s[24:25], s[22:23], 20
	s_add_u32 s24, s34, s24
	s_addc_u32 s25, s35, s25
	s_and_b64 s[26:27], s[6:7], exec
	s_cselect_b32 s23, s25, s29
	s_cselect_b32 s67, s24, s28
	s_ashr_i32 s21, s20, 31
	s_lshl_b64 s[26:27], s[20:21], 20
	s_add_u32 s26, s36, s26
	s_addc_u32 s27, s37, s27
	s_and_b64 s[30:31], s[6:7], exec
	s_cselect_b32 s21, s27, s3
	s_cselect_b32 s68, s26, s2
	s_add_u32 s69, s2, 0x100
	s_addc_u32 s70, s3, 0
	s_add_u32 s2, s28, 0x80080
	v_mov_b32_e32 v0, 0
	s_addc_u32 s3, s29, 0
	s_mov_b32 s71, -2
	v_mov_b32_e32 v1, v0
	v_mov_b32_e32 v2, v0
	v_mov_b32_e32 v3, v0
	v_mov_b32_e32 v4, v0
	v_mov_b32_e32 v5, v0
	v_mov_b32_e32 v6, v0
	v_mov_b32_e32 v7, v0
	v_mov_b32_e32 v32, v0
	v_mov_b32_e32 v33, v0
	v_mov_b32_e32 v34, v0
	v_mov_b32_e32 v35, v0
	v_mov_b32_e32 v40, v0
	v_mov_b32_e32 v41, v0
	v_mov_b32_e32 v42, v0
	v_mov_b32_e32 v43, v0
	v_mov_b32_e32 v52, v0
	v_mov_b32_e32 v53, v0
	v_mov_b32_e32 v54, v0
	v_mov_b32_e32 v55, v0
	v_mov_b32_e32 v56, v0
	v_mov_b32_e32 v57, v0
	v_mov_b32_e32 v58, v0
	v_mov_b32_e32 v59, v0
	v_mov_b32_e32 v68, v0
	v_mov_b32_e32 v69, v0
	v_mov_b32_e32 v70, v0
	v_mov_b32_e32 v71, v0
	v_mov_b32_e32 v72, v0
	v_mov_b32_e32 v73, v0
	v_mov_b32_e32 v74, v0
	v_mov_b32_e32 v75, v0
	v_mov_b32_e32 v12, v0
	v_mov_b32_e32 v13, v0
	v_mov_b32_e32 v14, v0
	v_mov_b32_e32 v15, v0
	v_mov_b32_e32 v16, v0
	v_mov_b32_e32 v17, v0
	v_mov_b32_e32 v18, v0
	v_mov_b32_e32 v19, v0
	v_mov_b32_e32 v44, v0
	v_mov_b32_e32 v45, v0
	v_mov_b32_e32 v46, v0
	v_mov_b32_e32 v47, v0
	v_mov_b32_e32 v48, v0
	v_mov_b32_e32 v49, v0
	v_mov_b32_e32 v50, v0
	v_mov_b32_e32 v51, v0
	v_mov_b32_e32 v60, v0
	v_mov_b32_e32 v61, v0
	v_mov_b32_e32 v62, v0
	v_mov_b32_e32 v63, v0
	v_mov_b32_e32 v64, v0
	v_mov_b32_e32 v65, v0
	v_mov_b32_e32 v66, v0
	v_mov_b32_e32 v67, v0
	v_mov_b32_e32 v76, v0
	v_mov_b32_e32 v77, v0
	v_mov_b32_e32 v78, v0
	v_mov_b32_e32 v79, v0
	v_mov_b32_e32 v80, v0
	v_mov_b32_e32 v81, v0
	v_mov_b32_e32 v82, v0
	v_mov_b32_e32 v83, v0
	v_mov_b32_e32 v84, v0
	v_mov_b32_e32 v85, v0
	v_mov_b32_e32 v86, v0
	v_mov_b32_e32 v87, v0
	v_mov_b32_e32 v88, v0
	v_mov_b32_e32 v89, v0
	v_mov_b32_e32 v90, v0
	v_mov_b32_e32 v91, v0
	v_mov_b32_e32 v100, v0
	v_mov_b32_e32 v101, v0
	v_mov_b32_e32 v102, v0
	v_mov_b32_e32 v103, v0
	v_mov_b32_e32 v104, v0
	v_mov_b32_e32 v105, v0
	v_mov_b32_e32 v106, v0
	v_mov_b32_e32 v107, v0
	v_mov_b32_e32 v116, v0
	v_mov_b32_e32 v117, v0
	v_mov_b32_e32 v118, v0
	v_mov_b32_e32 v119, v0
	v_mov_b32_e32 v120, v0
	v_mov_b32_e32 v121, v0
	v_mov_b32_e32 v122, v0
	v_mov_b32_e32 v123, v0
	v_mov_b32_e32 v132, v0
	v_mov_b32_e32 v133, v0
	v_mov_b32_e32 v134, v0
	v_mov_b32_e32 v135, v0
	v_mov_b32_e32 v136, v0
	v_mov_b32_e32 v137, v0
	v_mov_b32_e32 v138, v0
	v_mov_b32_e32 v139, v0
	v_mov_b32_e32 v92, v0
	v_mov_b32_e32 v93, v0
	v_mov_b32_e32 v94, v0
	v_mov_b32_e32 v95, v0
	v_mov_b32_e32 v96, v0
	v_mov_b32_e32 v97, v0
	v_mov_b32_e32 v98, v0
	v_mov_b32_e32 v99, v0
	v_mov_b32_e32 v108, v0
	v_mov_b32_e32 v109, v0
	v_mov_b32_e32 v110, v0
	v_mov_b32_e32 v111, v0
	v_mov_b32_e32 v112, v0
	v_mov_b32_e32 v113, v0
	v_mov_b32_e32 v114, v0
	v_mov_b32_e32 v115, v0
	v_mov_b32_e32 v124, v0
	v_mov_b32_e32 v125, v0
	v_mov_b32_e32 v126, v0
	v_mov_b32_e32 v127, v0
	v_mov_b32_e32 v128, v0
	v_mov_b32_e32 v129, v0
	v_mov_b32_e32 v130, v0
	v_mov_b32_e32 v131, v0
	v_mov_b32_e32 v140, v0
	v_mov_b32_e32 v141, v0
	v_mov_b32_e32 v142, v0
	v_mov_b32_e32 v143, v0
	v_mov_b32_e32 v144, v0
	v_mov_b32_e32 v145, v0
	v_mov_b32_e32 v146, v0
	v_mov_b32_e32 v147, v0
	s_and_b64 vcc, exec, s[18:19]
	s_cbranch_vccnz .Lprio_1002
	s_setprio 1
.Lprio_1002:
.LBB0_1002:
	s_add_u32 s28, s2, 0xfff80080
	s_addc_u32 s29, s3, -1
	s_add_i32 s72, 0, 0x10000
	s_cmp_eq_u32 s71, 28
	s_cselect_b32 s31, s23, s29
	s_cselect_b32 s30, s67, s28
	s_cselect_b32 s29, s21, s70
	s_cselect_b32 s28, s68, s69
	s_add_i32 s78, 0, 0x14000
	v_add_u32_e32 v36, s72, v188
	v_add_u32_e32 v150, s78, v188
	ds_read_b128 v[20:23], v36
	ds_read_b128 v[24:27], v36 offset:1024
	ds_read_b128 v[28:31], v36 offset:2048
	ds_read_b128 v[36:39], v36 offset:3072
	ds_read_b128 v[164:167], v150
	ds_read_b128 v[168:171], v150 offset:1024
	ds_read_b128 v[172:175], v150 offset:2048
	ds_read_b128 v[192:195], v150 offset:3072
	v_lshl_add_u64 v[228:229], s[2:3], 0, v[162:163]
	s_add_i32 m0, s51, 0xc000
	ds_read_b128 v[196:199], v190
	ds_read_b128 v[200:203], v190 offset:1024
	ds_read_b128 v[204:207], v190 offset:2048
	ds_read_b128 v[208:211], v190 offset:3072
	ds_read_b128 v[212:215], v190 offset:4096
	ds_read_b128 v[216:219], v190 offset:5120
	ds_read_b128 v[220:223], v190 offset:6144
	ds_read_b128 v[224:227], v190 offset:7168
	global_load_lds_dwordx4 v[228:229], off
	v_lshl_add_u64 v[228:229], s[2:3], 0, v[160:161]
	s_add_i32 m0, s51, 0xe000
	s_nop 0
	global_load_lds_dwordx4 v[228:229], off
	s_waitcnt vmcnt(8)
	s_waitcnt lgkmcnt(0)
	s_barrier
; #define PG8_STAGE(bufoff, gbase, voff) do { _Pragma("unroll") for (int _i = 0; _i < 2; ++_i) \
;         __builtin_amdgcn_global_load_lds((const unsigned*)((const char*)(gbase) + (voff)[_i]), (PG8_LAS unsigned*)(lds + (bufoff) + ldsw + _i * 8192), 16, 0, 0); } while (0)
; #define PG8_LDA(dst, b, h) do { _Pragma("unroll") for (int m = 0; m < 4; ++m) _Pragma("unroll") for (int k = 0; k < 2; ++k) dst[m][k] = *(const PG8_LAS bf16x8*)(lds + PG8_SA(b, h) + aoff + m * 2048 + k * 1024); } while (0)
; #define PG8_MMA(ai, bj, At, Bt) do { __builtin_amdgcn_s_setprio(1); _Pragma("unroll") for (int m = 0; m < 4; ++m) _Pragma("unroll") for (int n = 0; n < 2; ++n) _Pragma("unroll") for (int k = 0; k < 2; ++k) \
;         acc[ai][bj][m][n] = __builtin_amdgcn_mfma_f32_16x16x32_bf16(Bt[n][k], At[m][k], acc[ai][bj][m][n], 0, 0, 0); __builtin_amdgcn_s_setprio(0); } while (0)
; #define PG8_WAIT_V(n) asm volatile("s_waitcnt vmcnt(" #n ")" ::: "memory")
; #define PG8_WAIT_L(n) asm volatile("s_waitcnt lgkmcnt(" #n ")" ::: "memory")
; #define PG8_BAR __builtin_amdgcn_s_barrier()
; #define PG8_SCHED __builtin_amdgcn_sched_barrier(0)
; template <class Epi, class Sched, bool ALIGN_EPI = GEMM_ALIGN, bool SP2 = GEMM_SP2>
; __device__ __forceinline__ void gemm_phase(PG8_LAS unsigned char* lds, const Gemm g, const Sched& S, const Epi& E, unsigned long long*  , int tid_in) {
;     ...
;             PG8_WAIT_V(8); PG8_WAIT_L(0); PG8_BAR; PG8_MMA(0, 0, At, B0); PG8_MMA(0, 1, At, B1); PG8_BAR; PG8_SCHED;
;             PG8_LDA(At, 0, 1); PG8_STAGE(PG8_SB(0, 0), b2, voffB); PG8_STAGE(PG8_SB(0, 1), b2 + hstep, voffB); PG8_STAGE(PG8_SA(0, 0), a2, voffA);
;             PG8_WAIT_V(8); PG8_WAIT_L(0); PG8_BAR; PG8_MMA(1, 0, At, B0); PG8_MMA(1, 1, At, B1); PG8_BAR; PG8_SCHED;
	s_nop 0
	s_waitcnt lgkmcnt(0)
	v_mfma_f32_16x16x32_bf16 v[144:147], v[20:23], v[196:199], v[144:147]
	v_mfma_f32_16x16x32_bf16 v[140:143], v[28:31], v[196:199], v[140:143]
	v_mfma_f32_16x16x32_bf16 v[128:131], v[20:23], v[204:207], v[128:131]
	v_mfma_f32_16x16x32_bf16 v[124:127], v[28:31], v[204:207], v[124:127]
	v_mfma_f32_16x16x32_bf16 v[112:115], v[20:23], v[212:215], v[112:115]
	v_mfma_f32_16x16x32_bf16 v[108:111], v[28:31], v[212:215], v[108:111]
	v_mfma_f32_16x16x32_bf16 v[96:99], v[20:23], v[220:223], v[96:99]
	v_mfma_f32_16x16x32_bf16 v[92:95], v[28:31], v[220:223], v[92:95]
	v_mfma_f32_16x16x32_bf16 v[144:147], v[24:27], v[200:203], v[144:147]
	v_mfma_f32_16x16x32_bf16 v[140:143], v[36:39], v[200:203], v[140:143]
	v_mfma_f32_16x16x32_bf16 v[128:131], v[24:27], v[208:211], v[128:131]
	v_mfma_f32_16x16x32_bf16 v[124:127], v[36:39], v[208:211], v[124:127]
	v_mfma_f32_16x16x32_bf16 v[112:115], v[24:27], v[216:219], v[112:115]
	v_mfma_f32_16x16x32_bf16 v[108:111], v[36:39], v[216:219], v[108:111]
	v_mfma_f32_16x16x32_bf16 v[96:99], v[24:27], v[224:227], v[96:99]
	v_mfma_f32_16x16x32_bf16 v[92:95], v[36:39], v[224:227], v[92:95]
	s_nop 0
	s_nop 0
	v_mfma_f32_16x16x32_bf16 v[136:139], v[164:167], v[196:199], v[136:139]
	v_mfma_f32_16x16x32_bf16 v[132:135], v[172:175], v[196:199], v[132:135]
	v_mfma_f32_16x16x32_bf16 v[120:123], v[164:167], v[204:207], v[120:123]
	v_mfma_f32_16x16x32_bf16 v[116:119], v[172:175], v[204:207], v[116:119]
	v_mfma_f32_16x16x32_bf16 v[104:107], v[164:167], v[212:215], v[104:107]
	v_mfma_f32_16x16x32_bf16 v[100:103], v[172:175], v[212:215], v[100:103]
	v_mfma_f32_16x16x32_bf16 v[88:91], v[164:167], v[220:223], v[88:91]
	v_mfma_f32_16x16x32_bf16 v[84:87], v[172:175], v[220:223], v[84:87]
	v_mfma_f32_16x16x32_bf16 v[136:139], v[168:171], v[200:203], v[136:139]
	v_mfma_f32_16x16x32_bf16 v[132:135], v[192:195], v[200:203], v[132:135]
	v_mfma_f32_16x16x32_bf16 v[120:123], v[168:171], v[208:211], v[120:123]
	v_mfma_f32_16x16x32_bf16 v[116:119], v[192:195], v[208:211], v[116:119]
	v_mfma_f32_16x16x32_bf16 v[104:107], v[168:171], v[216:219], v[104:107]
	v_mfma_f32_16x16x32_bf16 v[100:103], v[192:195], v[216:219], v[100:103]
	v_mfma_f32_16x16x32_bf16 v[88:91], v[168:171], v[224:227], v[88:91]
	v_mfma_f32_16x16x32_bf16 v[84:87], v[192:195], v[224:227], v[84:87]
	s_nop 0
	s_barrier
	s_add_i32 s72, s72, s50
	v_lshl_add_u64 v[228:229], s[28:29], 0, v[10:11]
	s_mov_b32 m0, s72
	ds_read_b128 v[196:199], v190 offset:16384
	ds_read_b128 v[200:203], v190 offset:17408
	ds_read_b128 v[204:207], v190 offset:18432
	ds_read_b128 v[208:211], v190 offset:19456
	ds_read_b128 v[212:215], v190 offset:20480
	ds_read_b128 v[216:219], v190 offset:21504
	ds_read_b128 v[220:223], v190 offset:22528
	ds_read_b128 v[224:227], v190 offset:23552
	global_load_lds_dwordx4 v[228:229], off
	s_add_i32 m0, s72, 0x2000
	s_add_u32 s72, s28, 0x80000
	v_lshl_add_u64 v[230:231], s[28:29], 0, v[8:9]
	s_addc_u32 s73, s29, 0
	s_add_i32 s78, s78, s50
	global_load_lds_dwordx4 v[230:231], off
	v_lshl_add_u64 v[232:233], s[72:73], 0, v[10:11]
	s_mov_b32 m0, s78
	v_lshl_add_u64 v[234:235], s[30:31], 0, v[156:157]
	global_load_lds_dwordx4 v[232:233], off
	v_lshl_add_u64 v[232:233], s[72:73], 0, v[8:9]
	s_add_i32 m0, s78, 0x2000
	s_nop 0
	global_load_lds_dwordx4 v[232:233], off
	v_lshl_add_u64 v[232:233], s[30:31], 0, v[158:159]
	s_mov_b32 m0, s51
	s_nop 0
	global_load_lds_dwordx4 v[232:233], off
	s_mov_b32 m0, s58
	s_nop 0
	global_load_lds_dwordx4 v[234:235], off
	s_waitcnt vmcnt(8)
	s_waitcnt lgkmcnt(0)
	s_barrier
	s_nop 0
	s_waitcnt lgkmcnt(0)
	v_mfma_f32_16x16x32_bf16 v[80:83], v[20:23], v[196:199], v[80:83]
	v_mfma_f32_16x16x32_bf16 v[76:79], v[28:31], v[196:199], v[76:79]
	v_mfma_f32_16x16x32_bf16 v[64:67], v[20:23], v[204:207], v[64:67]
	v_mfma_f32_16x16x32_bf16 v[60:63], v[28:31], v[204:207], v[60:63]
	v_mfma_f32_16x16x32_bf16 v[48:51], v[20:23], v[212:215], v[48:51]
	v_mfma_f32_16x16x32_bf16 v[44:47], v[28:31], v[212:215], v[44:47]
	v_mfma_f32_16x16x32_bf16 v[16:19], v[20:23], v[220:223], v[16:19]
	v_mfma_f32_16x16x32_bf16 v[12:15], v[28:31], v[220:223], v[12:15]
	v_mfma_f32_16x16x32_bf16 v[80:83], v[24:27], v[200:203], v[80:83]
	v_mfma_f32_16x16x32_bf16 v[76:79], v[36:39], v[200:203], v[76:79]
	v_mfma_f32_16x16x32_bf16 v[64:67], v[24:27], v[208:211], v[64:67]
	v_mfma_f32_16x16x32_bf16 v[60:63], v[36:39], v[208:211], v[60:63]
	v_mfma_f32_16x16x32_bf16 v[48:51], v[24:27], v[216:219], v[48:51]
	v_mfma_f32_16x16x32_bf16 v[44:47], v[36:39], v[216:219], v[44:47]
	v_mfma_f32_16x16x32_bf16 v[16:19], v[24:27], v[224:227], v[16:19]
	v_mfma_f32_16x16x32_bf16 v[12:15], v[36:39], v[224:227], v[12:15]
	s_nop 0
	s_nop 0
	v_mfma_f32_16x16x32_bf16 v[40:43], v[164:167], v[212:215], v[40:43]
	v_mfma_f32_16x16x32_bf16 v[32:35], v[172:175], v[212:215], v[32:35]
	v_mfma_f32_16x16x32_bf16 v[4:7], v[164:167], v[220:223], v[4:7]
	v_mfma_f32_16x16x32_bf16 v[0:3], v[172:175], v[220:223], v[0:3]
	v_mfma_f32_16x16x32_bf16 v[20:23], v[164:167], v[196:199], v[72:75]
	v_mfma_f32_16x16x32_bf16 v[24:27], v[172:175], v[196:199], v[68:71]
	v_mfma_f32_16x16x32_bf16 v[28:31], v[164:167], v[204:207], v[56:59]
	v_mfma_f32_16x16x32_bf16 v[36:39], v[172:175], v[204:207], v[52:55]
	v_mfma_f32_16x16x32_bf16 v[40:43], v[168:171], v[216:219], v[40:43]
	v_mfma_f32_16x16x32_bf16 v[32:35], v[192:195], v[216:219], v[32:35]
	v_mfma_f32_16x16x32_bf16 v[4:7], v[168:171], v[224:227], v[4:7]
	v_mfma_f32_16x16x32_bf16 v[0:3], v[192:195], v[224:227], v[0:3]
	v_mfma_f32_16x16x32_bf16 v[20:23], v[168:171], v[200:203], v[20:23]
	v_mfma_f32_16x16x32_bf16 v[24:27], v[192:195], v[200:203], v[24:27]
	v_mfma_f32_16x16x32_bf16 v[28:31], v[168:171], v[208:211], v[28:31]
	v_mfma_f32_16x16x32_bf16 v[36:39], v[192:195], v[208:211], v[36:39]
	s_nop 0
	s_barrier
; #define PG8_STAGE(bufoff, gbase, voff) do { _Pragma("unroll") for (int _i = 0; _i < 2; ++_i) \
;         __builtin_amdgcn_global_load_lds((const unsigned*)((const char*)(gbase) + (voff)[_i]), (PG8_LAS unsigned*)(lds + (bufoff) + ldsw + _i * 8192), 16, 0, 0); } while (0)
; #define PG8_LDA(dst, b, h) do { _Pragma("unroll") for (int m = 0; m < 4; ++m) _Pragma("unroll") for (int k = 0; k < 2; ++k) dst[m][k] = *(const PG8_LAS bf16x8*)(lds + PG8_SA(b, h) + aoff + m * 2048 + k * 1024); } while (0)
; #define PG8_LDB(dst, b, h) do { _Pragma("unroll") for (int n = 0; n < 2; ++n) _Pragma("unroll") for (int k = 0; k < 2; ++k) dst[n][k] = *(const PG8_LAS bf16x8*)(lds + PG8_SB(b, h) + boff + n * 2048 + k * 1024); } while (0)
; #define PG8_MMA(ai, bj, At, Bt) do { __builtin_amdgcn_s_setprio(1); _Pragma("unroll") for (int m = 0; m < 4; ++m) _Pragma("unroll") for (int n = 0; n < 2; ++n) _Pragma("unroll") for (int k = 0; k < 2; ++k) \
;         acc[ai][bj][m][n] = __builtin_amdgcn_mfma_f32_16x16x32_bf16(Bt[n][k], At[m][k], acc[ai][bj][m][n], 0, 0, 0); __builtin_amdgcn_s_setprio(0); } while (0)
; #define PG8_WAIT_V(n) asm volatile("s_waitcnt vmcnt(" #n ")" ::: "memory")
; #define PG8_WAIT_L(n) asm volatile("s_waitcnt lgkmcnt(" #n ")" ::: "memory")
; #define PG8_BAR __builtin_amdgcn_s_barrier()
; #define PG8_SCHED __builtin_amdgcn_sched_barrier(0)
; template <class Epi, class Sched, bool ALIGN_EPI = GEMM_ALIGN, bool SP2 = GEMM_SP2>
; __device__ __forceinline__ void gemm_phase(PG8_LAS unsigned char* lds, const Gemm g, const Sched& S, const Epi& E, unsigned long long*  , int tid_in) {
;     ...
;             PG8_LDB(B0, 1, 0); PG8_LDB(B1, 1, 1); PG8_SCHED; PG8_LDA(At, 1, 0); PG8_STAGE(PG8_SA(0, 1), a2 + hstep, voffA);
;             PG8_WAIT_V(8); PG8_WAIT_L(0); PG8_BAR; PG8_MMA(0, 0, At, B0); PG8_MMA(0, 1, At, B1); PG8_BAR; PG8_SCHED;
	s_add_i32 s72, 0, 0x18000
	s_add_i32 s73, 0, 0x1c000
	v_add_u32_e32 v72, s72, v188
	v_add_u32_e32 v150, s73, v188
	ds_read_b128 v[52:55], v72
	ds_read_b128 v[56:59], v72 offset:1024
	ds_read_b128 v[68:71], v72 offset:2048
	ds_read_b128 v[72:75], v72 offset:3072
	ds_read_b128 v[164:167], v150
	ds_read_b128 v[168:171], v150 offset:1024
	ds_read_b128 v[172:175], v150 offset:2048
	ds_read_b128 v[192:195], v150 offset:3072
	s_add_u32 s30, s30, 0x80000
	s_addc_u32 s31, s31, 0
	s_mov_b32 m0, s59
	v_lshl_add_u64 v[236:237], s[30:31], 0, v[158:159]
	ds_read_b128 v[196:199], v190 offset:32768
	ds_read_b128 v[200:203], v190 offset:33792
	ds_read_b128 v[204:207], v190 offset:34816
	ds_read_b128 v[208:211], v190 offset:35840
	ds_read_b128 v[212:215], v190 offset:36864
	ds_read_b128 v[216:219], v190 offset:37888
	ds_read_b128 v[220:223], v190 offset:38912
	ds_read_b128 v[224:227], v190 offset:39936
	global_load_lds_dwordx4 v[236:237], off
	v_lshl_add_u64 v[236:237], s[30:31], 0, v[156:157]
	s_mov_b32 m0, s60
	s_nop 0
	global_load_lds_dwordx4 v[236:237], off
	s_waitcnt vmcnt(8)
	s_waitcnt lgkmcnt(0)
	s_barrier
	s_nop 0
	s_waitcnt lgkmcnt(0)
	v_mfma_f32_16x16x32_bf16 v[144:147], v[52:55], v[196:199], v[144:147]
	v_mfma_f32_16x16x32_bf16 v[140:143], v[68:71], v[196:199], v[140:143]
	v_mfma_f32_16x16x32_bf16 v[128:131], v[52:55], v[204:207], v[128:131]
	v_mfma_f32_16x16x32_bf16 v[124:127], v[68:71], v[204:207], v[124:127]
	v_mfma_f32_16x16x32_bf16 v[112:115], v[52:55], v[212:215], v[112:115]
	v_mfma_f32_16x16x32_bf16 v[108:111], v[68:71], v[212:215], v[108:111]
	v_mfma_f32_16x16x32_bf16 v[96:99], v[52:55], v[220:223], v[96:99]
	v_mfma_f32_16x16x32_bf16 v[92:95], v[68:71], v[220:223], v[92:95]
	v_mfma_f32_16x16x32_bf16 v[144:147], v[56:59], v[200:203], v[144:147]
	v_mfma_f32_16x16x32_bf16 v[140:143], v[72:75], v[200:203], v[140:143]
	v_mfma_f32_16x16x32_bf16 v[128:131], v[56:59], v[208:211], v[128:131]
	v_mfma_f32_16x16x32_bf16 v[124:127], v[72:75], v[208:211], v[124:127]
	v_mfma_f32_16x16x32_bf16 v[112:115], v[56:59], v[216:219], v[112:115]
	v_mfma_f32_16x16x32_bf16 v[108:111], v[72:75], v[216:219], v[108:111]
	v_mfma_f32_16x16x32_bf16 v[96:99], v[56:59], v[224:227], v[96:99]
	v_mfma_f32_16x16x32_bf16 v[92:95], v[72:75], v[224:227], v[92:95]
	s_nop 0
	s_nop 0
	v_mfma_f32_16x16x32_bf16 v[136:139], v[164:167], v[196:199], v[136:139]
	v_mfma_f32_16x16x32_bf16 v[132:135], v[172:175], v[196:199], v[132:135]
	v_mfma_f32_16x16x32_bf16 v[120:123], v[164:167], v[204:207], v[120:123]
	v_mfma_f32_16x16x32_bf16 v[116:119], v[172:175], v[204:207], v[116:119]
	v_mfma_f32_16x16x32_bf16 v[104:107], v[164:167], v[212:215], v[104:107]
	v_mfma_f32_16x16x32_bf16 v[100:103], v[172:175], v[212:215], v[100:103]
	v_mfma_f32_16x16x32_bf16 v[88:91], v[164:167], v[220:223], v[88:91]
	v_mfma_f32_16x16x32_bf16 v[84:87], v[172:175], v[220:223], v[84:87]
	v_mfma_f32_16x16x32_bf16 v[136:139], v[168:171], v[200:203], v[136:139]
	v_mfma_f32_16x16x32_bf16 v[132:135], v[192:195], v[200:203], v[132:135]
	v_mfma_f32_16x16x32_bf16 v[120:123], v[168:171], v[208:211], v[120:123]
	v_mfma_f32_16x16x32_bf16 v[116:119], v[192:195], v[208:211], v[116:119]
	v_mfma_f32_16x16x32_bf16 v[104:107], v[168:171], v[216:219], v[104:107]
	v_mfma_f32_16x16x32_bf16 v[100:103], v[192:195], v[216:219], v[100:103]
	v_mfma_f32_16x16x32_bf16 v[88:91], v[168:171], v[224:227], v[88:91]
	v_mfma_f32_16x16x32_bf16 v[84:87], v[192:195], v[224:227], v[84:87]
	s_nop 0
	s_barrier
; #define PG8_STAGE(bufoff, gbase, voff) do { _Pragma("unroll") for (int _i = 0; _i < 2; ++_i) \
;         __builtin_amdgcn_global_load_lds((const unsigned*)((const char*)(gbase) + (voff)[_i]), (PG8_LAS unsigned*)(lds + (bufoff) + ldsw + _i * 8192), 16, 0, 0); } while (0)
; #define PG8_LDA(dst, b, h) do { _Pragma("unroll") for (int m = 0; m < 4; ++m) _Pragma("unroll") for (int k = 0; k < 2; ++k) dst[m][k] = *(const PG8_LAS bf16x8*)(lds + PG8_SA(b, h) + aoff + m * 2048 + k * 1024); } while (0)
; #define PG8_MMA(ai, bj, At, Bt) do { __builtin_amdgcn_s_setprio(1); _Pragma("unroll") for (int m = 0; m < 4; ++m) _Pragma("unroll") for (int n = 0; n < 2; ++n) _Pragma("unroll") for (int k = 0; k < 2; ++k) \
;         acc[ai][bj][m][n] = __builtin_amdgcn_mfma_f32_16x16x32_bf16(Bt[n][k], At[m][k], acc[ai][bj][m][n], 0, 0, 0); __builtin_amdgcn_s_setprio(0); } while (0)
; #define PG8_WAIT_V(n) asm volatile("s_waitcnt vmcnt(" #n ")" ::: "memory")
; #define PG8_WAIT_L(n) asm volatile("s_waitcnt lgkmcnt(" #n ")" ::: "memory")
; #define PG8_BAR __builtin_amdgcn_s_barrier()
; #define PG8_SCHED __builtin_amdgcn_sched_barrier(0)
; template <class Epi, class Sched, bool ALIGN_EPI = GEMM_ALIGN, bool SP2 = GEMM_SP2>
; __device__ __forceinline__ void gemm_phase(PG8_LAS unsigned char* lds, const Gemm g, const Sched& S, const Epi& E, unsigned long long*  , int tid_in) {
;     ...
;         for (int t = 0; t < nt; t += 2) {
;             const bool last = (t == nt - 2);
;             const char* a1 = cA + (size_t)(t + 1) * kstep;
;             const char* a2 = last ? nA : cA + (size_t)(t + 2) * kstep; const char* b2 = last ? nB : cB + (size_t)(t + 2) * kstep;
;             const char* a3 = a2 + kstep; const char* b3 = b2 + kstep;
;             if (last && has_next) S.a_ready(nxt);
;     ...
;             PG8_LDA(At, 1, 1); PG8_STAGE(PG8_SB(1, 0), b3, voffB); PG8_STAGE(PG8_SB(1, 1), b3 + hstep, voffB); PG8_STAGE(PG8_SA(1, 0), a3, voffA);
;             PG8_WAIT_V(8); PG8_WAIT_L(0); PG8_BAR; PG8_MMA(1, 0, At, B0); PG8_MMA(1, 1, At, B1); PG8_BAR; PG8_SCHED;
	s_add_i32 s30, s72, s50
	v_lshl_add_u64 v[228:229], v[228:229], 0, s[82:83]
	s_mov_b32 m0, s30
	ds_read_b128 v[196:199], v190 offset:49152
	ds_read_b128 v[200:203], v190 offset:50176
	ds_read_b128 v[204:207], v190 offset:51200
	ds_read_b128 v[208:211], v190 offset:52224
	ds_read_b128 v[212:215], v190 offset:53248
	ds_read_b128 v[216:219], v190 offset:54272
	ds_read_b128 v[220:223], v190 offset:55296
	ds_read_b128 v[224:227], v190 offset:56320
	global_load_lds_dwordx4 v[228:229], off
	s_add_i32 m0, s30, 0x2000
	s_add_u32 s28, s28, 0x80080
	v_lshl_add_u64 v[228:229], v[230:231], 0, s[82:83]
	s_addc_u32 s29, s29, 0
	s_add_i32 s30, s73, s50
	global_load_lds_dwordx4 v[228:229], off
	v_lshl_add_u64 v[228:229], s[28:29], 0, v[10:11]
	s_mov_b32 m0, s30
	s_nop 0
	global_load_lds_dwordx4 v[228:229], off
	v_lshl_add_u64 v[228:229], s[28:29], 0, v[8:9]
	s_add_i32 m0, s30, 0x2000
	s_nop 0
	global_load_lds_dwordx4 v[228:229], off
	v_lshl_add_u64 v[228:229], v[232:233], 0, s[82:83]
	s_mov_b32 m0, s61
	s_nop 0
	global_load_lds_dwordx4 v[228:229], off
	v_lshl_add_u64 v[228:229], v[234:235], 0, s[82:83]
	s_mov_b32 m0, s62
	s_nop 0
	global_load_lds_dwordx4 v[228:229], off
	s_waitcnt vmcnt(8)
	s_waitcnt lgkmcnt(0)
	s_barrier
	s_nop 0
	s_waitcnt lgkmcnt(0)
	v_mfma_f32_16x16x32_bf16 v[80:83], v[52:55], v[196:199], v[80:83]
	v_mfma_f32_16x16x32_bf16 v[76:79], v[68:71], v[196:199], v[76:79]
	v_mfma_f32_16x16x32_bf16 v[64:67], v[52:55], v[204:207], v[64:67]
	v_mfma_f32_16x16x32_bf16 v[60:63], v[68:71], v[204:207], v[60:63]
	v_mfma_f32_16x16x32_bf16 v[48:51], v[52:55], v[212:215], v[48:51]
	v_mfma_f32_16x16x32_bf16 v[44:47], v[68:71], v[212:215], v[44:47]
	v_mfma_f32_16x16x32_bf16 v[16:19], v[52:55], v[220:223], v[16:19]
	v_mfma_f32_16x16x32_bf16 v[12:15], v[68:71], v[220:223], v[12:15]
	v_mfma_f32_16x16x32_bf16 v[80:83], v[56:59], v[200:203], v[80:83]
	v_mfma_f32_16x16x32_bf16 v[76:79], v[72:75], v[200:203], v[76:79]
	v_mfma_f32_16x16x32_bf16 v[64:67], v[56:59], v[208:211], v[64:67]
	v_mfma_f32_16x16x32_bf16 v[60:63], v[72:75], v[208:211], v[60:63]
	v_mfma_f32_16x16x32_bf16 v[48:51], v[56:59], v[216:219], v[48:51]
	v_mfma_f32_16x16x32_bf16 v[44:47], v[72:75], v[216:219], v[44:47]
	v_mfma_f32_16x16x32_bf16 v[16:19], v[56:59], v[224:227], v[16:19]
	v_mfma_f32_16x16x32_bf16 v[12:15], v[72:75], v[224:227], v[12:15]
	s_nop 0
	s_nop 0
	v_mfma_f32_16x16x32_bf16 v[20:23], v[164:167], v[196:199], v[20:23]
	v_mfma_f32_16x16x32_bf16 v[72:75], v[168:171], v[200:203], v[20:23]
	v_mfma_f32_16x16x32_bf16 v[20:23], v[172:175], v[196:199], v[24:27]
	v_mfma_f32_16x16x32_bf16 v[68:71], v[192:195], v[200:203], v[20:23]
	v_mfma_f32_16x16x32_bf16 v[20:23], v[164:167], v[204:207], v[28:31]
	v_mfma_f32_16x16x32_bf16 v[56:59], v[168:171], v[208:211], v[20:23]
	v_mfma_f32_16x16x32_bf16 v[20:23], v[172:175], v[204:207], v[36:39]
	v_mfma_f32_16x16x32_bf16 v[52:55], v[192:195], v[208:211], v[20:23]
	v_mfma_f32_16x16x32_bf16 v[20:23], v[164:167], v[212:215], v[40:43]
	v_mfma_f32_16x16x32_bf16 v[40:43], v[168:171], v[216:219], v[20:23]
	v_mfma_f32_16x16x32_bf16 v[20:23], v[172:175], v[212:215], v[32:35]
	v_mfma_f32_16x16x32_bf16 v[4:7], v[164:167], v[220:223], v[4:7]
	v_mfma_f32_16x16x32_bf16 v[0:3], v[172:175], v[220:223], v[0:3]
	v_mfma_f32_16x16x32_bf16 v[32:35], v[192:195], v[216:219], v[20:23]
	v_mfma_f32_16x16x32_bf16 v[4:7], v[168:171], v[224:227], v[4:7]
	v_mfma_f32_16x16x32_bf16 v[0:3], v[192:195], v[224:227], v[0:3]
	s_nop 0
	s_barrier
	s_add_i32 s71, s71, 2
	s_add_u32 s69, s69, 0x100
	s_addc_u32 s70, s70, 0
	s_add_u32 s2, s2, 0x100
	s_addc_u32 s3, s3, 0
	s_cmp_gt_u32 s71, 29
	s_cbranch_scc0 .LBB0_1002
	s_setprio 0
	s_and_b64 vcc, exec, s[18:19]
	s_cbranch_vccz .LBB0_1005
	s_barrier

; #define PG8_WAIT_V(n) asm volatile("s_waitcnt vmcnt(" #n ")" ::: "memory")
; template <class Epi, class Sched, bool ALIGN_EPI = GEMM_ALIGN, bool SP2 = GEMM_SP2>
; __device__ __forceinline__ void gemm_phase(PG8_LAS unsigned char* lds, const Gemm g, const Sched& S, const Epi& E, unsigned long long*  , int tid_in) {
;     ...
;     f32x4 acc[2][2][4][2];
; #pragma unroll
;     for (int a = 0; a < 2; ++a)
; #pragma unroll
;         for (int b = 0; b < 2; ++b)
; #pragma unroll
;             for (int m = 0; m < 4; ++m)
; #pragma unroll
;                 for (int n = 0; n < 2; ++n) acc[a][b][m][n] = (f32x4){0.f, 0.f, 0.f, 0.f};
;     bf16x8 At[4][2], B0[2][2], B1[2][2];
;     const char* cA = (const char*)g.A + (size_t)cur.pm * tstep; const char* cB = (const char*)g.Bt + (size_t)cur.pn * tstep;
;     S.a_ready(cur);
;     if constexpr (SP2) {
;         PG8_STAGE(PG8_SB(0, 0), cB, voffB); PG8_STAGE(PG8_SB(0, 1), cB + hstep, voffB); PG8_STAGE(PG8_SA(0, 0), cA, voffA); PG8_STAGE(PG8_SA(0, 1), cA + hstep, voffA);
;         if (wr == 1) PG8_BAR;
;         PG8_WAIT_V(2); PG8_BAR;
;         PG8_STAGE(PG8_SB(1, 0), cB + kstep, voffB); PG8_STAGE(PG8_SA(1, 0), cA + kstep, voffA); PG8_STAGE(PG8_SB(1, 1), cB + hstep + kstep, voffB);
;         PG8_WAIT_V(6); PG8_BAR;
;     } else {
;         PG8_STAGE(PG8_SB(0, 0), cB, voffB); PG8_STAGE(PG8_SA(0, 0), cA, voffA); PG8_STAGE(PG8_SB(0, 1), cB + hstep, voffB); PG8_STAGE(PG8_SA(0, 1), cA + hstep, voffA);
;         if (wr == 1) PG8_BAR;
;         PG8_WAIT_V(4); PG8_BAR;
;         PG8_STAGE(PG8_SB(1, 0), cB + kstep, voffB); PG8_STAGE(PG8_SA(1, 0), cA + kstep, voffA); PG8_STAGE(PG8_SB(1, 1), cB + hstep + kstep, voffB);
;         PG8_WAIT_V(6); PG8_BAR;
;     }
;     for (;;) {
;         const bool has_next = S.next(ui + 1, nxt);
;         const char* nA = has_next ? (const char*)g.A + (size_t)nxt.pm * tstep : cA; const char* nB = has_next ? (const char*)g.Bt + (size_t)nxt.pn * tstep : cB;
;         for (int t = 0; t < nt; t += 2) {
;             const bool last = (t == nt - 2);
;             const char* a1 = cA + (size_t)(t + 1) * kstep;
;             const char* a2 = last ? nA : cA + (size_t)(t + 2) * kstep; const char* b2 = last ? nB : cB + (size_t)(t + 2) * kstep;
;             const char* a3 = a2 + kstep; const char* b3 = b2 + kstep;
;             if (last && has_next) S.a_ready(nxt);
;             if constexpr (SP2) {
.LBB0_1073:
	s_ashr_i32 s19, s18, 31
	s_lshl_b64 s[20:21], s[18:19], 19
	s_add_u32 s20, s34, s20
	s_addc_u32 s21, s35, s21
	s_and_b64 s[22:23], s[6:7], exec
	s_cselect_b32 s19, s21, s27
	s_cselect_b32 s67, s20, s26
	s_ashr_i32 s17, s16, 31
	s_lshl_b64 s[22:23], s[16:17], 19
	s_add_u32 s22, s8, s22
	s_addc_u32 s23, s9, s23
	s_and_b64 s[28:29], s[6:7], exec
	s_cselect_b32 s17, s23, s25
	s_cselect_b32 s68, s22, s24
	s_add_u32 s69, s24, 0x100
	s_addc_u32 s70, s25, 0
	s_add_u32 s24, s26, 0x40080
	v_mov_b32_e32 v0, 0
	s_addc_u32 s25, s27, 0
	s_mov_b32 s71, -2
	v_mov_b32_e32 v1, v0
	v_mov_b32_e32 v2, v0
	v_mov_b32_e32 v3, v0
	v_mov_b32_e32 v4, v0
	v_mov_b32_e32 v5, v0
	v_mov_b32_e32 v6, v0
	v_mov_b32_e32 v7, v0
	v_mov_b32_e32 v16, v0
	v_mov_b32_e32 v17, v0
	v_mov_b32_e32 v18, v0
	v_mov_b32_e32 v19, v0
	v_mov_b32_e32 v24, v0
	v_mov_b32_e32 v25, v0
	v_mov_b32_e32 v26, v0
	v_mov_b32_e32 v27, v0
	v_mov_b32_e32 v32, v0
	v_mov_b32_e32 v33, v0
	v_mov_b32_e32 v34, v0
	v_mov_b32_e32 v35, v0
	v_mov_b32_e32 v40, v0
	v_mov_b32_e32 v41, v0
	v_mov_b32_e32 v42, v0
	v_mov_b32_e32 v43, v0
	v_mov_b32_e32 v48, v0
	v_mov_b32_e32 v49, v0
	v_mov_b32_e32 v50, v0
	v_mov_b32_e32 v51, v0
	v_mov_b32_e32 v56, v0
	v_mov_b32_e32 v57, v0
	v_mov_b32_e32 v58, v0
	v_mov_b32_e32 v59, v0
	v_mov_b32_e32 v12, v0
	v_mov_b32_e32 v13, v0
	v_mov_b32_e32 v14, v0
	v_mov_b32_e32 v15, v0
	v_mov_b32_e32 v20, v0
	v_mov_b32_e32 v21, v0
	v_mov_b32_e32 v22, v0
	v_mov_b32_e32 v23, v0
	v_mov_b32_e32 v28, v0
	v_mov_b32_e32 v29, v0
	v_mov_b32_e32 v30, v0
	v_mov_b32_e32 v31, v0
	v_mov_b32_e32 v36, v0
	v_mov_b32_e32 v37, v0
	v_mov_b32_e32 v38, v0
	v_mov_b32_e32 v39, v0
	v_mov_b32_e32 v44, v0
	v_mov_b32_e32 v45, v0
	v_mov_b32_e32 v46, v0
	v_mov_b32_e32 v47, v0
	v_mov_b32_e32 v52, v0
	v_mov_b32_e32 v53, v0
	v_mov_b32_e32 v54, v0
	v_mov_b32_e32 v55, v0
	v_mov_b32_e32 v60, v0
	v_mov_b32_e32 v61, v0
	v_mov_b32_e32 v62, v0
	v_mov_b32_e32 v63, v0
	v_mov_b32_e32 v64, v0
	v_mov_b32_e32 v65, v0
	v_mov_b32_e32 v66, v0
	v_mov_b32_e32 v67, v0
	v_mov_b32_e32 v68, v0
	v_mov_b32_e32 v69, v0
	v_mov_b32_e32 v70, v0
	v_mov_b32_e32 v71, v0
	v_mov_b32_e32 v72, v0
	v_mov_b32_e32 v73, v0
	v_mov_b32_e32 v74, v0
	v_mov_b32_e32 v75, v0
	v_mov_b32_e32 v80, v0
	v_mov_b32_e32 v81, v0
	v_mov_b32_e32 v82, v0
	v_mov_b32_e32 v83, v0
	v_mov_b32_e32 v84, v0
	v_mov_b32_e32 v85, v0
	v_mov_b32_e32 v86, v0
	v_mov_b32_e32 v87, v0
	v_mov_b32_e32 v96, v0
	v_mov_b32_e32 v97, v0
	v_mov_b32_e32 v98, v0
	v_mov_b32_e32 v99, v0
	v_mov_b32_e32 v100, v0
	v_mov_b32_e32 v101, v0
	v_mov_b32_e32 v102, v0
	v_mov_b32_e32 v103, v0
	v_mov_b32_e32 v112, v0
	v_mov_b32_e32 v113, v0
	v_mov_b32_e32 v114, v0
	v_mov_b32_e32 v115, v0
	v_mov_b32_e32 v124, v0
	v_mov_b32_e32 v125, v0
	v_mov_b32_e32 v126, v0
	v_mov_b32_e32 v127, v0
	v_mov_b32_e32 v76, v0
	v_mov_b32_e32 v77, v0
	v_mov_b32_e32 v78, v0
	v_mov_b32_e32 v79, v0
	v_mov_b32_e32 v88, v0
	v_mov_b32_e32 v89, v0
	v_mov_b32_e32 v90, v0
	v_mov_b32_e32 v91, v0
	v_mov_b32_e32 v92, v0
	v_mov_b32_e32 v93, v0
	v_mov_b32_e32 v94, v0
	v_mov_b32_e32 v95, v0
	v_mov_b32_e32 v104, v0
	v_mov_b32_e32 v105, v0
	v_mov_b32_e32 v106, v0
	v_mov_b32_e32 v107, v0
	v_mov_b32_e32 v108, v0
	v_mov_b32_e32 v109, v0
	v_mov_b32_e32 v110, v0
	v_mov_b32_e32 v111, v0
	v_mov_b32_e32 v128, v0
	v_mov_b32_e32 v129, v0
	v_mov_b32_e32 v130, v0
	v_mov_b32_e32 v131, v0
	v_mov_b32_e32 v140, v0
	v_mov_b32_e32 v141, v0
	v_mov_b32_e32 v142, v0
	v_mov_b32_e32 v143, v0
	v_mov_b32_e32 v144, v0
	v_mov_b32_e32 v145, v0
	v_mov_b32_e32 v146, v0
	v_mov_b32_e32 v147, v0
	s_and_b64 vcc, exec, s[14:15]
	s_cbranch_vccnz .Lprio_1074
	s_setprio 1
.Lprio_1074:
.LBB0_1074:
	s_add_u32 s26, s24, 0xfffc0080
	s_addc_u32 s27, s25, -1
	s_add_i32 s72, 0, 0x10000
	s_cmp_eq_u32 s71, 12
	s_cselect_b32 s29, s19, s27
	s_cselect_b32 s28, s67, s26
	s_cselect_b32 s27, s17, s70
	s_cselect_b32 s26, s68, s69
	s_add_i32 s78, 0, 0x14000
	v_add_u32_e32 v136, s72, v170
	v_add_u32_e32 v150, s78, v170
	ds_read_b128 v[116:119], v136
	ds_read_b128 v[120:123], v136 offset:1024
	ds_read_b128 v[132:135], v136 offset:2048
	ds_read_b128 v[136:139], v136 offset:3072
	ds_read_b128 v[164:167], v150
	ds_read_b128 v[188:191], v150 offset:1024
	ds_read_b128 v[192:195], v150 offset:2048
	ds_read_b128 v[196:199], v150 offset:3072
	v_lshl_add_u64 v[168:169], s[24:25], 0, v[162:163]
	s_add_i32 m0, s37, 0xc000
	ds_read_b128 v[200:203], v172
	ds_read_b128 v[204:207], v172 offset:1024
	ds_read_b128 v[208:211], v172 offset:2048
	ds_read_b128 v[212:215], v172 offset:3072
	ds_read_b128 v[216:219], v172 offset:4096
	ds_read_b128 v[220:223], v172 offset:5120
	ds_read_b128 v[224:227], v172 offset:6144
	ds_read_b128 v[228:231], v172 offset:7168
	global_load_lds_dwordx4 v[168:169], off
	v_lshl_add_u64 v[168:169], s[24:25], 0, v[160:161]
	s_add_i32 m0, s37, 0xe000
	s_nop 0
	global_load_lds_dwordx4 v[168:169], off
	s_waitcnt vmcnt(8)
	s_waitcnt lgkmcnt(0)
	s_barrier
; #define PG8_STAGE(bufoff, gbase, voff) do { _Pragma("unroll") for (int _i = 0; _i < 2; ++_i) \
;         __builtin_amdgcn_global_load_lds((const unsigned*)((const char*)(gbase) + (voff)[_i]), (PG8_LAS unsigned*)(lds + (bufoff) + ldsw + _i * 8192), 16, 0, 0); } while (0)
; #define PG8_LDA(dst, b, h) do { _Pragma("unroll") for (int m = 0; m < 4; ++m) _Pragma("unroll") for (int k = 0; k < 2; ++k) dst[m][k] = *(const PG8_LAS bf16x8*)(lds + PG8_SA(b, h) + aoff + m * 2048 + k * 1024); } while (0)
; #define PG8_MMA(ai, bj, At, Bt) do { __builtin_amdgcn_s_setprio(1); _Pragma("unroll") for (int m = 0; m < 4; ++m) _Pragma("unroll") for (int n = 0; n < 2; ++n) _Pragma("unroll") for (int k = 0; k < 2; ++k) \
;         acc[ai][bj][m][n] = __builtin_amdgcn_mfma_f32_16x16x32_bf16(Bt[n][k], At[m][k], acc[ai][bj][m][n], 0, 0, 0); __builtin_amdgcn_s_setprio(0); } while (0)
; #define PG8_WAIT_V(n) asm volatile("s_waitcnt vmcnt(" #n ")" ::: "memory")
; #define PG8_WAIT_L(n) asm volatile("s_waitcnt lgkmcnt(" #n ")" ::: "memory")
; #define PG8_BAR __builtin_amdgcn_s_barrier()
; #define PG8_SCHED __builtin_amdgcn_sched_barrier(0)
; template <class Epi, class Sched, bool ALIGN_EPI = GEMM_ALIGN, bool SP2 = GEMM_SP2>
; __device__ __forceinline__ void gemm_phase(PG8_LAS unsigned char* lds, const Gemm g, const Sched& S, const Epi& E, unsigned long long*  , int tid_in) {
;     ...
;             PG8_WAIT_V(8); PG8_WAIT_L(0); PG8_BAR; PG8_MMA(0, 0, At, B0); PG8_MMA(0, 1, At, B1); PG8_BAR; PG8_SCHED;
;             PG8_LDA(At, 0, 1); PG8_STAGE(PG8_SB(0, 0), b2, voffB); PG8_STAGE(PG8_SB(0, 1), b2 + hstep, voffB); PG8_STAGE(PG8_SA(0, 0), a2, voffA);
;             PG8_WAIT_V(8); PG8_WAIT_L(0); PG8_BAR; PG8_MMA(1, 0, At, B0); PG8_MMA(1, 1, At, B1); PG8_BAR; PG8_SCHED;
	s_nop 0
	s_waitcnt lgkmcnt(0)
	v_mfma_f32_16x16x32_bf16 v[144:147], v[116:119], v[200:203], v[144:147]
	v_mfma_f32_16x16x32_bf16 v[140:143], v[132:135], v[200:203], v[140:143]
	v_mfma_f32_16x16x32_bf16 v[128:131], v[116:119], v[208:211], v[128:131]
	v_mfma_f32_16x16x32_bf16 v[108:111], v[132:135], v[208:211], v[108:111]
	v_mfma_f32_16x16x32_bf16 v[104:107], v[116:119], v[216:219], v[104:107]
	v_mfma_f32_16x16x32_bf16 v[92:95], v[132:135], v[216:219], v[92:95]
	v_mfma_f32_16x16x32_bf16 v[88:91], v[116:119], v[224:227], v[88:91]
	v_mfma_f32_16x16x32_bf16 v[76:79], v[132:135], v[224:227], v[76:79]
	v_mfma_f32_16x16x32_bf16 v[144:147], v[120:123], v[204:207], v[144:147]
	v_mfma_f32_16x16x32_bf16 v[140:143], v[136:139], v[204:207], v[140:143]
	v_mfma_f32_16x16x32_bf16 v[128:131], v[120:123], v[212:215], v[128:131]
	v_mfma_f32_16x16x32_bf16 v[108:111], v[136:139], v[212:215], v[108:111]
	v_mfma_f32_16x16x32_bf16 v[104:107], v[120:123], v[220:223], v[104:107]
	v_mfma_f32_16x16x32_bf16 v[92:95], v[136:139], v[220:223], v[92:95]
	v_mfma_f32_16x16x32_bf16 v[88:91], v[120:123], v[228:231], v[88:91]
	v_mfma_f32_16x16x32_bf16 v[76:79], v[136:139], v[228:231], v[76:79]
	s_nop 0
	s_nop 0
	v_mfma_f32_16x16x32_bf16 v[124:127], v[164:167], v[200:203], v[124:127]
	v_mfma_f32_16x16x32_bf16 v[112:115], v[192:195], v[200:203], v[112:115]
	v_mfma_f32_16x16x32_bf16 v[100:103], v[164:167], v[208:211], v[100:103]
	v_mfma_f32_16x16x32_bf16 v[96:99], v[192:195], v[208:211], v[96:99]
	v_mfma_f32_16x16x32_bf16 v[84:87], v[164:167], v[216:219], v[84:87]
	v_mfma_f32_16x16x32_bf16 v[80:83], v[192:195], v[216:219], v[80:83]
	v_mfma_f32_16x16x32_bf16 v[72:75], v[164:167], v[224:227], v[72:75]
	v_mfma_f32_16x16x32_bf16 v[68:71], v[192:195], v[224:227], v[68:71]
	v_mfma_f32_16x16x32_bf16 v[124:127], v[188:191], v[204:207], v[124:127]
	v_mfma_f32_16x16x32_bf16 v[112:115], v[196:199], v[204:207], v[112:115]
	v_mfma_f32_16x16x32_bf16 v[100:103], v[188:191], v[212:215], v[100:103]
	v_mfma_f32_16x16x32_bf16 v[96:99], v[196:199], v[212:215], v[96:99]
	v_mfma_f32_16x16x32_bf16 v[84:87], v[188:191], v[220:223], v[84:87]
	v_mfma_f32_16x16x32_bf16 v[80:83], v[196:199], v[220:223], v[80:83]
	v_mfma_f32_16x16x32_bf16 v[72:75], v[188:191], v[228:231], v[72:75]
	v_mfma_f32_16x16x32_bf16 v[68:71], v[196:199], v[228:231], v[68:71]
	s_nop 0
	s_barrier
	s_add_i32 s72, s72, s36
	v_lshl_add_u64 v[168:169], s[26:27], 0, v[10:11]
	s_mov_b32 m0, s72
	ds_read_b128 v[200:203], v172 offset:16384
	ds_read_b128 v[204:207], v172 offset:17408
	ds_read_b128 v[208:211], v172 offset:18432
	ds_read_b128 v[212:215], v172 offset:19456
	ds_read_b128 v[216:219], v172 offset:20480
	ds_read_b128 v[220:223], v172 offset:21504
	ds_read_b128 v[224:227], v172 offset:22528
	ds_read_b128 v[228:231], v172 offset:23552
	global_load_lds_dwordx4 v[168:169], off
	s_add_i32 m0, s72, 0x2000
	s_add_u32 s72, s26, 0x40000
	v_lshl_add_u64 v[174:175], s[26:27], 0, v[8:9]
	s_addc_u32 s73, s27, 0
	s_add_i32 s78, s78, s36
	global_load_lds_dwordx4 v[174:175], off
	v_lshl_add_u64 v[232:233], s[72:73], 0, v[10:11]
	s_mov_b32 m0, s78
	v_lshl_add_u64 v[234:235], s[28:29], 0, v[156:157]
	global_load_lds_dwordx4 v[232:233], off
	v_lshl_add_u64 v[232:233], s[72:73], 0, v[8:9]
	s_add_i32 m0, s78, 0x2000
	s_nop 0
	global_load_lds_dwordx4 v[232:233], off
	v_lshl_add_u64 v[232:233], s[28:29], 0, v[158:159]
	s_mov_b32 m0, s37
	s_nop 0
	global_load_lds_dwordx4 v[232:233], off
	s_mov_b32 m0, s50
	s_nop 0
	global_load_lds_dwordx4 v[234:235], off
	s_waitcnt vmcnt(8)
	s_waitcnt lgkmcnt(0)
	s_barrier
	s_nop 0
	s_waitcnt lgkmcnt(0)
	v_mfma_f32_16x16x32_bf16 v[64:67], v[116:119], v[200:203], v[64:67]
	v_mfma_f32_16x16x32_bf16 v[60:63], v[132:135], v[200:203], v[60:63]
	v_mfma_f32_16x16x32_bf16 v[52:55], v[116:119], v[208:211], v[52:55]
	v_mfma_f32_16x16x32_bf16 v[44:47], v[132:135], v[208:211], v[44:47]
	v_mfma_f32_16x16x32_bf16 v[36:39], v[116:119], v[216:219], v[36:39]
	v_mfma_f32_16x16x32_bf16 v[28:31], v[132:135], v[216:219], v[28:31]
	v_mfma_f32_16x16x32_bf16 v[20:23], v[116:119], v[224:227], v[20:23]
	v_mfma_f32_16x16x32_bf16 v[12:15], v[132:135], v[224:227], v[12:15]
	v_mfma_f32_16x16x32_bf16 v[64:67], v[120:123], v[204:207], v[64:67]
	v_mfma_f32_16x16x32_bf16 v[60:63], v[136:139], v[204:207], v[60:63]
	v_mfma_f32_16x16x32_bf16 v[52:55], v[120:123], v[212:215], v[52:55]
	v_mfma_f32_16x16x32_bf16 v[44:47], v[136:139], v[212:215], v[44:47]
	v_mfma_f32_16x16x32_bf16 v[36:39], v[120:123], v[220:223], v[36:39]
	v_mfma_f32_16x16x32_bf16 v[28:31], v[136:139], v[220:223], v[28:31]
	v_mfma_f32_16x16x32_bf16 v[20:23], v[120:123], v[228:231], v[20:23]
	v_mfma_f32_16x16x32_bf16 v[12:15], v[136:139], v[228:231], v[12:15]
	s_nop 0
	s_nop 0
	v_mfma_f32_16x16x32_bf16 v[56:59], v[164:167], v[200:203], v[56:59]
	v_mfma_f32_16x16x32_bf16 v[48:51], v[192:195], v[200:203], v[48:51]
	v_mfma_f32_16x16x32_bf16 v[40:43], v[164:167], v[208:211], v[40:43]
	v_mfma_f32_16x16x32_bf16 v[32:35], v[192:195], v[208:211], v[32:35]
	v_mfma_f32_16x16x32_bf16 v[24:27], v[164:167], v[216:219], v[24:27]
	v_mfma_f32_16x16x32_bf16 v[16:19], v[192:195], v[216:219], v[16:19]
	v_mfma_f32_16x16x32_bf16 v[4:7], v[164:167], v[224:227], v[4:7]
	v_mfma_f32_16x16x32_bf16 v[0:3], v[192:195], v[224:227], v[0:3]
	v_mfma_f32_16x16x32_bf16 v[56:59], v[188:191], v[204:207], v[56:59]
	v_mfma_f32_16x16x32_bf16 v[48:51], v[196:199], v[204:207], v[48:51]
	v_mfma_f32_16x16x32_bf16 v[40:43], v[188:191], v[212:215], v[40:43]
	v_mfma_f32_16x16x32_bf16 v[32:35], v[196:199], v[212:215], v[32:35]
	v_mfma_f32_16x16x32_bf16 v[24:27], v[188:191], v[220:223], v[24:27]
	v_mfma_f32_16x16x32_bf16 v[16:19], v[196:199], v[220:223], v[16:19]
	v_mfma_f32_16x16x32_bf16 v[4:7], v[188:191], v[228:231], v[4:7]
	v_mfma_f32_16x16x32_bf16 v[0:3], v[196:199], v[228:231], v[0:3]
	s_nop 0
	s_barrier
; #define PG8_STAGE(bufoff, gbase, voff) do { _Pragma("unroll") for (int _i = 0; _i < 2; ++_i) \
;         __builtin_amdgcn_global_load_lds((const unsigned*)((const char*)(gbase) + (voff)[_i]), (PG8_LAS unsigned*)(lds + (bufoff) + ldsw + _i * 8192), 16, 0, 0); } while (0)
; #define PG8_LDA(dst, b, h) do { _Pragma("unroll") for (int m = 0; m < 4; ++m) _Pragma("unroll") for (int k = 0; k < 2; ++k) dst[m][k] = *(const PG8_LAS bf16x8*)(lds + PG8_SA(b, h) + aoff + m * 2048 + k * 1024); } while (0)
; #define PG8_LDB(dst, b, h) do { _Pragma("unroll") for (int n = 0; n < 2; ++n) _Pragma("unroll") for (int k = 0; k < 2; ++k) dst[n][k] = *(const PG8_LAS bf16x8*)(lds + PG8_SB(b, h) + boff + n * 2048 + k * 1024); } while (0)
; #define PG8_MMA(ai, bj, At, Bt) do { __builtin_amdgcn_s_setprio(1); _Pragma("unroll") for (int m = 0; m < 4; ++m) _Pragma("unroll") for (int n = 0; n < 2; ++n) _Pragma("unroll") for (int k = 0; k < 2; ++k) \
;         acc[ai][bj][m][n] = __builtin_amdgcn_mfma_f32_16x16x32_bf16(Bt[n][k], At[m][k], acc[ai][bj][m][n], 0, 0, 0); __builtin_amdgcn_s_setprio(0); } while (0)
; #define PG8_WAIT_V(n) asm volatile("s_waitcnt vmcnt(" #n ")" ::: "memory")
; #define PG8_WAIT_L(n) asm volatile("s_waitcnt lgkmcnt(" #n ")" ::: "memory")
; #define PG8_BAR __builtin_amdgcn_s_barrier()
; #define PG8_SCHED __builtin_amdgcn_sched_barrier(0)
; template <class Epi, class Sched, bool ALIGN_EPI = GEMM_ALIGN, bool SP2 = GEMM_SP2>
; __device__ __forceinline__ void gemm_phase(PG8_LAS unsigned char* lds, const Gemm g, const Sched& S, const Epi& E, unsigned long long*  , int tid_in) {
;     ...
;             PG8_LDB(B0, 1, 0); PG8_LDB(B1, 1, 1); PG8_SCHED; PG8_LDA(At, 1, 0); PG8_STAGE(PG8_SA(0, 1), a2 + hstep, voffA);
;             PG8_WAIT_V(8); PG8_WAIT_L(0); PG8_BAR; PG8_MMA(0, 0, At, B0); PG8_MMA(0, 1, At, B1); PG8_BAR; PG8_SCHED;
	s_add_i32 s72, 0, 0x18000
	s_add_i32 s73, 0, 0x1c000
	v_add_u32_e32 v136, s72, v170
	v_add_u32_e32 v150, s73, v170
	ds_read_b128 v[116:119], v136
	ds_read_b128 v[120:123], v136 offset:1024
	ds_read_b128 v[132:135], v136 offset:2048
	ds_read_b128 v[136:139], v136 offset:3072
	ds_read_b128 v[164:167], v150
	ds_read_b128 v[188:191], v150 offset:1024
	ds_read_b128 v[192:195], v150 offset:2048
	ds_read_b128 v[196:199], v150 offset:3072
	s_add_u32 s28, s28, 0x40000
	s_addc_u32 s29, s29, 0
	s_mov_b32 m0, s51
	v_lshl_add_u64 v[236:237], s[28:29], 0, v[158:159]
	ds_read_b128 v[200:203], v172 offset:32768
	ds_read_b128 v[204:207], v172 offset:33792
	ds_read_b128 v[208:211], v172 offset:34816
	ds_read_b128 v[212:215], v172 offset:35840
	ds_read_b128 v[216:219], v172 offset:36864
	ds_read_b128 v[220:223], v172 offset:37888
	ds_read_b128 v[224:227], v172 offset:38912
	ds_read_b128 v[228:231], v172 offset:39936
	global_load_lds_dwordx4 v[236:237], off
	v_lshl_add_u64 v[236:237], s[28:29], 0, v[156:157]
	s_mov_b32 m0, s58
	s_nop 0
	global_load_lds_dwordx4 v[236:237], off
	s_waitcnt vmcnt(8)
	s_waitcnt lgkmcnt(0)
	s_barrier
	s_nop 0
	s_waitcnt lgkmcnt(0)
	v_mfma_f32_16x16x32_bf16 v[144:147], v[116:119], v[200:203], v[144:147]
	v_mfma_f32_16x16x32_bf16 v[140:143], v[132:135], v[200:203], v[140:143]
	v_mfma_f32_16x16x32_bf16 v[128:131], v[116:119], v[208:211], v[128:131]
	v_mfma_f32_16x16x32_bf16 v[108:111], v[132:135], v[208:211], v[108:111]
	v_mfma_f32_16x16x32_bf16 v[104:107], v[116:119], v[216:219], v[104:107]
	v_mfma_f32_16x16x32_bf16 v[92:95], v[132:135], v[216:219], v[92:95]
	v_mfma_f32_16x16x32_bf16 v[88:91], v[116:119], v[224:227], v[88:91]
	v_mfma_f32_16x16x32_bf16 v[76:79], v[132:135], v[224:227], v[76:79]
	v_mfma_f32_16x16x32_bf16 v[144:147], v[120:123], v[204:207], v[144:147]
	v_mfma_f32_16x16x32_bf16 v[140:143], v[136:139], v[204:207], v[140:143]
	v_mfma_f32_16x16x32_bf16 v[128:131], v[120:123], v[212:215], v[128:131]
	v_mfma_f32_16x16x32_bf16 v[108:111], v[136:139], v[212:215], v[108:111]
	v_mfma_f32_16x16x32_bf16 v[104:107], v[120:123], v[220:223], v[104:107]
	v_mfma_f32_16x16x32_bf16 v[92:95], v[136:139], v[220:223], v[92:95]
	v_mfma_f32_16x16x32_bf16 v[88:91], v[120:123], v[228:231], v[88:91]
	v_mfma_f32_16x16x32_bf16 v[76:79], v[136:139], v[228:231], v[76:79]
	s_nop 0
	s_nop 0
	v_mfma_f32_16x16x32_bf16 v[124:127], v[164:167], v[200:203], v[124:127]
	v_mfma_f32_16x16x32_bf16 v[112:115], v[192:195], v[200:203], v[112:115]
	v_mfma_f32_16x16x32_bf16 v[100:103], v[164:167], v[208:211], v[100:103]
	v_mfma_f32_16x16x32_bf16 v[96:99], v[192:195], v[208:211], v[96:99]
	v_mfma_f32_16x16x32_bf16 v[84:87], v[164:167], v[216:219], v[84:87]
	v_mfma_f32_16x16x32_bf16 v[80:83], v[192:195], v[216:219], v[80:83]
	v_mfma_f32_16x16x32_bf16 v[72:75], v[164:167], v[224:227], v[72:75]
	v_mfma_f32_16x16x32_bf16 v[68:71], v[192:195], v[224:227], v[68:71]
	v_mfma_f32_16x16x32_bf16 v[124:127], v[188:191], v[204:207], v[124:127]
	v_mfma_f32_16x16x32_bf16 v[112:115], v[196:199], v[204:207], v[112:115]
	v_mfma_f32_16x16x32_bf16 v[100:103], v[188:191], v[212:215], v[100:103]
	v_mfma_f32_16x16x32_bf16 v[96:99], v[196:199], v[212:215], v[96:99]
	v_mfma_f32_16x16x32_bf16 v[84:87], v[188:191], v[220:223], v[84:87]
	v_mfma_f32_16x16x32_bf16 v[80:83], v[196:199], v[220:223], v[80:83]
	v_mfma_f32_16x16x32_bf16 v[72:75], v[188:191], v[228:231], v[72:75]
	v_mfma_f32_16x16x32_bf16 v[68:71], v[196:199], v[228:231], v[68:71]
	s_nop 0
	s_barrier
; #define PG8_STAGE(bufoff, gbase, voff) do { _Pragma("unroll") for (int _i = 0; _i < 2; ++_i) \
;         __builtin_amdgcn_global_load_lds((const unsigned*)((const char*)(gbase) + (voff)[_i]), (PG8_LAS unsigned*)(lds + (bufoff) + ldsw + _i * 8192), 16, 0, 0); } while (0)
; #define PG8_LDA(dst, b, h) do { _Pragma("unroll") for (int m = 0; m < 4; ++m) _Pragma("unroll") for (int k = 0; k < 2; ++k) dst[m][k] = *(const PG8_LAS bf16x8*)(lds + PG8_SA(b, h) + aoff + m * 2048 + k * 1024); } while (0)
; #define PG8_MMA(ai, bj, At, Bt) do { __builtin_amdgcn_s_setprio(1); _Pragma("unroll") for (int m = 0; m < 4; ++m) _Pragma("unroll") for (int n = 0; n < 2; ++n) _Pragma("unroll") for (int k = 0; k < 2; ++k) \
;         acc[ai][bj][m][n] = __builtin_amdgcn_mfma_f32_16x16x32_bf16(Bt[n][k], At[m][k], acc[ai][bj][m][n], 0, 0, 0); __builtin_amdgcn_s_setprio(0); } while (0)
; #define PG8_WAIT_V(n) asm volatile("s_waitcnt vmcnt(" #n ")" ::: "memory")
; #define PG8_WAIT_L(n) asm volatile("s_waitcnt lgkmcnt(" #n ")" ::: "memory")
; #define PG8_BAR __builtin_amdgcn_s_barrier()
; #define PG8_SCHED __builtin_amdgcn_sched_barrier(0)
; template <class Epi, class Sched, bool ALIGN_EPI = GEMM_ALIGN, bool SP2 = GEMM_SP2>
; __device__ __forceinline__ void gemm_phase(PG8_LAS unsigned char* lds, const Gemm g, const Sched& S, const Epi& E, unsigned long long*  , int tid_in) {
;     ...
;         for (int t = 0; t < nt; t += 2) {
;             const bool last = (t == nt - 2);
;             const char* a1 = cA + (size_t)(t + 1) * kstep;
;             const char* a2 = last ? nA : cA + (size_t)(t + 2) * kstep; const char* b2 = last ? nB : cB + (size_t)(t + 2) * kstep;
;             const char* a3 = a2 + kstep; const char* b3 = b2 + kstep;
;             if (last && has_next) S.a_ready(nxt);
;     ...
;             PG8_LDA(At, 1, 1); PG8_STAGE(PG8_SB(1, 0), b3, voffB); PG8_STAGE(PG8_SB(1, 1), b3 + hstep, voffB); PG8_STAGE(PG8_SA(1, 0), a3, voffA);
;             PG8_WAIT_V(8); PG8_WAIT_L(0); PG8_BAR; PG8_MMA(1, 0, At, B0); PG8_MMA(1, 1, At, B1); PG8_BAR; PG8_SCHED;
	s_add_i32 s28, s72, s36
	v_lshl_add_u64 v[168:169], v[168:169], 0, s[82:83]
	s_mov_b32 m0, s28
	ds_read_b128 v[200:203], v172 offset:49152
	ds_read_b128 v[204:207], v172 offset:50176
	ds_read_b128 v[208:211], v172 offset:51200
	ds_read_b128 v[212:215], v172 offset:52224
	ds_read_b128 v[216:219], v172 offset:53248
	ds_read_b128 v[220:223], v172 offset:54272
	ds_read_b128 v[224:227], v172 offset:55296
	ds_read_b128 v[228:231], v172 offset:56320
	global_load_lds_dwordx4 v[168:169], off
	s_add_i32 m0, s28, 0x2000
	s_add_u32 s26, s26, 0x40080
	v_lshl_add_u64 v[168:169], v[174:175], 0, s[82:83]
	s_addc_u32 s27, s27, 0
	s_add_i32 s28, s73, s36
	global_load_lds_dwordx4 v[168:169], off
	v_lshl_add_u64 v[168:169], s[26:27], 0, v[10:11]
	s_mov_b32 m0, s28
	s_nop 0
	global_load_lds_dwordx4 v[168:169], off
	v_lshl_add_u64 v[168:169], s[26:27], 0, v[8:9]
	s_add_i32 m0, s28, 0x2000
	s_nop 0
	global_load_lds_dwordx4 v[168:169], off
	v_lshl_add_u64 v[168:169], v[232:233], 0, s[82:83]
	s_mov_b32 m0, s61
	s_nop 0
	global_load_lds_dwordx4 v[168:169], off
	v_lshl_add_u64 v[168:169], v[234:235], 0, s[82:83]
	s_mov_b32 m0, s62
	s_nop 0
	global_load_lds_dwordx4 v[168:169], off
	s_waitcnt vmcnt(8)
	s_waitcnt lgkmcnt(0)
	s_barrier
	s_nop 0
	s_waitcnt lgkmcnt(0)
	v_mfma_f32_16x16x32_bf16 v[64:67], v[116:119], v[200:203], v[64:67]
	v_mfma_f32_16x16x32_bf16 v[60:63], v[132:135], v[200:203], v[60:63]
	v_mfma_f32_16x16x32_bf16 v[52:55], v[116:119], v[208:211], v[52:55]
	v_mfma_f32_16x16x32_bf16 v[44:47], v[132:135], v[208:211], v[44:47]
	v_mfma_f32_16x16x32_bf16 v[36:39], v[116:119], v[216:219], v[36:39]
	v_mfma_f32_16x16x32_bf16 v[28:31], v[132:135], v[216:219], v[28:31]
	v_mfma_f32_16x16x32_bf16 v[20:23], v[116:119], v[224:227], v[20:23]
	v_mfma_f32_16x16x32_bf16 v[12:15], v[132:135], v[224:227], v[12:15]
	v_mfma_f32_16x16x32_bf16 v[64:67], v[120:123], v[204:207], v[64:67]
	v_mfma_f32_16x16x32_bf16 v[60:63], v[136:139], v[204:207], v[60:63]
	v_mfma_f32_16x16x32_bf16 v[52:55], v[120:123], v[212:215], v[52:55]
	v_mfma_f32_16x16x32_bf16 v[44:47], v[136:139], v[212:215], v[44:47]
	v_mfma_f32_16x16x32_bf16 v[36:39], v[120:123], v[220:223], v[36:39]
	v_mfma_f32_16x16x32_bf16 v[28:31], v[136:139], v[220:223], v[28:31]
	v_mfma_f32_16x16x32_bf16 v[20:23], v[120:123], v[228:231], v[20:23]
	v_mfma_f32_16x16x32_bf16 v[12:15], v[136:139], v[228:231], v[12:15]
	s_nop 0
	s_nop 0
	v_mfma_f32_16x16x32_bf16 v[56:59], v[164:167], v[200:203], v[56:59]
	v_mfma_f32_16x16x32_bf16 v[48:51], v[192:195], v[200:203], v[48:51]
	v_mfma_f32_16x16x32_bf16 v[40:43], v[164:167], v[208:211], v[40:43]
	v_mfma_f32_16x16x32_bf16 v[32:35], v[192:195], v[208:211], v[32:35]
	v_mfma_f32_16x16x32_bf16 v[24:27], v[164:167], v[216:219], v[24:27]
	v_mfma_f32_16x16x32_bf16 v[16:19], v[192:195], v[216:219], v[16:19]
	v_mfma_f32_16x16x32_bf16 v[4:7], v[164:167], v[224:227], v[4:7]
	v_mfma_f32_16x16x32_bf16 v[0:3], v[192:195], v[224:227], v[0:3]
	v_mfma_f32_16x16x32_bf16 v[56:59], v[188:191], v[204:207], v[56:59]
	v_mfma_f32_16x16x32_bf16 v[48:51], v[196:199], v[204:207], v[48:51]
	v_mfma_f32_16x16x32_bf16 v[40:43], v[188:191], v[212:215], v[40:43]
	v_mfma_f32_16x16x32_bf16 v[32:35], v[196:199], v[212:215], v[32:35]
	v_mfma_f32_16x16x32_bf16 v[24:27], v[188:191], v[220:223], v[24:27]
	v_mfma_f32_16x16x32_bf16 v[16:19], v[196:199], v[220:223], v[16:19]
	v_mfma_f32_16x16x32_bf16 v[4:7], v[188:191], v[228:231], v[4:7]
	v_mfma_f32_16x16x32_bf16 v[0:3], v[196:199], v[228:231], v[0:3]
	s_nop 0
	s_barrier
	s_add_i32 s71, s71, 2
	s_add_u32 s69, s69, 0x100
	s_addc_u32 s70, s70, 0
	s_add_u32 s24, s24, 0x100
	s_addc_u32 s25, s25, 0
	s_cmp_gt_u32 s71, 13
	s_cbranch_scc0 .LBB0_1074
	s_setprio 0
	s_and_b64 vcc, exec, s[14:15]
	s_cbranch_vccz .LBB0_1077
	s_barrier

; #define PG8_WAIT_V(n) asm volatile("s_waitcnt vmcnt(" #n ")" ::: "memory")
; template <class Epi, class Sched, bool ALIGN_EPI = GEMM_ALIGN, bool SP2 = GEMM_SP2>
; __device__ __forceinline__ void gemm_phase(PG8_LAS unsigned char* lds, const Gemm g, const Sched& S, const Epi& E, unsigned long long*  , int tid_in) {
;     ...
;     f32x4 acc[2][2][4][2];
; #pragma unroll
;     for (int a = 0; a < 2; ++a)
; #pragma unroll
;         for (int b = 0; b < 2; ++b)
; #pragma unroll
;             for (int m = 0; m < 4; ++m)
; #pragma unroll
;                 for (int n = 0; n < 2; ++n) acc[a][b][m][n] = (f32x4){0.f, 0.f, 0.f, 0.f};
;     bf16x8 At[4][2], B0[2][2], B1[2][2];
;     const char* cA = (const char*)g.A + (size_t)cur.pm * tstep; const char* cB = (const char*)g.Bt + (size_t)cur.pn * tstep;
;     S.a_ready(cur);
;     if constexpr (SP2) {
;         PG8_STAGE(PG8_SB(0, 0), cB, voffB); PG8_STAGE(PG8_SB(0, 1), cB + hstep, voffB); PG8_STAGE(PG8_SA(0, 0), cA, voffA); PG8_STAGE(PG8_SA(0, 1), cA + hstep, voffA);
;         if (wr == 1) PG8_BAR;
;         PG8_WAIT_V(2); PG8_BAR;
;         PG8_STAGE(PG8_SB(1, 0), cB + kstep, voffB); PG8_STAGE(PG8_SA(1, 0), cA + kstep, voffA); PG8_STAGE(PG8_SB(1, 1), cB + hstep + kstep, voffB);
;         PG8_WAIT_V(6); PG8_BAR;
;     } else {
;         PG8_STAGE(PG8_SB(0, 0), cB, voffB); PG8_STAGE(PG8_SA(0, 0), cA, voffA); PG8_STAGE(PG8_SB(0, 1), cB + hstep, voffB); PG8_STAGE(PG8_SA(0, 1), cA + hstep, voffA);
;         if (wr == 1) PG8_BAR;
;         PG8_WAIT_V(4); PG8_BAR;
;         PG8_STAGE(PG8_SB(1, 0), cB + kstep, voffB); PG8_STAGE(PG8_SA(1, 0), cA + kstep, voffA); PG8_STAGE(PG8_SB(1, 1), cB + hstep + kstep, voffB);
;         PG8_WAIT_V(6); PG8_BAR;
;     }
;     for (;;) {
;         const bool has_next = S.next(ui + 1, nxt);
;         const char* nA = has_next ? (const char*)g.A + (size_t)nxt.pm * tstep : cA; const char* nB = has_next ? (const char*)g.Bt + (size_t)nxt.pn * tstep : cB;
;         for (int t = 0; t < nt; t += 2) {
;             const bool last = (t == nt - 2);
;             const char* a1 = cA + (size_t)(t + 1) * kstep;
;             const char* a2 = last ? nA : cA + (size_t)(t + 2) * kstep; const char* b2 = last ? nB : cB + (size_t)(t + 2) * kstep;
;             const char* a3 = a2 + kstep; const char* b3 = b2 + kstep;
;             if (last && has_next) S.a_ready(nxt);
;             if constexpr (SP2) {
.LBB0_1193:
	s_ashr_i32 s19, s18, 31
	s_lshl_b64 s[20:21], s[18:19], 19
	s_add_u32 s20, s30, s20
	s_addc_u32 s21, s31, s21
	s_and_b64 s[22:23], s[6:7], exec
	s_cselect_b32 s19, s21, s27
	s_cselect_b32 s62, s20, s26
	s_ashr_i32 s17, s16, 31
	s_lshl_b64 s[22:23], s[16:17], 19
	s_add_u32 s22, s2, s22
	s_addc_u32 s23, s3, s23
	s_and_b64 s[28:29], s[6:7], exec
	s_cselect_b32 s17, s23, s25
	s_cselect_b32 s63, s22, s24
	s_add_u32 s64, s24, 0x100
	s_addc_u32 s66, s25, 0
	s_add_u32 s24, s26, 0x40080
	v_mov_b32_e32 v0, 0
	s_addc_u32 s25, s27, 0
	s_mov_b32 s67, -2
	v_mov_b32_e32 v1, v0
	v_mov_b32_e32 v2, v0
	v_mov_b32_e32 v3, v0
	v_mov_b32_e32 v4, v0
	v_mov_b32_e32 v5, v0
	v_mov_b32_e32 v6, v0
	v_mov_b32_e32 v7, v0
	v_mov_b32_e32 v20, v0
	v_mov_b32_e32 v21, v0
	v_mov_b32_e32 v22, v0
	v_mov_b32_e32 v23, v0
	v_mov_b32_e32 v24, v0
	v_mov_b32_e32 v25, v0
	v_mov_b32_e32 v26, v0
	v_mov_b32_e32 v27, v0
	v_mov_b32_e32 v36, v0
	v_mov_b32_e32 v37, v0
	v_mov_b32_e32 v38, v0
	v_mov_b32_e32 v39, v0
	v_mov_b32_e32 v40, v0
	v_mov_b32_e32 v41, v0
	v_mov_b32_e32 v42, v0
	v_mov_b32_e32 v43, v0
	v_mov_b32_e32 v52, v0
	v_mov_b32_e32 v53, v0
	v_mov_b32_e32 v54, v0
	v_mov_b32_e32 v55, v0
	v_mov_b32_e32 v56, v0
	v_mov_b32_e32 v57, v0
	v_mov_b32_e32 v58, v0
	v_mov_b32_e32 v59, v0
	v_mov_b32_e32 v12, v0
	v_mov_b32_e32 v13, v0
	v_mov_b32_e32 v14, v0
	v_mov_b32_e32 v15, v0
	v_mov_b32_e32 v16, v0
	v_mov_b32_e32 v17, v0
	v_mov_b32_e32 v18, v0
	v_mov_b32_e32 v19, v0
	v_mov_b32_e32 v28, v0
	v_mov_b32_e32 v29, v0
	v_mov_b32_e32 v30, v0
	v_mov_b32_e32 v31, v0
	v_mov_b32_e32 v32, v0
	v_mov_b32_e32 v33, v0
	v_mov_b32_e32 v34, v0
	v_mov_b32_e32 v35, v0
	v_mov_b32_e32 v44, v0
	v_mov_b32_e32 v45, v0
	v_mov_b32_e32 v46, v0
	v_mov_b32_e32 v47, v0
	v_mov_b32_e32 v48, v0
	v_mov_b32_e32 v49, v0
	v_mov_b32_e32 v50, v0
	v_mov_b32_e32 v51, v0
	v_mov_b32_e32 v60, v0
	v_mov_b32_e32 v61, v0
	v_mov_b32_e32 v62, v0
	v_mov_b32_e32 v63, v0
	v_mov_b32_e32 v64, v0
	v_mov_b32_e32 v65, v0
	v_mov_b32_e32 v66, v0
	v_mov_b32_e32 v67, v0
	v_mov_b32_e32 v68, v0
	v_mov_b32_e32 v69, v0
	v_mov_b32_e32 v70, v0
	v_mov_b32_e32 v71, v0
	v_mov_b32_e32 v72, v0
	v_mov_b32_e32 v73, v0
	v_mov_b32_e32 v74, v0
	v_mov_b32_e32 v75, v0
	v_mov_b32_e32 v84, v0
	v_mov_b32_e32 v85, v0
	v_mov_b32_e32 v86, v0
	v_mov_b32_e32 v87, v0
	v_mov_b32_e32 v88, v0
	v_mov_b32_e32 v89, v0
	v_mov_b32_e32 v90, v0
	v_mov_b32_e32 v91, v0
	v_mov_b32_e32 v100, v0
	v_mov_b32_e32 v101, v0
	v_mov_b32_e32 v102, v0
	v_mov_b32_e32 v103, v0
	v_mov_b32_e32 v104, v0
	v_mov_b32_e32 v105, v0
	v_mov_b32_e32 v106, v0
	v_mov_b32_e32 v107, v0
	v_mov_b32_e32 v116, v0
	v_mov_b32_e32 v117, v0
	v_mov_b32_e32 v118, v0
	v_mov_b32_e32 v119, v0
	v_mov_b32_e32 v120, v0
	v_mov_b32_e32 v121, v0
	v_mov_b32_e32 v122, v0
	v_mov_b32_e32 v123, v0
	v_mov_b32_e32 v76, v0
	v_mov_b32_e32 v77, v0
	v_mov_b32_e32 v78, v0
	v_mov_b32_e32 v79, v0
	v_mov_b32_e32 v80, v0
	v_mov_b32_e32 v81, v0
	v_mov_b32_e32 v82, v0
	v_mov_b32_e32 v83, v0
	v_mov_b32_e32 v92, v0
	v_mov_b32_e32 v93, v0
	v_mov_b32_e32 v94, v0
	v_mov_b32_e32 v95, v0
	v_mov_b32_e32 v96, v0
	v_mov_b32_e32 v97, v0
	v_mov_b32_e32 v98, v0
	v_mov_b32_e32 v99, v0
	v_mov_b32_e32 v108, v0
	v_mov_b32_e32 v109, v0
	v_mov_b32_e32 v110, v0
	v_mov_b32_e32 v111, v0
	v_mov_b32_e32 v112, v0
	v_mov_b32_e32 v113, v0
	v_mov_b32_e32 v114, v0
	v_mov_b32_e32 v115, v0
	v_mov_b32_e32 v124, v0
	v_mov_b32_e32 v125, v0
	v_mov_b32_e32 v126, v0
	v_mov_b32_e32 v127, v0
	v_mov_b32_e32 v128, v0
	v_mov_b32_e32 v129, v0
	v_mov_b32_e32 v130, v0
	v_mov_b32_e32 v131, v0
	s_and_b64 vcc, exec, s[14:15]
	s_cbranch_vccnz .Lprio_1194
	s_setprio 1
.Lprio_1194:
.LBB0_1194:
	s_add_u32 s26, s24, 0xfffc0080
	s_addc_u32 s27, s25, -1
	s_add_i32 s68, 0, 0x10000
	s_cmp_eq_u32 s67, 12
	s_cselect_b32 s29, s19, s27
	s_cselect_b32 s28, s62, s26
	v_add_u32_e32 v140, s68, v142
	s_cselect_b32 s27, s17, s66
	s_cselect_b32 s26, s63, s64
	s_add_i32 s70, 0, 0x14000
	ds_read_b128 v[156:159], v140
	ds_read_b128 v[160:163], v140 offset:1024
	ds_read_b128 v[164:167], v140 offset:2048
	ds_read_b128 v[168:171], v140 offset:3072
	v_add_u32_e32 v140, s70, v142
	ds_read_b128 v[172:175], v140
	ds_read_b128 v[188:191], v140 offset:1024
	ds_read_b128 v[192:195], v140 offset:2048
	ds_read_b128 v[196:199], v140 offset:3072
	v_lshl_add_u64 v[140:141], s[24:25], 0, v[138:139]
	s_add_i32 m0, s35, 0xc000
	ds_read_b128 v[200:203], v146
	ds_read_b128 v[204:207], v146 offset:1024
	ds_read_b128 v[208:211], v146 offset:2048
	ds_read_b128 v[212:215], v146 offset:3072
	ds_read_b128 v[216:219], v146 offset:4096
	ds_read_b128 v[220:223], v146 offset:5120
	ds_read_b128 v[224:227], v146 offset:6144
	ds_read_b128 v[228:231], v146 offset:7168
	global_load_lds_dwordx4 v[140:141], off
	v_lshl_add_u64 v[140:141], s[24:25], 0, v[136:137]
	s_add_i32 m0, s35, 0xe000
	s_nop 0
	global_load_lds_dwordx4 v[140:141], off
	s_waitcnt vmcnt(8)
	s_waitcnt lgkmcnt(0)
	s_barrier
; #define PG8_STAGE(bufoff, gbase, voff) do { _Pragma("unroll") for (int _i = 0; _i < 2; ++_i) \
;         __builtin_amdgcn_global_load_lds((const unsigned*)((const char*)(gbase) + (voff)[_i]), (PG8_LAS unsigned*)(lds + (bufoff) + ldsw + _i * 8192), 16, 0, 0); } while (0)
; #define PG8_LDA(dst, b, h) do { _Pragma("unroll") for (int m = 0; m < 4; ++m) _Pragma("unroll") for (int k = 0; k < 2; ++k) dst[m][k] = *(const PG8_LAS bf16x8*)(lds + PG8_SA(b, h) + aoff + m * 2048 + k * 1024); } while (0)
; #define PG8_MMA(ai, bj, At, Bt) do { __builtin_amdgcn_s_setprio(1); _Pragma("unroll") for (int m = 0; m < 4; ++m) _Pragma("unroll") for (int n = 0; n < 2; ++n) _Pragma("unroll") for (int k = 0; k < 2; ++k) \
;         acc[ai][bj][m][n] = __builtin_amdgcn_mfma_f32_16x16x32_bf16(Bt[n][k], At[m][k], acc[ai][bj][m][n], 0, 0, 0); __builtin_amdgcn_s_setprio(0); } while (0)
; #define PG8_WAIT_V(n) asm volatile("s_waitcnt vmcnt(" #n ")" ::: "memory")
; #define PG8_WAIT_L(n) asm volatile("s_waitcnt lgkmcnt(" #n ")" ::: "memory")
; #define PG8_BAR __builtin_amdgcn_s_barrier()
; #define PG8_SCHED __builtin_amdgcn_sched_barrier(0)
; template <class Epi, class Sched, bool ALIGN_EPI = GEMM_ALIGN, bool SP2 = GEMM_SP2>
; __device__ __forceinline__ void gemm_phase(PG8_LAS unsigned char* lds, const Gemm g, const Sched& S, const Epi& E, unsigned long long*  , int tid_in) {
;     ...
;             PG8_WAIT_V(8); PG8_WAIT_L(0); PG8_BAR; PG8_MMA(0, 0, At, B0); PG8_MMA(0, 1, At, B1); PG8_BAR; PG8_SCHED;
;             PG8_LDA(At, 0, 1); PG8_STAGE(PG8_SB(0, 0), b2, voffB); PG8_STAGE(PG8_SB(0, 1), b2 + hstep, voffB); PG8_STAGE(PG8_SA(0, 0), a2, voffA);
;             PG8_WAIT_V(8); PG8_WAIT_L(0); PG8_BAR; PG8_MMA(1, 0, At, B0); PG8_MMA(1, 1, At, B1); PG8_BAR; PG8_SCHED;
	s_nop 0
	s_waitcnt lgkmcnt(0)
	v_mfma_f32_16x16x32_bf16 v[128:131], v[156:159], v[200:203], v[128:131]
	v_mfma_f32_16x16x32_bf16 v[124:127], v[164:167], v[200:203], v[124:127]
	v_mfma_f32_16x16x32_bf16 v[112:115], v[156:159], v[208:211], v[112:115]
	v_mfma_f32_16x16x32_bf16 v[108:111], v[164:167], v[208:211], v[108:111]
	v_mfma_f32_16x16x32_bf16 v[96:99], v[156:159], v[216:219], v[96:99]
	v_mfma_f32_16x16x32_bf16 v[92:95], v[164:167], v[216:219], v[92:95]
	v_mfma_f32_16x16x32_bf16 v[80:83], v[156:159], v[224:227], v[80:83]
	v_mfma_f32_16x16x32_bf16 v[76:79], v[164:167], v[224:227], v[76:79]
	v_mfma_f32_16x16x32_bf16 v[128:131], v[160:163], v[204:207], v[128:131]
	v_mfma_f32_16x16x32_bf16 v[124:127], v[168:171], v[204:207], v[124:127]
	v_mfma_f32_16x16x32_bf16 v[112:115], v[160:163], v[212:215], v[112:115]
	v_mfma_f32_16x16x32_bf16 v[108:111], v[168:171], v[212:215], v[108:111]
	v_mfma_f32_16x16x32_bf16 v[96:99], v[160:163], v[220:223], v[96:99]
	v_mfma_f32_16x16x32_bf16 v[92:95], v[168:171], v[220:223], v[92:95]
	v_mfma_f32_16x16x32_bf16 v[80:83], v[160:163], v[228:231], v[80:83]
	v_mfma_f32_16x16x32_bf16 v[76:79], v[168:171], v[228:231], v[76:79]
	s_nop 0
	s_nop 0
	v_mfma_f32_16x16x32_bf16 v[120:123], v[172:175], v[200:203], v[120:123]
	v_mfma_f32_16x16x32_bf16 v[116:119], v[192:195], v[200:203], v[116:119]
	v_mfma_f32_16x16x32_bf16 v[104:107], v[172:175], v[208:211], v[104:107]
	v_mfma_f32_16x16x32_bf16 v[100:103], v[192:195], v[208:211], v[100:103]
	v_mfma_f32_16x16x32_bf16 v[88:91], v[172:175], v[216:219], v[88:91]
	v_mfma_f32_16x16x32_bf16 v[84:87], v[192:195], v[216:219], v[84:87]
	v_mfma_f32_16x16x32_bf16 v[72:75], v[172:175], v[224:227], v[72:75]
	v_mfma_f32_16x16x32_bf16 v[68:71], v[192:195], v[224:227], v[68:71]
	v_mfma_f32_16x16x32_bf16 v[120:123], v[188:191], v[204:207], v[120:123]
	v_mfma_f32_16x16x32_bf16 v[116:119], v[196:199], v[204:207], v[116:119]
	v_mfma_f32_16x16x32_bf16 v[104:107], v[188:191], v[212:215], v[104:107]
	v_mfma_f32_16x16x32_bf16 v[100:103], v[196:199], v[212:215], v[100:103]
	v_mfma_f32_16x16x32_bf16 v[88:91], v[188:191], v[220:223], v[88:91]
	v_mfma_f32_16x16x32_bf16 v[84:87], v[196:199], v[220:223], v[84:87]
	v_mfma_f32_16x16x32_bf16 v[72:75], v[188:191], v[228:231], v[72:75]
	v_mfma_f32_16x16x32_bf16 v[68:71], v[196:199], v[228:231], v[68:71]
	s_nop 0
	s_barrier
	s_add_i32 s68, s68, s34
	v_lshl_add_u64 v[140:141], s[26:27], 0, v[10:11]
	s_mov_b32 m0, s68
	ds_read_b128 v[200:203], v146 offset:16384
	ds_read_b128 v[204:207], v146 offset:17408
	ds_read_b128 v[208:211], v146 offset:18432
	ds_read_b128 v[212:215], v146 offset:19456
	ds_read_b128 v[216:219], v146 offset:20480
	ds_read_b128 v[220:223], v146 offset:21504
	ds_read_b128 v[224:227], v146 offset:22528
	ds_read_b128 v[228:231], v146 offset:23552
	global_load_lds_dwordx4 v[140:141], off
	s_add_i32 m0, s68, 0x2000
	s_add_u32 s68, s26, 0x40000
	v_lshl_add_u64 v[232:233], s[26:27], 0, v[8:9]
	s_addc_u32 s69, s27, 0
	s_add_i32 s70, s70, s34
	global_load_lds_dwordx4 v[232:233], off
	v_lshl_add_u64 v[234:235], s[68:69], 0, v[10:11]
	s_mov_b32 m0, s70
	v_lshl_add_u64 v[236:237], s[28:29], 0, v[132:133]
	global_load_lds_dwordx4 v[234:235], off
	v_lshl_add_u64 v[234:235], s[68:69], 0, v[8:9]
	s_add_i32 m0, s70, 0x2000
	s_nop 0
	global_load_lds_dwordx4 v[234:235], off
	v_lshl_add_u64 v[234:235], s[28:29], 0, v[134:135]
	s_mov_b32 m0, s35
	s_nop 0
	global_load_lds_dwordx4 v[234:235], off
	s_mov_b32 m0, s36
	s_nop 0
	global_load_lds_dwordx4 v[236:237], off
	s_waitcnt vmcnt(8)
	s_waitcnt lgkmcnt(0)
	s_barrier
	s_nop 0
	s_waitcnt lgkmcnt(0)
	v_mfma_f32_16x16x32_bf16 v[64:67], v[156:159], v[200:203], v[64:67]
	v_mfma_f32_16x16x32_bf16 v[60:63], v[164:167], v[200:203], v[60:63]
	v_mfma_f32_16x16x32_bf16 v[48:51], v[156:159], v[208:211], v[48:51]
	v_mfma_f32_16x16x32_bf16 v[44:47], v[164:167], v[208:211], v[44:47]
	v_mfma_f32_16x16x32_bf16 v[32:35], v[156:159], v[216:219], v[32:35]
	v_mfma_f32_16x16x32_bf16 v[28:31], v[164:167], v[216:219], v[28:31]
	v_mfma_f32_16x16x32_bf16 v[16:19], v[156:159], v[224:227], v[16:19]
	v_mfma_f32_16x16x32_bf16 v[12:15], v[164:167], v[224:227], v[12:15]
	v_mfma_f32_16x16x32_bf16 v[64:67], v[160:163], v[204:207], v[64:67]
	v_mfma_f32_16x16x32_bf16 v[60:63], v[168:171], v[204:207], v[60:63]
	v_mfma_f32_16x16x32_bf16 v[48:51], v[160:163], v[212:215], v[48:51]
	v_mfma_f32_16x16x32_bf16 v[44:47], v[168:171], v[212:215], v[44:47]
	v_mfma_f32_16x16x32_bf16 v[32:35], v[160:163], v[220:223], v[32:35]
	v_mfma_f32_16x16x32_bf16 v[28:31], v[168:171], v[220:223], v[28:31]
	v_mfma_f32_16x16x32_bf16 v[16:19], v[160:163], v[228:231], v[16:19]
	v_mfma_f32_16x16x32_bf16 v[12:15], v[168:171], v[228:231], v[12:15]
	s_nop 0
	s_nop 0
	v_mfma_f32_16x16x32_bf16 v[56:59], v[172:175], v[200:203], v[56:59]
	v_mfma_f32_16x16x32_bf16 v[52:55], v[192:195], v[200:203], v[52:55]
	v_mfma_f32_16x16x32_bf16 v[40:43], v[172:175], v[208:211], v[40:43]
	v_mfma_f32_16x16x32_bf16 v[36:39], v[192:195], v[208:211], v[36:39]
	v_mfma_f32_16x16x32_bf16 v[24:27], v[172:175], v[216:219], v[24:27]
	v_mfma_f32_16x16x32_bf16 v[20:23], v[192:195], v[216:219], v[20:23]
	v_mfma_f32_16x16x32_bf16 v[4:7], v[172:175], v[224:227], v[4:7]
	v_mfma_f32_16x16x32_bf16 v[0:3], v[192:195], v[224:227], v[0:3]
	v_mfma_f32_16x16x32_bf16 v[56:59], v[188:191], v[204:207], v[56:59]
	v_mfma_f32_16x16x32_bf16 v[52:55], v[196:199], v[204:207], v[52:55]
	v_mfma_f32_16x16x32_bf16 v[40:43], v[188:191], v[212:215], v[40:43]
	v_mfma_f32_16x16x32_bf16 v[36:39], v[196:199], v[212:215], v[36:39]
	v_mfma_f32_16x16x32_bf16 v[24:27], v[188:191], v[220:223], v[24:27]
	v_mfma_f32_16x16x32_bf16 v[20:23], v[196:199], v[220:223], v[20:23]
	v_mfma_f32_16x16x32_bf16 v[4:7], v[188:191], v[228:231], v[4:7]
	v_mfma_f32_16x16x32_bf16 v[0:3], v[196:199], v[228:231], v[0:3]
	s_nop 0
	s_barrier
; #define PG8_STAGE(bufoff, gbase, voff) do { _Pragma("unroll") for (int _i = 0; _i < 2; ++_i) \
;         __builtin_amdgcn_global_load_lds((const unsigned*)((const char*)(gbase) + (voff)[_i]), (PG8_LAS unsigned*)(lds + (bufoff) + ldsw + _i * 8192), 16, 0, 0); } while (0)
; #define PG8_LDA(dst, b, h) do { _Pragma("unroll") for (int m = 0; m < 4; ++m) _Pragma("unroll") for (int k = 0; k < 2; ++k) dst[m][k] = *(const PG8_LAS bf16x8*)(lds + PG8_SA(b, h) + aoff + m * 2048 + k * 1024); } while (0)
; #define PG8_LDB(dst, b, h) do { _Pragma("unroll") for (int n = 0; n < 2; ++n) _Pragma("unroll") for (int k = 0; k < 2; ++k) dst[n][k] = *(const PG8_LAS bf16x8*)(lds + PG8_SB(b, h) + boff + n * 2048 + k * 1024); } while (0)
; #define PG8_MMA(ai, bj, At, Bt) do { __builtin_amdgcn_s_setprio(1); _Pragma("unroll") for (int m = 0; m < 4; ++m) _Pragma("unroll") for (int n = 0; n < 2; ++n) _Pragma("unroll") for (int k = 0; k < 2; ++k) \
;         acc[ai][bj][m][n] = __builtin_amdgcn_mfma_f32_16x16x32_bf16(Bt[n][k], At[m][k], acc[ai][bj][m][n], 0, 0, 0); __builtin_amdgcn_s_setprio(0); } while (0)
; #define PG8_WAIT_V(n) asm volatile("s_waitcnt vmcnt(" #n ")" ::: "memory")
; #define PG8_WAIT_L(n) asm volatile("s_waitcnt lgkmcnt(" #n ")" ::: "memory")
; #define PG8_BAR __builtin_amdgcn_s_barrier()
; #define PG8_SCHED __builtin_amdgcn_sched_barrier(0)
; template <class Epi, class Sched, bool ALIGN_EPI = GEMM_ALIGN, bool SP2 = GEMM_SP2>
; __device__ __forceinline__ void gemm_phase(PG8_LAS unsigned char* lds, const Gemm g, const Sched& S, const Epi& E, unsigned long long*  , int tid_in) {
;     ...
;             PG8_LDB(B0, 1, 0); PG8_LDB(B1, 1, 1); PG8_SCHED; PG8_LDA(At, 1, 0); PG8_STAGE(PG8_SA(0, 1), a2 + hstep, voffA);
;             PG8_WAIT_V(8); PG8_WAIT_L(0); PG8_BAR; PG8_MMA(0, 0, At, B0); PG8_MMA(0, 1, At, B1); PG8_BAR; PG8_SCHED;
	s_add_i32 s68, 0, 0x18000
	v_add_u32_e32 v147, s68, v142
	s_add_i32 s69, 0, 0x1c000
	ds_read_b128 v[156:159], v147
	ds_read_b128 v[160:163], v147 offset:1024
	ds_read_b128 v[164:167], v147 offset:2048
	ds_read_b128 v[168:171], v147 offset:3072
	v_add_u32_e32 v147, s69, v142
	ds_read_b128 v[172:175], v147
	ds_read_b128 v[188:191], v147 offset:1024
	ds_read_b128 v[192:195], v147 offset:2048
	ds_read_b128 v[196:199], v147 offset:3072
	s_add_u32 s28, s28, 0x40000
	s_addc_u32 s29, s29, 0
	s_mov_b32 m0, s37
	v_lshl_add_u64 v[238:239], s[28:29], 0, v[134:135]
	ds_read_b128 v[200:203], v146 offset:32768
	ds_read_b128 v[204:207], v146 offset:33792
	ds_read_b128 v[208:211], v146 offset:34816
	ds_read_b128 v[212:215], v146 offset:35840
	ds_read_b128 v[216:219], v146 offset:36864
	ds_read_b128 v[220:223], v146 offset:37888
	ds_read_b128 v[224:227], v146 offset:38912
	ds_read_b128 v[228:231], v146 offset:39936
	global_load_lds_dwordx4 v[238:239], off
	v_lshl_add_u64 v[238:239], s[28:29], 0, v[132:133]
	s_mov_b32 m0, s50
	s_nop 0
	global_load_lds_dwordx4 v[238:239], off
	s_waitcnt vmcnt(8)
	s_waitcnt lgkmcnt(0)
	s_barrier
	s_nop 0
	s_waitcnt lgkmcnt(0)
	v_mfma_f32_16x16x32_bf16 v[128:131], v[156:159], v[200:203], v[128:131]
	v_mfma_f32_16x16x32_bf16 v[124:127], v[164:167], v[200:203], v[124:127]
	v_mfma_f32_16x16x32_bf16 v[112:115], v[156:159], v[208:211], v[112:115]
	v_mfma_f32_16x16x32_bf16 v[108:111], v[164:167], v[208:211], v[108:111]
	v_mfma_f32_16x16x32_bf16 v[96:99], v[156:159], v[216:219], v[96:99]
	v_mfma_f32_16x16x32_bf16 v[92:95], v[164:167], v[216:219], v[92:95]
	v_mfma_f32_16x16x32_bf16 v[80:83], v[156:159], v[224:227], v[80:83]
	v_mfma_f32_16x16x32_bf16 v[76:79], v[164:167], v[224:227], v[76:79]
	v_mfma_f32_16x16x32_bf16 v[128:131], v[160:163], v[204:207], v[128:131]
	v_mfma_f32_16x16x32_bf16 v[124:127], v[168:171], v[204:207], v[124:127]
	v_mfma_f32_16x16x32_bf16 v[112:115], v[160:163], v[212:215], v[112:115]
	v_mfma_f32_16x16x32_bf16 v[108:111], v[168:171], v[212:215], v[108:111]
	v_mfma_f32_16x16x32_bf16 v[96:99], v[160:163], v[220:223], v[96:99]
	v_mfma_f32_16x16x32_bf16 v[92:95], v[168:171], v[220:223], v[92:95]
	v_mfma_f32_16x16x32_bf16 v[80:83], v[160:163], v[228:231], v[80:83]
	v_mfma_f32_16x16x32_bf16 v[76:79], v[168:171], v[228:231], v[76:79]
	s_nop 0
	s_nop 0
	v_mfma_f32_16x16x32_bf16 v[120:123], v[172:175], v[200:203], v[120:123]
	v_mfma_f32_16x16x32_bf16 v[116:119], v[192:195], v[200:203], v[116:119]
	v_mfma_f32_16x16x32_bf16 v[104:107], v[172:175], v[208:211], v[104:107]
	v_mfma_f32_16x16x32_bf16 v[100:103], v[192:195], v[208:211], v[100:103]
	v_mfma_f32_16x16x32_bf16 v[88:91], v[172:175], v[216:219], v[88:91]
	v_mfma_f32_16x16x32_bf16 v[84:87], v[192:195], v[216:219], v[84:87]
	v_mfma_f32_16x16x32_bf16 v[72:75], v[172:175], v[224:227], v[72:75]
	v_mfma_f32_16x16x32_bf16 v[68:71], v[192:195], v[224:227], v[68:71]
	v_mfma_f32_16x16x32_bf16 v[120:123], v[188:191], v[204:207], v[120:123]
	v_mfma_f32_16x16x32_bf16 v[116:119], v[196:199], v[204:207], v[116:119]
	v_mfma_f32_16x16x32_bf16 v[104:107], v[188:191], v[212:215], v[104:107]
	v_mfma_f32_16x16x32_bf16 v[100:103], v[196:199], v[212:215], v[100:103]
	v_mfma_f32_16x16x32_bf16 v[88:91], v[188:191], v[220:223], v[88:91]
	v_mfma_f32_16x16x32_bf16 v[84:87], v[196:199], v[220:223], v[84:87]
	v_mfma_f32_16x16x32_bf16 v[72:75], v[188:191], v[228:231], v[72:75]
	v_mfma_f32_16x16x32_bf16 v[68:71], v[196:199], v[228:231], v[68:71]
	s_nop 0
	s_barrier
; #define PG8_STAGE(bufoff, gbase, voff) do { _Pragma("unroll") for (int _i = 0; _i < 2; ++_i) \
;         __builtin_amdgcn_global_load_lds((const unsigned*)((const char*)(gbase) + (voff)[_i]), (PG8_LAS unsigned*)(lds + (bufoff) + ldsw + _i * 8192), 16, 0, 0); } while (0)
; #define PG8_LDA(dst, b, h) do { _Pragma("unroll") for (int m = 0; m < 4; ++m) _Pragma("unroll") for (int k = 0; k < 2; ++k) dst[m][k] = *(const PG8_LAS bf16x8*)(lds + PG8_SA(b, h) + aoff + m * 2048 + k * 1024); } while (0)
; #define PG8_MMA(ai, bj, At, Bt) do { __builtin_amdgcn_s_setprio(1); _Pragma("unroll") for (int m = 0; m < 4; ++m) _Pragma("unroll") for (int n = 0; n < 2; ++n) _Pragma("unroll") for (int k = 0; k < 2; ++k) \
;         acc[ai][bj][m][n] = __builtin_amdgcn_mfma_f32_16x16x32_bf16(Bt[n][k], At[m][k], acc[ai][bj][m][n], 0, 0, 0); __builtin_amdgcn_s_setprio(0); } while (0)
; #define PG8_WAIT_V(n) asm volatile("s_waitcnt vmcnt(" #n ")" ::: "memory")
; #define PG8_WAIT_L(n) asm volatile("s_waitcnt lgkmcnt(" #n ")" ::: "memory")
; #define PG8_BAR __builtin_amdgcn_s_barrier()
; #define PG8_SCHED __builtin_amdgcn_sched_barrier(0)
; template <class Epi, class Sched, bool ALIGN_EPI = GEMM_ALIGN, bool SP2 = GEMM_SP2>
; __device__ __forceinline__ void gemm_phase(PG8_LAS unsigned char* lds, const Gemm g, const Sched& S, const Epi& E, unsigned long long*  , int tid_in) {
;     ...
;         for (int t = 0; t < nt; t += 2) {
;             const bool last = (t == nt - 2);
;             const char* a1 = cA + (size_t)(t + 1) * kstep;
;             const char* a2 = last ? nA : cA + (size_t)(t + 2) * kstep; const char* b2 = last ? nB : cB + (size_t)(t + 2) * kstep;
;             const char* a3 = a2 + kstep; const char* b3 = b2 + kstep;
;             if (last && has_next) S.a_ready(nxt);
;     ...
;             PG8_LDA(At, 1, 1); PG8_STAGE(PG8_SB(1, 0), b3, voffB); PG8_STAGE(PG8_SB(1, 1), b3 + hstep, voffB); PG8_STAGE(PG8_SA(1, 0), a3, voffA);
;             PG8_WAIT_V(8); PG8_WAIT_L(0); PG8_BAR; PG8_MMA(1, 0, At, B0); PG8_MMA(1, 1, At, B1); PG8_BAR; PG8_SCHED;
	s_add_i32 s28, s68, s34
	v_lshl_add_u64 v[140:141], v[140:141], 0, s[82:83]
	s_mov_b32 m0, s28
	ds_read_b128 v[200:203], v146 offset:49152
	ds_read_b128 v[204:207], v146 offset:50176
	ds_read_b128 v[208:211], v146 offset:51200
	ds_read_b128 v[212:215], v146 offset:52224
	ds_read_b128 v[216:219], v146 offset:53248
	ds_read_b128 v[220:223], v146 offset:54272
	ds_read_b128 v[224:227], v146 offset:55296
	ds_read_b128 v[228:231], v146 offset:56320
	global_load_lds_dwordx4 v[140:141], off
	s_add_i32 m0, s28, 0x2000
	s_add_u32 s26, s26, 0x40080
	v_lshl_add_u64 v[140:141], v[232:233], 0, s[82:83]
	s_addc_u32 s27, s27, 0
	s_add_i32 s28, s69, s34
	global_load_lds_dwordx4 v[140:141], off
	v_lshl_add_u64 v[140:141], s[26:27], 0, v[10:11]
	s_mov_b32 m0, s28
	s_nop 0
	global_load_lds_dwordx4 v[140:141], off
	v_lshl_add_u64 v[140:141], s[26:27], 0, v[8:9]
	s_add_i32 m0, s28, 0x2000
	s_nop 0
	global_load_lds_dwordx4 v[140:141], off
	v_lshl_add_u64 v[140:141], v[234:235], 0, s[82:83]
	s_mov_b32 m0, s51
	s_nop 0
	global_load_lds_dwordx4 v[140:141], off
	v_lshl_add_u64 v[140:141], v[236:237], 0, s[82:83]
	s_mov_b32 m0, s58
	s_nop 0
	global_load_lds_dwordx4 v[140:141], off
	s_waitcnt vmcnt(8)
	s_waitcnt lgkmcnt(0)
	s_barrier
	s_nop 0
	s_waitcnt lgkmcnt(0)
	v_mfma_f32_16x16x32_bf16 v[64:67], v[156:159], v[200:203], v[64:67]
	v_mfma_f32_16x16x32_bf16 v[60:63], v[164:167], v[200:203], v[60:63]
	v_mfma_f32_16x16x32_bf16 v[48:51], v[156:159], v[208:211], v[48:51]
	v_mfma_f32_16x16x32_bf16 v[44:47], v[164:167], v[208:211], v[44:47]
	v_mfma_f32_16x16x32_bf16 v[32:35], v[156:159], v[216:219], v[32:35]
	v_mfma_f32_16x16x32_bf16 v[28:31], v[164:167], v[216:219], v[28:31]
	v_mfma_f32_16x16x32_bf16 v[16:19], v[156:159], v[224:227], v[16:19]
	v_mfma_f32_16x16x32_bf16 v[12:15], v[164:167], v[224:227], v[12:15]
	v_mfma_f32_16x16x32_bf16 v[64:67], v[160:163], v[204:207], v[64:67]
	v_mfma_f32_16x16x32_bf16 v[60:63], v[168:171], v[204:207], v[60:63]
	v_mfma_f32_16x16x32_bf16 v[48:51], v[160:163], v[212:215], v[48:51]
	v_mfma_f32_16x16x32_bf16 v[44:47], v[168:171], v[212:215], v[44:47]
	v_mfma_f32_16x16x32_bf16 v[32:35], v[160:163], v[220:223], v[32:35]
	v_mfma_f32_16x16x32_bf16 v[28:31], v[168:171], v[220:223], v[28:31]
	v_mfma_f32_16x16x32_bf16 v[16:19], v[160:163], v[228:231], v[16:19]
	v_mfma_f32_16x16x32_bf16 v[12:15], v[168:171], v[228:231], v[12:15]
	s_nop 0
	s_nop 0
	v_mfma_f32_16x16x32_bf16 v[56:59], v[172:175], v[200:203], v[56:59]
	v_mfma_f32_16x16x32_bf16 v[52:55], v[192:195], v[200:203], v[52:55]
	v_mfma_f32_16x16x32_bf16 v[40:43], v[172:175], v[208:211], v[40:43]
	v_mfma_f32_16x16x32_bf16 v[36:39], v[192:195], v[208:211], v[36:39]
	v_mfma_f32_16x16x32_bf16 v[24:27], v[172:175], v[216:219], v[24:27]
	v_mfma_f32_16x16x32_bf16 v[20:23], v[192:195], v[216:219], v[20:23]
	v_mfma_f32_16x16x32_bf16 v[4:7], v[172:175], v[224:227], v[4:7]
	v_mfma_f32_16x16x32_bf16 v[0:3], v[192:195], v[224:227], v[0:3]
	v_mfma_f32_16x16x32_bf16 v[56:59], v[188:191], v[204:207], v[56:59]
	v_mfma_f32_16x16x32_bf16 v[52:55], v[196:199], v[204:207], v[52:55]
	v_mfma_f32_16x16x32_bf16 v[40:43], v[188:191], v[212:215], v[40:43]
	v_mfma_f32_16x16x32_bf16 v[36:39], v[196:199], v[212:215], v[36:39]
	v_mfma_f32_16x16x32_bf16 v[24:27], v[188:191], v[220:223], v[24:27]
	v_mfma_f32_16x16x32_bf16 v[20:23], v[196:199], v[220:223], v[20:23]
	v_mfma_f32_16x16x32_bf16 v[4:7], v[188:191], v[228:231], v[4:7]
	v_mfma_f32_16x16x32_bf16 v[0:3], v[196:199], v[228:231], v[0:3]
	s_nop 0
	s_barrier
	s_add_i32 s67, s67, 2
	s_add_u32 s64, s64, 0x100
	s_addc_u32 s66, s66, 0
	s_add_u32 s24, s24, 0x100
	s_addc_u32 s25, s25, 0
	s_cmp_gt_u32 s67, 13
	s_cbranch_scc0 .LBB0_1194
	s_setprio 0
	s_and_b64 vcc, exec, s[14:15]
	s_cbranch_vccz .LBB0_1197
	s_barrier

; #define PG8_WAIT_V(n) asm volatile("s_waitcnt vmcnt(" #n ")" ::: "memory")
; template <class Epi, class Sched, bool ALIGN_EPI = GEMM_ALIGN, bool SP2 = GEMM_SP2>
; __device__ __forceinline__ void gemm_phase(PG8_LAS unsigned char* lds, const Gemm g, const Sched& S, const Epi& E, unsigned long long*  , int tid_in) {
;     ...
;     f32x4 acc[2][2][4][2];
; #pragma unroll
;     for (int a = 0; a < 2; ++a)
; #pragma unroll
;         for (int b = 0; b < 2; ++b)
; #pragma unroll
;             for (int m = 0; m < 4; ++m)
; #pragma unroll
;                 for (int n = 0; n < 2; ++n) acc[a][b][m][n] = (f32x4){0.f, 0.f, 0.f, 0.f};
;     bf16x8 At[4][2], B0[2][2], B1[2][2];
;     const char* cA = (const char*)g.A + (size_t)cur.pm * tstep; const char* cB = (const char*)g.Bt + (size_t)cur.pn * tstep;
;     S.a_ready(cur);
;     if constexpr (SP2) {
;         PG8_STAGE(PG8_SB(0, 0), cB, voffB); PG8_STAGE(PG8_SB(0, 1), cB + hstep, voffB); PG8_STAGE(PG8_SA(0, 0), cA, voffA); PG8_STAGE(PG8_SA(0, 1), cA + hstep, voffA);
;         if (wr == 1) PG8_BAR;
;         PG8_WAIT_V(2); PG8_BAR;
;         PG8_STAGE(PG8_SB(1, 0), cB + kstep, voffB); PG8_STAGE(PG8_SA(1, 0), cA + kstep, voffA); PG8_STAGE(PG8_SB(1, 1), cB + hstep + kstep, voffB);
;         PG8_WAIT_V(6); PG8_BAR;
;     } else {
;         PG8_STAGE(PG8_SB(0, 0), cB, voffB); PG8_STAGE(PG8_SA(0, 0), cA, voffA); PG8_STAGE(PG8_SB(0, 1), cB + hstep, voffB); PG8_STAGE(PG8_SA(0, 1), cA + hstep, voffA);
;         if (wr == 1) PG8_BAR;
;         PG8_WAIT_V(4); PG8_BAR;
;         PG8_STAGE(PG8_SB(1, 0), cB + kstep, voffB); PG8_STAGE(PG8_SA(1, 0), cA + kstep, voffA); PG8_STAGE(PG8_SB(1, 1), cB + hstep + kstep, voffB);
;         PG8_WAIT_V(6); PG8_BAR;
;     }
;     for (;;) {
;         const bool has_next = S.next(ui + 1, nxt);
;         const char* nA = has_next ? (const char*)g.A + (size_t)nxt.pm * tstep : cA; const char* nB = has_next ? (const char*)g.Bt + (size_t)nxt.pn * tstep : cB;
;         for (int t = 0; t < nt; t += 2) {
;             const bool last = (t == nt - 2);
;             const char* a1 = cA + (size_t)(t + 1) * kstep;
;             const char* a2 = last ? nA : cA + (size_t)(t + 2) * kstep; const char* b2 = last ? nB : cB + (size_t)(t + 2) * kstep;
;             const char* a3 = a2 + kstep; const char* b3 = b2 + kstep;
;             if (last && has_next) S.a_ready(nxt);
;             if constexpr (SP2) {
.LBB0_1263:
	s_ashr_i32 s15, s14, 31
	s_lshl_b64 s[16:17], s[14:15], 21
	s_add_u32 s16, s28, s16
	s_addc_u32 s17, s29, s17
	s_and_b64 s[18:19], s[0:1], exec
	s_cselect_b32 s15, s17, s23
	s_cselect_b32 s64, s16, s22
	s_ashr_i32 s13, s12, 31
	s_lshl_b64 s[18:19], s[12:13], 21
	s_add_u32 s18, s30, s18
	s_addc_u32 s19, s31, s19
	s_and_b64 s[24:25], s[0:1], exec
	s_cselect_b32 s13, s19, s21
	s_cselect_b32 s66, s18, s20
	s_add_u32 s67, s20, 0x100
	s_addc_u32 s68, s21, 0
	s_add_u32 s20, s22, 0x100080
	v_mov_b32_e32 v0, 0
	s_addc_u32 s21, s23, 0
	s_mov_b32 s69, -2
	v_mov_b32_e32 v1, v0
	v_mov_b32_e32 v2, v0
	v_mov_b32_e32 v3, v0
	v_mov_b32_e32 v4, v0
	v_mov_b32_e32 v5, v0
	v_mov_b32_e32 v6, v0
	v_mov_b32_e32 v7, v0
	v_mov_b32_e32 v16, v0
	v_mov_b32_e32 v17, v0
	v_mov_b32_e32 v18, v0
	v_mov_b32_e32 v19, v0
	v_mov_b32_e32 v24, v0
	v_mov_b32_e32 v25, v0
	v_mov_b32_e32 v26, v0
	v_mov_b32_e32 v27, v0
	v_mov_b32_e32 v32, v0
	v_mov_b32_e32 v33, v0
	v_mov_b32_e32 v34, v0
	v_mov_b32_e32 v35, v0
	v_mov_b32_e32 v40, v0
	v_mov_b32_e32 v41, v0
	v_mov_b32_e32 v42, v0
	v_mov_b32_e32 v43, v0
	v_mov_b32_e32 v48, v0
	v_mov_b32_e32 v49, v0
	v_mov_b32_e32 v50, v0
	v_mov_b32_e32 v51, v0
	v_mov_b32_e32 v56, v0
	v_mov_b32_e32 v57, v0
	v_mov_b32_e32 v58, v0
	v_mov_b32_e32 v59, v0
	v_mov_b32_e32 v12, v0
	v_mov_b32_e32 v13, v0
	v_mov_b32_e32 v14, v0
	v_mov_b32_e32 v15, v0
	v_mov_b32_e32 v20, v0
	v_mov_b32_e32 v21, v0
	v_mov_b32_e32 v22, v0
	v_mov_b32_e32 v23, v0
	v_mov_b32_e32 v28, v0
	v_mov_b32_e32 v29, v0
	v_mov_b32_e32 v30, v0
	v_mov_b32_e32 v31, v0
	v_mov_b32_e32 v36, v0
	v_mov_b32_e32 v37, v0
	v_mov_b32_e32 v38, v0
	v_mov_b32_e32 v39, v0
	v_mov_b32_e32 v44, v0
	v_mov_b32_e32 v45, v0
	v_mov_b32_e32 v46, v0
	v_mov_b32_e32 v47, v0
	v_mov_b32_e32 v52, v0
	v_mov_b32_e32 v53, v0
	v_mov_b32_e32 v54, v0
	v_mov_b32_e32 v55, v0
	v_mov_b32_e32 v60, v0
	v_mov_b32_e32 v61, v0
	v_mov_b32_e32 v62, v0
	v_mov_b32_e32 v63, v0
	v_mov_b32_e32 v64, v0
	v_mov_b32_e32 v65, v0
	v_mov_b32_e32 v66, v0
	v_mov_b32_e32 v67, v0
	v_mov_b32_e32 v68, v0
	v_mov_b32_e32 v69, v0
	v_mov_b32_e32 v70, v0
	v_mov_b32_e32 v71, v0
	v_mov_b32_e32 v72, v0
	v_mov_b32_e32 v73, v0
	v_mov_b32_e32 v74, v0
	v_mov_b32_e32 v75, v0
	v_mov_b32_e32 v80, v0
	v_mov_b32_e32 v81, v0
	v_mov_b32_e32 v82, v0
	v_mov_b32_e32 v83, v0
	v_mov_b32_e32 v84, v0
	v_mov_b32_e32 v85, v0
	v_mov_b32_e32 v86, v0
	v_mov_b32_e32 v87, v0
	v_mov_b32_e32 v96, v0
	v_mov_b32_e32 v97, v0
	v_mov_b32_e32 v98, v0
	v_mov_b32_e32 v99, v0
	v_mov_b32_e32 v100, v0
	v_mov_b32_e32 v101, v0
	v_mov_b32_e32 v102, v0
	v_mov_b32_e32 v103, v0
	v_mov_b32_e32 v112, v0
	v_mov_b32_e32 v113, v0
	v_mov_b32_e32 v114, v0
	v_mov_b32_e32 v115, v0
	v_mov_b32_e32 v124, v0
	v_mov_b32_e32 v125, v0
	v_mov_b32_e32 v126, v0
	v_mov_b32_e32 v127, v0
	v_mov_b32_e32 v76, v0
	v_mov_b32_e32 v77, v0
	v_mov_b32_e32 v78, v0
	v_mov_b32_e32 v79, v0
	v_mov_b32_e32 v88, v0
	v_mov_b32_e32 v89, v0
	v_mov_b32_e32 v90, v0
	v_mov_b32_e32 v91, v0
	v_mov_b32_e32 v92, v0
	v_mov_b32_e32 v93, v0
	v_mov_b32_e32 v94, v0
	v_mov_b32_e32 v95, v0
	v_mov_b32_e32 v104, v0
	v_mov_b32_e32 v105, v0
	v_mov_b32_e32 v106, v0
	v_mov_b32_e32 v107, v0
	v_mov_b32_e32 v108, v0
	v_mov_b32_e32 v109, v0
	v_mov_b32_e32 v110, v0
	v_mov_b32_e32 v111, v0
	v_mov_b32_e32 v128, v0
	v_mov_b32_e32 v129, v0
	v_mov_b32_e32 v130, v0
	v_mov_b32_e32 v131, v0
	v_mov_b32_e32 v140, v0
	v_mov_b32_e32 v141, v0
	v_mov_b32_e32 v142, v0
	v_mov_b32_e32 v143, v0
	v_mov_b32_e32 v144, v0
	v_mov_b32_e32 v145, v0
	v_mov_b32_e32 v146, v0
	v_mov_b32_e32 v147, v0
	s_and_b64 vcc, exec, s[10:11]
	s_cbranch_vccnz .Lprio_1264
	s_setprio 1
.Lprio_1264:
.LBB0_1264:
	s_add_u32 s22, s20, 0xfff00080
	s_addc_u32 s23, s21, -1
	s_add_i32 s70, 0, 0x10000
	s_cmp_eq_u32 s69, 60
	s_cselect_b32 s25, s15, s23
	s_cselect_b32 s24, s64, s22
	s_cselect_b32 s23, s13, s68
	s_cselect_b32 s22, s66, s67
	s_add_i32 s72, 0, 0x14000
	v_add_u32_e32 v136, s70, v170
	v_add_u32_e32 v150, s72, v170
	ds_read_b128 v[116:119], v136
	ds_read_b128 v[120:123], v136 offset:1024
	ds_read_b128 v[132:135], v136 offset:2048
	ds_read_b128 v[136:139], v136 offset:3072
	ds_read_b128 v[164:167], v150
	ds_read_b128 v[188:191], v150 offset:1024
	ds_read_b128 v[192:195], v150 offset:2048
	ds_read_b128 v[196:199], v150 offset:3072
	v_lshl_add_u64 v[168:169], s[20:21], 0, v[162:163]
	s_add_i32 m0, s35, 0xc000
	ds_read_b128 v[200:203], v172
	ds_read_b128 v[204:207], v172 offset:1024
	ds_read_b128 v[208:211], v172 offset:2048
	ds_read_b128 v[212:215], v172 offset:3072
	ds_read_b128 v[216:219], v172 offset:4096
	ds_read_b128 v[220:223], v172 offset:5120
	ds_read_b128 v[224:227], v172 offset:6144
	ds_read_b128 v[228:231], v172 offset:7168
	global_load_lds_dwordx4 v[168:169], off
	v_lshl_add_u64 v[168:169], s[20:21], 0, v[160:161]
	s_add_i32 m0, s35, 0xe000
	s_nop 0
	global_load_lds_dwordx4 v[168:169], off
	s_waitcnt vmcnt(8)
	s_waitcnt lgkmcnt(0)
	s_barrier
; #define PG8_STAGE(bufoff, gbase, voff) do { _Pragma("unroll") for (int _i = 0; _i < 2; ++_i) \
;         __builtin_amdgcn_global_load_lds((const unsigned*)((const char*)(gbase) + (voff)[_i]), (PG8_LAS unsigned*)(lds + (bufoff) + ldsw + _i * 8192), 16, 0, 0); } while (0)
; #define PG8_LDA(dst, b, h) do { _Pragma("unroll") for (int m = 0; m < 4; ++m) _Pragma("unroll") for (int k = 0; k < 2; ++k) dst[m][k] = *(const PG8_LAS bf16x8*)(lds + PG8_SA(b, h) + aoff + m * 2048 + k * 1024); } while (0)
; #define PG8_MMA(ai, bj, At, Bt) do { __builtin_amdgcn_s_setprio(1); _Pragma("unroll") for (int m = 0; m < 4; ++m) _Pragma("unroll") for (int n = 0; n < 2; ++n) _Pragma("unroll") for (int k = 0; k < 2; ++k) \
;         acc[ai][bj][m][n] = __builtin_amdgcn_mfma_f32_16x16x32_bf16(Bt[n][k], At[m][k], acc[ai][bj][m][n], 0, 0, 0); __builtin_amdgcn_s_setprio(0); } while (0)
; #define PG8_WAIT_V(n) asm volatile("s_waitcnt vmcnt(" #n ")" ::: "memory")
; #define PG8_WAIT_L(n) asm volatile("s_waitcnt lgkmcnt(" #n ")" ::: "memory")
; #define PG8_BAR __builtin_amdgcn_s_barrier()
; #define PG8_SCHED __builtin_amdgcn_sched_barrier(0)
; template <class Epi, class Sched, bool ALIGN_EPI = GEMM_ALIGN, bool SP2 = GEMM_SP2>
; __device__ __forceinline__ void gemm_phase(PG8_LAS unsigned char* lds, const Gemm g, const Sched& S, const Epi& E, unsigned long long*  , int tid_in) {
;     ...
;             PG8_WAIT_V(8); PG8_WAIT_L(0); PG8_BAR; PG8_MMA(0, 0, At, B0); PG8_MMA(0, 1, At, B1); PG8_BAR; PG8_SCHED;
;             PG8_LDA(At, 0, 1); PG8_STAGE(PG8_SB(0, 0), b2, voffB); PG8_STAGE(PG8_SB(0, 1), b2 + hstep, voffB); PG8_STAGE(PG8_SA(0, 0), a2, voffA);
;             PG8_WAIT_V(8); PG8_WAIT_L(0); PG8_BAR; PG8_MMA(1, 0, At, B0); PG8_MMA(1, 1, At, B1); PG8_BAR; PG8_SCHED;
	s_nop 0
	s_waitcnt lgkmcnt(0)
	v_mfma_f32_16x16x32_bf16 v[144:147], v[116:119], v[200:203], v[144:147]
	v_mfma_f32_16x16x32_bf16 v[140:143], v[132:135], v[200:203], v[140:143]
	v_mfma_f32_16x16x32_bf16 v[128:131], v[116:119], v[208:211], v[128:131]
	v_mfma_f32_16x16x32_bf16 v[108:111], v[132:135], v[208:211], v[108:111]
	v_mfma_f32_16x16x32_bf16 v[104:107], v[116:119], v[216:219], v[104:107]
	v_mfma_f32_16x16x32_bf16 v[92:95], v[132:135], v[216:219], v[92:95]
	v_mfma_f32_16x16x32_bf16 v[88:91], v[116:119], v[224:227], v[88:91]
	v_mfma_f32_16x16x32_bf16 v[76:79], v[132:135], v[224:227], v[76:79]
	v_mfma_f32_16x16x32_bf16 v[144:147], v[120:123], v[204:207], v[144:147]
	v_mfma_f32_16x16x32_bf16 v[140:143], v[136:139], v[204:207], v[140:143]
	v_mfma_f32_16x16x32_bf16 v[128:131], v[120:123], v[212:215], v[128:131]
	v_mfma_f32_16x16x32_bf16 v[108:111], v[136:139], v[212:215], v[108:111]
	v_mfma_f32_16x16x32_bf16 v[104:107], v[120:123], v[220:223], v[104:107]
	v_mfma_f32_16x16x32_bf16 v[92:95], v[136:139], v[220:223], v[92:95]
	v_mfma_f32_16x16x32_bf16 v[88:91], v[120:123], v[228:231], v[88:91]
	v_mfma_f32_16x16x32_bf16 v[76:79], v[136:139], v[228:231], v[76:79]
	s_nop 0
	s_nop 0
	v_mfma_f32_16x16x32_bf16 v[124:127], v[164:167], v[200:203], v[124:127]
	v_mfma_f32_16x16x32_bf16 v[112:115], v[192:195], v[200:203], v[112:115]
	v_mfma_f32_16x16x32_bf16 v[100:103], v[164:167], v[208:211], v[100:103]
	v_mfma_f32_16x16x32_bf16 v[96:99], v[192:195], v[208:211], v[96:99]
	v_mfma_f32_16x16x32_bf16 v[84:87], v[164:167], v[216:219], v[84:87]
	v_mfma_f32_16x16x32_bf16 v[80:83], v[192:195], v[216:219], v[80:83]
	v_mfma_f32_16x16x32_bf16 v[72:75], v[164:167], v[224:227], v[72:75]
	v_mfma_f32_16x16x32_bf16 v[68:71], v[192:195], v[224:227], v[68:71]
	v_mfma_f32_16x16x32_bf16 v[124:127], v[188:191], v[204:207], v[124:127]
	v_mfma_f32_16x16x32_bf16 v[112:115], v[196:199], v[204:207], v[112:115]
	v_mfma_f32_16x16x32_bf16 v[100:103], v[188:191], v[212:215], v[100:103]
	v_mfma_f32_16x16x32_bf16 v[96:99], v[196:199], v[212:215], v[96:99]
	v_mfma_f32_16x16x32_bf16 v[84:87], v[188:191], v[220:223], v[84:87]
	v_mfma_f32_16x16x32_bf16 v[80:83], v[196:199], v[220:223], v[80:83]
	v_mfma_f32_16x16x32_bf16 v[72:75], v[188:191], v[228:231], v[72:75]
	v_mfma_f32_16x16x32_bf16 v[68:71], v[196:199], v[228:231], v[68:71]
	s_nop 0
	s_barrier
	s_add_i32 s70, s70, s34
	v_lshl_add_u64 v[168:169], s[22:23], 0, v[10:11]
	s_mov_b32 m0, s70
	ds_read_b128 v[200:203], v172 offset:16384
	ds_read_b128 v[204:207], v172 offset:17408
	ds_read_b128 v[208:211], v172 offset:18432
	ds_read_b128 v[212:215], v172 offset:19456
	ds_read_b128 v[216:219], v172 offset:20480
	ds_read_b128 v[220:223], v172 offset:21504
	ds_read_b128 v[224:227], v172 offset:22528
	ds_read_b128 v[228:231], v172 offset:23552
	global_load_lds_dwordx4 v[168:169], off
	s_add_i32 m0, s70, 0x2000
	s_add_u32 s70, s22, 0x100000
	v_lshl_add_u64 v[174:175], s[22:23], 0, v[8:9]
	s_addc_u32 s71, s23, 0
	s_add_i32 s72, s72, s34
	global_load_lds_dwordx4 v[174:175], off
	v_lshl_add_u64 v[232:233], s[70:71], 0, v[10:11]
	s_mov_b32 m0, s72
	v_lshl_add_u64 v[234:235], s[24:25], 0, v[156:157]
	global_load_lds_dwordx4 v[232:233], off
	v_lshl_add_u64 v[232:233], s[70:71], 0, v[8:9]
	s_add_i32 m0, s72, 0x2000
	s_nop 0
	global_load_lds_dwordx4 v[232:233], off
	v_lshl_add_u64 v[232:233], s[24:25], 0, v[158:159]
	s_mov_b32 m0, s35
	s_nop 0
	global_load_lds_dwordx4 v[232:233], off
	s_mov_b32 m0, s36
	s_nop 0
	global_load_lds_dwordx4 v[234:235], off
	s_waitcnt vmcnt(8)
	s_waitcnt lgkmcnt(0)
	s_barrier
	s_nop 0
	s_waitcnt lgkmcnt(0)
	v_mfma_f32_16x16x32_bf16 v[64:67], v[116:119], v[200:203], v[64:67]
	v_mfma_f32_16x16x32_bf16 v[60:63], v[132:135], v[200:203], v[60:63]
	v_mfma_f32_16x16x32_bf16 v[52:55], v[116:119], v[208:211], v[52:55]
	v_mfma_f32_16x16x32_bf16 v[44:47], v[132:135], v[208:211], v[44:47]
	v_mfma_f32_16x16x32_bf16 v[36:39], v[116:119], v[216:219], v[36:39]
	v_mfma_f32_16x16x32_bf16 v[28:31], v[132:135], v[216:219], v[28:31]
	v_mfma_f32_16x16x32_bf16 v[20:23], v[116:119], v[224:227], v[20:23]
	v_mfma_f32_16x16x32_bf16 v[12:15], v[132:135], v[224:227], v[12:15]
	v_mfma_f32_16x16x32_bf16 v[64:67], v[120:123], v[204:207], v[64:67]
	v_mfma_f32_16x16x32_bf16 v[60:63], v[136:139], v[204:207], v[60:63]
	v_mfma_f32_16x16x32_bf16 v[52:55], v[120:123], v[212:215], v[52:55]
	v_mfma_f32_16x16x32_bf16 v[44:47], v[136:139], v[212:215], v[44:47]
	v_mfma_f32_16x16x32_bf16 v[36:39], v[120:123], v[220:223], v[36:39]
	v_mfma_f32_16x16x32_bf16 v[28:31], v[136:139], v[220:223], v[28:31]
	v_mfma_f32_16x16x32_bf16 v[20:23], v[120:123], v[228:231], v[20:23]
	v_mfma_f32_16x16x32_bf16 v[12:15], v[136:139], v[228:231], v[12:15]
	s_nop 0
	s_nop 0
	v_mfma_f32_16x16x32_bf16 v[56:59], v[164:167], v[200:203], v[56:59]
	v_mfma_f32_16x16x32_bf16 v[48:51], v[192:195], v[200:203], v[48:51]
	v_mfma_f32_16x16x32_bf16 v[40:43], v[164:167], v[208:211], v[40:43]
	v_mfma_f32_16x16x32_bf16 v[32:35], v[192:195], v[208:211], v[32:35]
	v_mfma_f32_16x16x32_bf16 v[24:27], v[164:167], v[216:219], v[24:27]
	v_mfma_f32_16x16x32_bf16 v[16:19], v[192:195], v[216:219], v[16:19]
	v_mfma_f32_16x16x32_bf16 v[4:7], v[164:167], v[224:227], v[4:7]
	v_mfma_f32_16x16x32_bf16 v[0:3], v[192:195], v[224:227], v[0:3]
	v_mfma_f32_16x16x32_bf16 v[56:59], v[188:191], v[204:207], v[56:59]
	v_mfma_f32_16x16x32_bf16 v[48:51], v[196:199], v[204:207], v[48:51]
	v_mfma_f32_16x16x32_bf16 v[40:43], v[188:191], v[212:215], v[40:43]
	v_mfma_f32_16x16x32_bf16 v[32:35], v[196:199], v[212:215], v[32:35]
	v_mfma_f32_16x16x32_bf16 v[24:27], v[188:191], v[220:223], v[24:27]
	v_mfma_f32_16x16x32_bf16 v[16:19], v[196:199], v[220:223], v[16:19]
	v_mfma_f32_16x16x32_bf16 v[4:7], v[188:191], v[228:231], v[4:7]
	v_mfma_f32_16x16x32_bf16 v[0:3], v[196:199], v[228:231], v[0:3]
	s_nop 0
	s_barrier
; #define PG8_STAGE(bufoff, gbase, voff) do { _Pragma("unroll") for (int _i = 0; _i < 2; ++_i) \
;         __builtin_amdgcn_global_load_lds((const unsigned*)((const char*)(gbase) + (voff)[_i]), (PG8_LAS unsigned*)(lds + (bufoff) + ldsw + _i * 8192), 16, 0, 0); } while (0)
; #define PG8_LDA(dst, b, h) do { _Pragma("unroll") for (int m = 0; m < 4; ++m) _Pragma("unroll") for (int k = 0; k < 2; ++k) dst[m][k] = *(const PG8_LAS bf16x8*)(lds + PG8_SA(b, h) + aoff + m * 2048 + k * 1024); } while (0)
; #define PG8_LDB(dst, b, h) do { _Pragma("unroll") for (int n = 0; n < 2; ++n) _Pragma("unroll") for (int k = 0; k < 2; ++k) dst[n][k] = *(const PG8_LAS bf16x8*)(lds + PG8_SB(b, h) + boff + n * 2048 + k * 1024); } while (0)
; #define PG8_MMA(ai, bj, At, Bt) do { __builtin_amdgcn_s_setprio(1); _Pragma("unroll") for (int m = 0; m < 4; ++m) _Pragma("unroll") for (int n = 0; n < 2; ++n) _Pragma("unroll") for (int k = 0; k < 2; ++k) \
;         acc[ai][bj][m][n] = __builtin_amdgcn_mfma_f32_16x16x32_bf16(Bt[n][k], At[m][k], acc[ai][bj][m][n], 0, 0, 0); __builtin_amdgcn_s_setprio(0); } while (0)
; #define PG8_WAIT_V(n) asm volatile("s_waitcnt vmcnt(" #n ")" ::: "memory")
; #define PG8_WAIT_L(n) asm volatile("s_waitcnt lgkmcnt(" #n ")" ::: "memory")
; #define PG8_BAR __builtin_amdgcn_s_barrier()
; #define PG8_SCHED __builtin_amdgcn_sched_barrier(0)
; template <class Epi, class Sched, bool ALIGN_EPI = GEMM_ALIGN, bool SP2 = GEMM_SP2>
; __device__ __forceinline__ void gemm_phase(PG8_LAS unsigned char* lds, const Gemm g, const Sched& S, const Epi& E, unsigned long long*  , int tid_in) {
;     ...
;             PG8_LDB(B0, 1, 0); PG8_LDB(B1, 1, 1); PG8_SCHED; PG8_LDA(At, 1, 0); PG8_STAGE(PG8_SA(0, 1), a2 + hstep, voffA);
;             PG8_WAIT_V(8); PG8_WAIT_L(0); PG8_BAR; PG8_MMA(0, 0, At, B0); PG8_MMA(0, 1, At, B1); PG8_BAR; PG8_SCHED;
	s_add_i32 s70, 0, 0x18000
	s_add_i32 s71, 0, 0x1c000
	v_add_u32_e32 v136, s70, v170
	v_add_u32_e32 v150, s71, v170
	ds_read_b128 v[116:119], v136
	ds_read_b128 v[120:123], v136 offset:1024
	ds_read_b128 v[132:135], v136 offset:2048
	ds_read_b128 v[136:139], v136 offset:3072
	ds_read_b128 v[164:167], v150
	ds_read_b128 v[188:191], v150 offset:1024
	ds_read_b128 v[192:195], v150 offset:2048
	ds_read_b128 v[196:199], v150 offset:3072
	s_add_u32 s24, s24, 0x100000
	s_addc_u32 s25, s25, 0
	s_mov_b32 m0, s37
	v_lshl_add_u64 v[236:237], s[24:25], 0, v[158:159]
	ds_read_b128 v[200:203], v172 offset:32768
	ds_read_b128 v[204:207], v172 offset:33792
	ds_read_b128 v[208:211], v172 offset:34816
	ds_read_b128 v[212:215], v172 offset:35840
	ds_read_b128 v[216:219], v172 offset:36864
	ds_read_b128 v[220:223], v172 offset:37888
	ds_read_b128 v[224:227], v172 offset:38912
	ds_read_b128 v[228:231], v172 offset:39936
	global_load_lds_dwordx4 v[236:237], off
	v_lshl_add_u64 v[236:237], s[24:25], 0, v[156:157]
	s_mov_b32 m0, s50
	s_nop 0
	global_load_lds_dwordx4 v[236:237], off
	s_waitcnt vmcnt(8)
	s_waitcnt lgkmcnt(0)
	s_barrier
	s_nop 0
	s_waitcnt lgkmcnt(0)
	v_mfma_f32_16x16x32_bf16 v[144:147], v[116:119], v[200:203], v[144:147]
	v_mfma_f32_16x16x32_bf16 v[140:143], v[132:135], v[200:203], v[140:143]
	v_mfma_f32_16x16x32_bf16 v[128:131], v[116:119], v[208:211], v[128:131]
	v_mfma_f32_16x16x32_bf16 v[108:111], v[132:135], v[208:211], v[108:111]
	v_mfma_f32_16x16x32_bf16 v[104:107], v[116:119], v[216:219], v[104:107]
	v_mfma_f32_16x16x32_bf16 v[92:95], v[132:135], v[216:219], v[92:95]
	v_mfma_f32_16x16x32_bf16 v[88:91], v[116:119], v[224:227], v[88:91]
	v_mfma_f32_16x16x32_bf16 v[76:79], v[132:135], v[224:227], v[76:79]
	v_mfma_f32_16x16x32_bf16 v[144:147], v[120:123], v[204:207], v[144:147]
	v_mfma_f32_16x16x32_bf16 v[140:143], v[136:139], v[204:207], v[140:143]
	v_mfma_f32_16x16x32_bf16 v[128:131], v[120:123], v[212:215], v[128:131]
	v_mfma_f32_16x16x32_bf16 v[108:111], v[136:139], v[212:215], v[108:111]
	v_mfma_f32_16x16x32_bf16 v[104:107], v[120:123], v[220:223], v[104:107]
	v_mfma_f32_16x16x32_bf16 v[92:95], v[136:139], v[220:223], v[92:95]
	v_mfma_f32_16x16x32_bf16 v[88:91], v[120:123], v[228:231], v[88:91]
	v_mfma_f32_16x16x32_bf16 v[76:79], v[136:139], v[228:231], v[76:79]
	s_nop 0
	s_nop 0
	v_mfma_f32_16x16x32_bf16 v[124:127], v[164:167], v[200:203], v[124:127]
	v_mfma_f32_16x16x32_bf16 v[112:115], v[192:195], v[200:203], v[112:115]
	v_mfma_f32_16x16x32_bf16 v[100:103], v[164:167], v[208:211], v[100:103]
	v_mfma_f32_16x16x32_bf16 v[96:99], v[192:195], v[208:211], v[96:99]
	v_mfma_f32_16x16x32_bf16 v[84:87], v[164:167], v[216:219], v[84:87]
	v_mfma_f32_16x16x32_bf16 v[80:83], v[192:195], v[216:219], v[80:83]
	v_mfma_f32_16x16x32_bf16 v[72:75], v[164:167], v[224:227], v[72:75]
	v_mfma_f32_16x16x32_bf16 v[68:71], v[192:195], v[224:227], v[68:71]
	v_mfma_f32_16x16x32_bf16 v[124:127], v[188:191], v[204:207], v[124:127]
	v_mfma_f32_16x16x32_bf16 v[112:115], v[196:199], v[204:207], v[112:115]
	v_mfma_f32_16x16x32_bf16 v[100:103], v[188:191], v[212:215], v[100:103]
	v_mfma_f32_16x16x32_bf16 v[96:99], v[196:199], v[212:215], v[96:99]
	v_mfma_f32_16x16x32_bf16 v[84:87], v[188:191], v[220:223], v[84:87]
	v_mfma_f32_16x16x32_bf16 v[80:83], v[196:199], v[220:223], v[80:83]
	v_mfma_f32_16x16x32_bf16 v[72:75], v[188:191], v[228:231], v[72:75]
	v_mfma_f32_16x16x32_bf16 v[68:71], v[196:199], v[228:231], v[68:71]
	s_nop 0
	s_barrier
; #define PG8_STAGE(bufoff, gbase, voff) do { _Pragma("unroll") for (int _i = 0; _i < 2; ++_i) \
;         __builtin_amdgcn_global_load_lds((const unsigned*)((const char*)(gbase) + (voff)[_i]), (PG8_LAS unsigned*)(lds + (bufoff) + ldsw + _i * 8192), 16, 0, 0); } while (0)
; #define PG8_LDA(dst, b, h) do { _Pragma("unroll") for (int m = 0; m < 4; ++m) _Pragma("unroll") for (int k = 0; k < 2; ++k) dst[m][k] = *(const PG8_LAS bf16x8*)(lds + PG8_SA(b, h) + aoff + m * 2048 + k * 1024); } while (0)
; #define PG8_MMA(ai, bj, At, Bt) do { __builtin_amdgcn_s_setprio(1); _Pragma("unroll") for (int m = 0; m < 4; ++m) _Pragma("unroll") for (int n = 0; n < 2; ++n) _Pragma("unroll") for (int k = 0; k < 2; ++k) \
;         acc[ai][bj][m][n] = __builtin_amdgcn_mfma_f32_16x16x32_bf16(Bt[n][k], At[m][k], acc[ai][bj][m][n], 0, 0, 0); __builtin_amdgcn_s_setprio(0); } while (0)
; #define PG8_WAIT_V(n) asm volatile("s_waitcnt vmcnt(" #n ")" ::: "memory")
; #define PG8_WAIT_L(n) asm volatile("s_waitcnt lgkmcnt(" #n ")" ::: "memory")
; #define PG8_BAR __builtin_amdgcn_s_barrier()
; #define PG8_SCHED __builtin_amdgcn_sched_barrier(0)
; template <class Epi, class Sched, bool ALIGN_EPI = GEMM_ALIGN, bool SP2 = GEMM_SP2>
; __device__ __forceinline__ void gemm_phase(PG8_LAS unsigned char* lds, const Gemm g, const Sched& S, const Epi& E, unsigned long long*  , int tid_in) {
;     ...
;         for (int t = 0; t < nt; t += 2) {
;     ...
;             PG8_LDA(At, 1, 1); PG8_STAGE(PG8_SB(1, 0), b3, voffB); PG8_STAGE(PG8_SB(1, 1), b3 + hstep, voffB); PG8_STAGE(PG8_SA(1, 0), a3, voffA);
;             PG8_WAIT_V(8); PG8_WAIT_L(0); PG8_BAR; PG8_MMA(1, 0, At, B0); PG8_MMA(1, 1, At, B1); PG8_BAR; PG8_SCHED;
	s_add_i32 s24, s70, s34
	v_lshl_add_u64 v[168:169], v[168:169], 0, s[82:83]
	s_mov_b32 m0, s24
	ds_read_b128 v[200:203], v172 offset:49152
	ds_read_b128 v[204:207], v172 offset:50176
	ds_read_b128 v[208:211], v172 offset:51200
	ds_read_b128 v[212:215], v172 offset:52224
	ds_read_b128 v[216:219], v172 offset:53248
	ds_read_b128 v[220:223], v172 offset:54272
	ds_read_b128 v[224:227], v172 offset:55296
	ds_read_b128 v[228:231], v172 offset:56320
	global_load_lds_dwordx4 v[168:169], off
	s_add_i32 m0, s24, 0x2000
	s_add_u32 s22, s22, 0x100080
	v_lshl_add_u64 v[168:169], v[174:175], 0, s[82:83]
	s_addc_u32 s23, s23, 0
	s_add_i32 s24, s71, s34
	global_load_lds_dwordx4 v[168:169], off
	v_lshl_add_u64 v[168:169], s[22:23], 0, v[10:11]
	s_mov_b32 m0, s24
	s_nop 0
	global_load_lds_dwordx4 v[168:169], off
	v_lshl_add_u64 v[168:169], s[22:23], 0, v[8:9]
	s_add_i32 m0, s24, 0x2000
	s_nop 0
	global_load_lds_dwordx4 v[168:169], off
	v_lshl_add_u64 v[168:169], v[232:233], 0, s[82:83]
	s_mov_b32 m0, s59
	s_nop 0
	global_load_lds_dwordx4 v[168:169], off
	v_lshl_add_u64 v[168:169], v[234:235], 0, s[82:83]
	s_mov_b32 m0, s60
	s_nop 0
	global_load_lds_dwordx4 v[168:169], off
	s_waitcnt vmcnt(8)
	s_waitcnt lgkmcnt(0)
	s_barrier
	s_nop 0
	s_waitcnt lgkmcnt(0)
	v_mfma_f32_16x16x32_bf16 v[64:67], v[116:119], v[200:203], v[64:67]
	v_mfma_f32_16x16x32_bf16 v[60:63], v[132:135], v[200:203], v[60:63]
	v_mfma_f32_16x16x32_bf16 v[52:55], v[116:119], v[208:211], v[52:55]
	v_mfma_f32_16x16x32_bf16 v[44:47], v[132:135], v[208:211], v[44:47]
	v_mfma_f32_16x16x32_bf16 v[36:39], v[116:119], v[216:219], v[36:39]
	v_mfma_f32_16x16x32_bf16 v[28:31], v[132:135], v[216:219], v[28:31]
	v_mfma_f32_16x16x32_bf16 v[20:23], v[116:119], v[224:227], v[20:23]
	v_mfma_f32_16x16x32_bf16 v[12:15], v[132:135], v[224:227], v[12:15]
	v_mfma_f32_16x16x32_bf16 v[64:67], v[120:123], v[204:207], v[64:67]
	v_mfma_f32_16x16x32_bf16 v[60:63], v[136:139], v[204:207], v[60:63]
	v_mfma_f32_16x16x32_bf16 v[52:55], v[120:123], v[212:215], v[52:55]
	v_mfma_f32_16x16x32_bf16 v[44:47], v[136:139], v[212:215], v[44:47]
	v_mfma_f32_16x16x32_bf16 v[36:39], v[120:123], v[220:223], v[36:39]
	v_mfma_f32_16x16x32_bf16 v[28:31], v[136:139], v[220:223], v[28:31]
	v_mfma_f32_16x16x32_bf16 v[20:23], v[120:123], v[228:231], v[20:23]
	v_mfma_f32_16x16x32_bf16 v[12:15], v[136:139], v[228:231], v[12:15]
	s_nop 0
	s_nop 0
	v_mfma_f32_16x16x32_bf16 v[56:59], v[164:167], v[200:203], v[56:59]
	v_mfma_f32_16x16x32_bf16 v[48:51], v[192:195], v[200:203], v[48:51]
	v_mfma_f32_16x16x32_bf16 v[40:43], v[164:167], v[208:211], v[40:43]
	v_mfma_f32_16x16x32_bf16 v[32:35], v[192:195], v[208:211], v[32:35]
	v_mfma_f32_16x16x32_bf16 v[24:27], v[164:167], v[216:219], v[24:27]
	v_mfma_f32_16x16x32_bf16 v[16:19], v[192:195], v[216:219], v[16:19]
	v_mfma_f32_16x16x32_bf16 v[4:7], v[164:167], v[224:227], v[4:7]
	v_mfma_f32_16x16x32_bf16 v[0:3], v[192:195], v[224:227], v[0:3]
	v_mfma_f32_16x16x32_bf16 v[56:59], v[188:191], v[204:207], v[56:59]
	v_mfma_f32_16x16x32_bf16 v[48:51], v[196:199], v[204:207], v[48:51]
	v_mfma_f32_16x16x32_bf16 v[40:43], v[188:191], v[212:215], v[40:43]
	v_mfma_f32_16x16x32_bf16 v[32:35], v[196:199], v[212:215], v[32:35]
	v_mfma_f32_16x16x32_bf16 v[24:27], v[188:191], v[220:223], v[24:27]
	v_mfma_f32_16x16x32_bf16 v[16:19], v[196:199], v[220:223], v[16:19]
	v_mfma_f32_16x16x32_bf16 v[4:7], v[188:191], v[228:231], v[4:7]
	v_mfma_f32_16x16x32_bf16 v[0:3], v[196:199], v[228:231], v[0:3]
	s_nop 0
	s_barrier
	s_add_i32 s69, s69, 2
	s_add_u32 s67, s67, 0x100
	s_addc_u32 s68, s68, 0
	s_add_u32 s20, s20, 0x100
	s_addc_u32 s21, s21, 0
	s_cmp_gt_u32 s69, 61
	s_cbranch_scc0 .LBB0_1264
	s_setprio 0
	s_and_b64 vcc, exec, s[10:11]
	s_cbranch_vccz .LBB0_1267
	s_barrier
